# speedup vs baseline: 1.0083x; 1.0067x over previous
.LBB0_154:
	s_ashr_i32 s21, s20, 31
	s_lshl_b64 s[20:21], s[20:21], 20
	s_add_u32 s20, s26, s20
	s_addc_u32 s21, s27, s21
	s_ashr_i32 s23, s22, 31
	s_lshl_b64 s[22:23], s[22:23], 20
	s_add_u32 s22, s8, s22
	s_addc_u32 s23, s9, s23
	s_add_u32 s44, s16, 0x80
	v_and_b32_e32 v8, 48, v7
	v_lshlrev_b32_e32 v9, 6, v7
	v_lshlrev_b32_e32 v7, 2, v7
	s_addc_u32 s45, s17, 0
	v_and_b32_e32 v10, 0x3c0, v9
	v_and_b32_e32 v149, 32, v7
	s_add_u32 s46, s18, 0x80
	v_or_b32_e32 v145, v10, v8
	v_bitop3_b32 v12, v10, v149, v8 bitop3:0x36
	s_waitcnt vmcnt(0)
	s_barrier
	v_lshlrev_b32_e32 v8, 13, v6
	s_addc_u32 s47, s19, 0
	s_add_i32 s25, s1, 0x10000
	v_lshl_add_u64 v[6:7], s[44:45], 0, v[0:1]
	s_mov_b32 s39, m0
	s_mov_b32 m0, s25
	s_nop 0
	global_load_lds_dwordx4 v[6:7], off
	s_mov_b32 m0, s39
	s_add_i32 s24, s1, 0x18000
	v_lshl_add_u64 v[6:7], s[46:47], 0, v[0:1]
	s_mov_b32 s39, m0
	s_mov_b32 m0, s24
	s_nop 0
	global_load_lds_dwordx4 v[6:7], off
	s_mov_b32 m0, s39
	v_lshl_add_u64 v[6:7], s[44:45], 0, v[2:3]
	s_add_i32 s39, s1, 0x12000
	s_mov_b32 s40, m0
	s_mov_b32 m0, s39
	s_nop 0
	global_load_lds_dwordx4 v[6:7], off
	s_mov_b32 m0, s40
	v_lshl_add_u64 v[6:7], s[46:47], 0, v[2:3]
	s_add_i32 s40, s1, 0x1a000
	s_mov_b32 s41, m0
	s_mov_b32 m0, s40
	s_nop 0
	global_load_lds_dwordx4 v[6:7], off
	s_mov_b32 m0, s41
	v_lshl_add_u64 v[6:7], s[44:45], 0, v[4:5]
	s_add_i32 s41, s1, 0x14000
	s_mov_b32 s42, m0
	s_mov_b32 m0, s41
	s_nop 0
	global_load_lds_dwordx4 v[6:7], off
	s_mov_b32 m0, s42
	v_lshl_add_u64 v[6:7], s[46:47], 0, v[4:5]
	s_add_i32 s42, s1, 0x1c000
	s_mov_b32 s43, m0
	s_mov_b32 m0, s42
	s_nop 0
	global_load_lds_dwordx4 v[6:7], off
	s_mov_b32 m0, s43
	v_lshl_add_u64 v[6:7], s[44:45], 0, v[146:147]
	s_add_i32 s43, s1, 0x16000
	s_mov_b32 s44, m0
	s_mov_b32 m0, s43
	s_nop 0
	global_load_lds_dwordx4 v[6:7], off
	s_mov_b32 m0, s44
	v_lshl_add_u64 v[6:7], s[46:47], 0, v[146:147]
	s_add_i32 s44, s1, 0x1e000
	s_mov_b32 s45, m0
	s_mov_b32 m0, s44
	s_nop 0
	global_load_lds_dwordx4 v[6:7], off
	s_mov_b32 m0, s45
	v_and_b32_e32 v182, 0xffffc000, v9
	v_or_b32_e32 v183, 0x800, v182
	v_or_b32_e32 v189, 0x1000, v182
	v_or_b32_e32 v199, 0x1800, v182
	v_or_b32_e32 v200, 0x2000, v182
	v_or_b32_e32 v201, 0x2800, v182
	v_or_b32_e32 v203, 0x3000, v182
	v_or_b32_e32 v206, 0x3800, v182
	s_movk_i32 s45, 0x6000
	v_and_or_b32 v7, v8, s45, v12
	ds_read_b128 v[8:11], v7 offset:32768
	v_or_b32_e32 v6, v12, v182
	ds_read_b128 v[12:15], v7 offset:34816
	ds_read_b128 v[16:19], v7 offset:36864
	ds_read_b128 v[24:27], v7 offset:38912
	ds_read_b128 v[20:23], v6
	ds_read_b128 v[28:31], v6 offset:2048
	ds_read_b128 v[32:35], v6 offset:4096
	ds_read_b128 v[36:39], v6 offset:6144
	s_waitcnt lgkmcnt(3)
	v_mfma_f32_16x16x32_bf16 v[40:43], v[8:11], v[20:23], 0
	v_mfma_f32_16x16x32_bf16 v[44:47], v[12:15], v[20:23], 0
	v_mfma_f32_16x16x32_bf16 v[48:51], v[16:19], v[20:23], 0
	v_mfma_f32_16x16x32_bf16 v[20:23], v[24:27], v[20:23], 0
	ds_read_b128 v[52:55], v6 offset:8192
	s_waitcnt lgkmcnt(3)
	v_mfma_f32_16x16x32_bf16 v[56:59], v[8:11], v[28:31], 0
	v_mfma_f32_16x16x32_bf16 v[60:63], v[12:15], v[28:31], 0
	v_mfma_f32_16x16x32_bf16 v[64:67], v[16:19], v[28:31], 0
	v_mfma_f32_16x16x32_bf16 v[28:31], v[24:27], v[28:31], 0
	ds_read_b128 v[68:71], v6 offset:10240
	s_waitcnt lgkmcnt(3)
	v_mfma_f32_16x16x32_bf16 v[72:75], v[8:11], v[32:35], 0
	v_mfma_f32_16x16x32_bf16 v[76:79], v[12:15], v[32:35], 0
	v_mfma_f32_16x16x32_bf16 v[80:83], v[16:19], v[32:35], 0
	v_mfma_f32_16x16x32_bf16 v[32:35], v[24:27], v[32:35], 0
	ds_read_b128 v[84:87], v6 offset:12288
	s_waitcnt lgkmcnt(3)
	v_mfma_f32_16x16x32_bf16 v[88:91], v[8:11], v[36:39], 0
	v_mfma_f32_16x16x32_bf16 v[92:95], v[12:15], v[36:39], 0
	v_mfma_f32_16x16x32_bf16 v[96:99], v[16:19], v[36:39], 0
	v_mfma_f32_16x16x32_bf16 v[36:39], v[24:27], v[36:39], 0
	ds_read_b128 v[100:103], v6 offset:14336
	s_waitcnt lgkmcnt(3)
	v_mfma_f32_16x16x32_bf16 v[104:107], v[8:11], v[52:55], 0
	v_mfma_f32_16x16x32_bf16 v[108:111], v[12:15], v[52:55], 0
	v_mfma_f32_16x16x32_bf16 v[112:115], v[16:19], v[52:55], 0
	v_mfma_f32_16x16x32_bf16 v[52:55], v[24:27], v[52:55], 0
	s_waitcnt lgkmcnt(2)
	v_mfma_f32_16x16x32_bf16 v[116:119], v[8:11], v[68:71], 0
	v_mfma_f32_16x16x32_bf16 v[120:123], v[12:15], v[68:71], 0
	v_mfma_f32_16x16x32_bf16 v[124:127], v[16:19], v[68:71], 0
	v_mfma_f32_16x16x32_bf16 v[68:71], v[24:27], v[68:71], 0
	s_waitcnt lgkmcnt(1)
	v_mfma_f32_16x16x32_bf16 v[128:131], v[8:11], v[84:87], 0
	v_mfma_f32_16x16x32_bf16 v[132:135], v[12:15], v[84:87], 0
	v_mfma_f32_16x16x32_bf16 v[136:139], v[16:19], v[84:87], 0
	v_mfma_f32_16x16x32_bf16 v[84:87], v[24:27], v[84:87], 0
	s_waitcnt lgkmcnt(0)
	v_mfma_f32_16x16x32_bf16 v[8:11], v[8:11], v[100:103], 0
	v_mfma_f32_16x16x32_bf16 v[12:15], v[12:15], v[100:103], 0
	v_mfma_f32_16x16x32_bf16 v[16:19], v[16:19], v[100:103], 0
	v_mfma_f32_16x16x32_bf16 v[24:27], v[24:27], v[100:103], 0
	ds_read_b128 v[100:103], v7 offset:33792
	ds_read_b128 v[140:143], v7 offset:35840
	ds_read_b128 v[150:153], v7 offset:37888
	ds_read_b128 v[158:161], v7 offset:39936
	ds_read_b128 v[154:157], v6 offset:1024
	ds_read_b128 v[162:165], v6 offset:3072
	ds_read_b128 v[166:169], v6 offset:5120
	ds_read_b128 v[170:173], v6 offset:7168
	s_waitcnt lgkmcnt(3)
	v_mfma_f32_16x16x32_bf16 v[40:43], v[100:103], v[154:157], v[40:43]
	v_mfma_f32_16x16x32_bf16 v[44:47], v[140:143], v[154:157], v[44:47]
	v_mfma_f32_16x16x32_bf16 v[48:51], v[150:153], v[154:157], v[48:51]
	v_mfma_f32_16x16x32_bf16 v[20:23], v[158:161], v[154:157], v[20:23]
	ds_read_b128 v[154:157], v6 offset:9216
	s_waitcnt lgkmcnt(3)
	v_mfma_f32_16x16x32_bf16 v[56:59], v[100:103], v[162:165], v[56:59]
	v_mfma_f32_16x16x32_bf16 v[60:63], v[140:143], v[162:165], v[60:63]
	v_mfma_f32_16x16x32_bf16 v[64:67], v[150:153], v[162:165], v[64:67]
	v_mfma_f32_16x16x32_bf16 v[28:31], v[158:161], v[162:165], v[28:31]
	ds_read_b128 v[162:165], v6 offset:11264
	s_waitcnt lgkmcnt(3)
	v_mfma_f32_16x16x32_bf16 v[72:75], v[100:103], v[166:169], v[72:75]
	v_mfma_f32_16x16x32_bf16 v[76:79], v[140:143], v[166:169], v[76:79]
	v_mfma_f32_16x16x32_bf16 v[80:83], v[150:153], v[166:169], v[80:83]
	v_mfma_f32_16x16x32_bf16 v[32:35], v[158:161], v[166:169], v[32:35]
	ds_read_b128 v[166:169], v6 offset:13312
	s_waitcnt lgkmcnt(3)
	v_mfma_f32_16x16x32_bf16 v[88:91], v[100:103], v[170:173], v[88:91]
	v_mfma_f32_16x16x32_bf16 v[92:95], v[140:143], v[170:173], v[92:95]
	v_mfma_f32_16x16x32_bf16 v[96:99], v[150:153], v[170:173], v[96:99]
	v_mfma_f32_16x16x32_bf16 v[36:39], v[158:161], v[170:173], v[36:39]
	ds_read_b128 v[170:173], v6 offset:15360
	s_waitcnt lgkmcnt(3)
	v_mfma_f32_16x16x32_bf16 v[104:107], v[100:103], v[154:157], v[104:107]
	v_mfma_f32_16x16x32_bf16 v[108:111], v[140:143], v[154:157], v[108:111]
	v_mfma_f32_16x16x32_bf16 v[112:115], v[150:153], v[154:157], v[112:115]
	v_mfma_f32_16x16x32_bf16 v[52:55], v[158:161], v[154:157], v[52:55]
	s_waitcnt lgkmcnt(2)
	v_mfma_f32_16x16x32_bf16 v[116:119], v[100:103], v[162:165], v[116:119]
	v_mfma_f32_16x16x32_bf16 v[120:123], v[140:143], v[162:165], v[120:123]
	v_mfma_f32_16x16x32_bf16 v[124:127], v[150:153], v[162:165], v[124:127]
	v_mfma_f32_16x16x32_bf16 v[68:71], v[158:161], v[162:165], v[68:71]
	s_waitcnt lgkmcnt(1)
	v_mfma_f32_16x16x32_bf16 v[128:131], v[100:103], v[166:169], v[128:131]
	v_mfma_f32_16x16x32_bf16 v[132:135], v[140:143], v[166:169], v[132:135]
	v_mfma_f32_16x16x32_bf16 v[136:139], v[150:153], v[166:169], v[136:139]
	v_mfma_f32_16x16x32_bf16 v[84:87], v[158:161], v[166:169], v[84:87]
	s_waitcnt lgkmcnt(0)
	v_mfma_f32_16x16x32_bf16 v[100:103], v[100:103], v[170:173], v[8:11]
	v_mfma_f32_16x16x32_bf16 v[150:153], v[150:153], v[170:173], v[16:19]
	v_mfma_f32_16x16x32_bf16 v[24:27], v[158:161], v[170:173], v[24:27]
	v_mfma_f32_16x16x32_bf16 v[140:143], v[140:143], v[170:173], v[12:15]
	s_add_u32 s46, s16, 0x100
	s_addc_u32 s47, s17, 0
	s_add_u32 s48, s18, 0x100
	s_waitcnt vmcnt(0)
	s_barrier
	s_addc_u32 s49, s19, 0
	v_lshl_add_u64 v[8:9], s[46:47], 0, v[0:1]
	s_mov_b32 s45, m0
	s_mov_b32 m0, s1
	s_nop 0
	global_load_lds_dwordx4 v[8:9], off
	s_mov_b32 m0, s45
	v_lshl_add_u64 v[8:9], s[48:49], 0, v[0:1]
	s_mov_b32 s45, m0
	s_mov_b32 m0, s30
	s_nop 0
	global_load_lds_dwordx4 v[8:9], off
	s_mov_b32 m0, s45
	v_lshl_add_u64 v[8:9], s[46:47], 0, v[2:3]
	s_mov_b32 s45, m0
	s_mov_b32 m0, s31
	s_nop 0
	global_load_lds_dwordx4 v[8:9], off
	s_mov_b32 m0, s45
	v_lshl_add_u64 v[8:9], s[48:49], 0, v[2:3]
	s_mov_b32 s45, m0
	s_mov_b32 m0, s34
	s_nop 0
	global_load_lds_dwordx4 v[8:9], off
	s_mov_b32 m0, s45
	v_lshl_add_u64 v[8:9], s[46:47], 0, v[4:5]
	s_mov_b32 s45, m0
	s_mov_b32 m0, s35
	s_nop 0
	global_load_lds_dwordx4 v[8:9], off
	s_mov_b32 m0, s45
	v_lshl_add_u64 v[8:9], s[48:49], 0, v[4:5]
	s_mov_b32 s45, m0
	s_mov_b32 m0, s36
	s_nop 0
	global_load_lds_dwordx4 v[8:9], off
	s_mov_b32 m0, s45
	v_lshl_add_u64 v[8:9], s[46:47], 0, v[146:147]
	s_mov_b32 s45, m0
	s_mov_b32 m0, s37
	s_nop 0
	global_load_lds_dwordx4 v[8:9], off
	s_mov_b32 m0, s45
	v_lshl_add_u64 v[8:9], s[48:49], 0, v[146:147]
	s_mov_b32 s45, m0
	s_mov_b32 m0, s38
	s_nop 0
	global_load_lds_dwordx4 v[8:9], off
	s_mov_b32 m0, s45
	v_or_b32_e32 v8, 0x18000, v7
	v_or_b32_e32 v9, 0x18800, v7
	v_or_b32_e32 v11, 0x19000, v7
	v_or_b32_e32 v10, 0x19800, v7
	ds_read_b128 v[154:157], v8
	ds_read_b128 v[158:161], v9
	ds_read_b128 v[162:165], v11
	ds_read_b128 v[166:169], v10
	v_bitop3_b32 v207, v145, s33, v149 bitop3:0xde
	v_add_u32_e32 v12, v207, v182
	ds_read_b128 v[16:19], v12
	v_add_u32_e32 v13, v207, v183
	v_add_u32_e32 v14, v207, v189
	v_add_u32_e32 v15, v207, v199
	ds_read_b128 v[170:173], v13
	ds_read_b128 v[174:177], v14
	ds_read_b128 v[178:181], v15
	s_waitcnt lgkmcnt(3)
	v_mfma_f32_16x16x32_bf16 v[40:43], v[154:157], v[16:19], v[40:43]
	v_mfma_f32_16x16x32_bf16 v[44:47], v[158:161], v[16:19], v[44:47]
	v_mfma_f32_16x16x32_bf16 v[48:51], v[162:165], v[16:19], v[48:51]
	v_mfma_f32_16x16x32_bf16 v[214:217], v[166:169], v[16:19], v[20:23]
	v_add_u32_e32 v16, v207, v200
	v_add_u32_e32 v17, v207, v201
	v_add_u32_e32 v18, v207, v203
	v_add_u32_e32 v19, v207, v206
	ds_read_b128 v[20:23], v16
	s_waitcnt lgkmcnt(3)
	v_mfma_f32_16x16x32_bf16 v[56:59], v[154:157], v[170:173], v[56:59]
	v_mfma_f32_16x16x32_bf16 v[60:63], v[158:161], v[170:173], v[60:63]
	v_mfma_f32_16x16x32_bf16 v[64:67], v[162:165], v[170:173], v[64:67]
	v_mfma_f32_16x16x32_bf16 v[170:173], v[166:169], v[170:173], v[28:31]
	s_nop 2
	ds_read_b128 v[28:31], v17
	s_waitcnt lgkmcnt(3)
	v_mfma_f32_16x16x32_bf16 v[72:75], v[154:157], v[174:177], v[72:75]
	v_mfma_f32_16x16x32_bf16 v[76:79], v[158:161], v[174:177], v[76:79]
	v_mfma_f32_16x16x32_bf16 v[80:83], v[162:165], v[174:177], v[80:83]
	v_mfma_f32_16x16x32_bf16 v[32:35], v[166:169], v[174:177], v[32:35]
	ds_read_b128 v[174:177], v18
	s_waitcnt lgkmcnt(3)
	v_mfma_f32_16x16x32_bf16 v[88:91], v[154:157], v[178:181], v[88:91]
	v_mfma_f32_16x16x32_bf16 v[92:95], v[158:161], v[178:181], v[92:95]
	v_mfma_f32_16x16x32_bf16 v[96:99], v[162:165], v[178:181], v[96:99]
	v_mfma_f32_16x16x32_bf16 v[36:39], v[166:169], v[178:181], v[36:39]
	ds_read_b128 v[178:181], v19
	s_waitcnt lgkmcnt(3)
	v_mfma_f32_16x16x32_bf16 v[104:107], v[154:157], v[20:23], v[104:107]
	v_mfma_f32_16x16x32_bf16 v[108:111], v[158:161], v[20:23], v[108:111]
	v_mfma_f32_16x16x32_bf16 v[112:115], v[162:165], v[20:23], v[112:115]
	v_mfma_f32_16x16x32_bf16 v[52:55], v[166:169], v[20:23], v[52:55]
	s_waitcnt lgkmcnt(2)
	v_mfma_f32_16x16x32_bf16 v[116:119], v[154:157], v[28:31], v[116:119]
	v_mfma_f32_16x16x32_bf16 v[120:123], v[158:161], v[28:31], v[120:123]
	v_mfma_f32_16x16x32_bf16 v[124:127], v[162:165], v[28:31], v[124:127]
	v_mfma_f32_16x16x32_bf16 v[68:71], v[166:169], v[28:31], v[68:71]
	s_waitcnt lgkmcnt(1)
	v_mfma_f32_16x16x32_bf16 v[128:131], v[154:157], v[174:177], v[128:131]
	v_mfma_f32_16x16x32_bf16 v[132:135], v[158:161], v[174:177], v[132:135]
	v_mfma_f32_16x16x32_bf16 v[84:87], v[166:169], v[174:177], v[84:87]
	s_waitcnt lgkmcnt(0)
	v_mfma_f32_16x16x32_bf16 v[100:103], v[154:157], v[178:181], v[100:103]
	v_mfma_f32_16x16x32_bf16 v[150:153], v[162:165], v[178:181], v[150:153]
	v_mfma_f32_16x16x32_bf16 v[154:157], v[166:169], v[178:181], v[24:27]
	v_mfma_f32_16x16x32_bf16 v[136:139], v[162:165], v[174:177], v[136:139]
	v_mfma_f32_16x16x32_bf16 v[140:143], v[158:161], v[178:181], v[140:143]
	v_or_b32_e32 v20, 0x18400, v7
	v_or_b32_e32 v21, 0x18c00, v7
	v_or_b32_e32 v23, 0x19400, v7
	v_or_b32_e32 v22, 0x19c00, v7
	ds_read_b128 v[158:161], v20
	ds_read_b128 v[162:165], v21
	ds_read_b128 v[166:169], v23
	ds_read_b128 v[174:177], v22
	s_mov_b32 s45, 0x10400
	v_bitop3_b32 v145, v145, s45, v149 bitop3:0xde
	v_add_u32_e32 v24, v145, v182
	ds_read_b128 v[28:31], v24
	v_add_u32_e32 v25, v145, v183
	v_add_u32_e32 v26, v145, v189
	v_add_u32_e32 v27, v145, v199
	ds_read_b128 v[178:181], v25
	ds_read_b128 v[218:221], v26
	ds_read_b128 v[222:225], v27
	s_waitcnt lgkmcnt(3)
	v_mfma_f32_16x16x32_bf16 v[40:43], v[158:161], v[28:31], v[40:43]
	v_mfma_f32_16x16x32_bf16 v[44:47], v[162:165], v[28:31], v[44:47]
	v_mfma_f32_16x16x32_bf16 v[48:51], v[166:169], v[28:31], v[48:51]
	v_mfma_f32_16x16x32_bf16 v[214:217], v[174:177], v[28:31], v[214:217]
	v_add_u32_e32 v28, v145, v200
	v_add_u32_e32 v29, v145, v201
	v_add_u32_e32 v30, v145, v203
	v_add_u32_e32 v31, v145, v206
	ds_read_b128 v[226:229], v28
	s_waitcnt lgkmcnt(3)
	v_mfma_f32_16x16x32_bf16 v[56:59], v[158:161], v[178:181], v[56:59]
	v_mfma_f32_16x16x32_bf16 v[60:63], v[162:165], v[178:181], v[60:63]
	v_mfma_f32_16x16x32_bf16 v[64:67], v[166:169], v[178:181], v[64:67]
	v_mfma_f32_16x16x32_bf16 v[170:173], v[174:177], v[178:181], v[170:173]
	ds_read_b128 v[178:181], v29
	s_waitcnt lgkmcnt(3)
	v_mfma_f32_16x16x32_bf16 v[72:75], v[158:161], v[218:221], v[72:75]
	v_mfma_f32_16x16x32_bf16 v[76:79], v[162:165], v[218:221], v[76:79]
	v_mfma_f32_16x16x32_bf16 v[80:83], v[166:169], v[218:221], v[80:83]
	v_mfma_f32_16x16x32_bf16 v[32:35], v[174:177], v[218:221], v[32:35]
	ds_read_b128 v[218:221], v30
	s_waitcnt lgkmcnt(3)
	v_mfma_f32_16x16x32_bf16 v[88:91], v[158:161], v[222:225], v[88:91]
	v_mfma_f32_16x16x32_bf16 v[92:95], v[162:165], v[222:225], v[92:95]
	v_mfma_f32_16x16x32_bf16 v[96:99], v[166:169], v[222:225], v[96:99]
	v_mfma_f32_16x16x32_bf16 v[36:39], v[174:177], v[222:225], v[36:39]
	ds_read_b128 v[222:225], v31
	s_waitcnt lgkmcnt(3)
	v_mfma_f32_16x16x32_bf16 v[104:107], v[158:161], v[226:229], v[104:107]
	v_mfma_f32_16x16x32_bf16 v[108:111], v[162:165], v[226:229], v[108:111]
	v_mfma_f32_16x16x32_bf16 v[112:115], v[166:169], v[226:229], v[112:115]
	v_mfma_f32_16x16x32_bf16 v[52:55], v[174:177], v[226:229], v[52:55]
	s_waitcnt lgkmcnt(2)
	v_mfma_f32_16x16x32_bf16 v[116:119], v[158:161], v[178:181], v[116:119]
	v_mfma_f32_16x16x32_bf16 v[120:123], v[162:165], v[178:181], v[120:123]
	v_mfma_f32_16x16x32_bf16 v[124:127], v[166:169], v[178:181], v[124:127]
	v_mfma_f32_16x16x32_bf16 v[68:71], v[174:177], v[178:181], v[68:71]
	s_waitcnt lgkmcnt(1)
	v_mfma_f32_16x16x32_bf16 v[132:135], v[162:165], v[218:221], v[132:135]
	v_mfma_f32_16x16x32_bf16 v[84:87], v[174:177], v[218:221], v[84:87]
	s_waitcnt lgkmcnt(0)
	v_mfma_f32_16x16x32_bf16 v[100:103], v[158:161], v[222:225], v[100:103]
	v_mfma_f32_16x16x32_bf16 v[150:153], v[166:169], v[222:225], v[150:153]
	v_mfma_f32_16x16x32_bf16 v[154:157], v[174:177], v[222:225], v[154:157]
	v_mfma_f32_16x16x32_bf16 v[128:131], v[158:161], v[218:221], v[128:131]
	v_mfma_f32_16x16x32_bf16 v[136:139], v[166:169], v[218:221], v[136:139]
	v_mfma_f32_16x16x32_bf16 v[140:143], v[162:165], v[222:225], v[140:143]
	s_add_u32 s46, s16, 0x180
	s_addc_u32 s47, s17, 0
	s_add_u32 s48, s18, 0x180
	s_waitcnt vmcnt(0)
	s_barrier
	s_addc_u32 s49, s19, 0
	v_lshl_add_u64 v[158:159], s[46:47], 0, v[0:1]
	s_mov_b32 s45, m0
	s_mov_b32 m0, s25
	s_nop 0
	global_load_lds_dwordx4 v[158:159], off
	s_mov_b32 m0, s45
	v_lshl_add_u64 v[158:159], s[48:49], 0, v[0:1]
	s_mov_b32 s45, m0
	s_mov_b32 m0, s24
	s_nop 0
	global_load_lds_dwordx4 v[158:159], off
	s_mov_b32 m0, s45
	v_lshl_add_u64 v[158:159], s[46:47], 0, v[2:3]
	s_mov_b32 s45, m0
	s_mov_b32 m0, s39
	s_nop 0
	global_load_lds_dwordx4 v[158:159], off
	s_mov_b32 m0, s45
	v_lshl_add_u64 v[158:159], s[48:49], 0, v[2:3]
	s_mov_b32 s45, m0
	s_mov_b32 m0, s40
	s_nop 0
	global_load_lds_dwordx4 v[158:159], off
	s_mov_b32 m0, s45
	v_lshl_add_u64 v[158:159], s[46:47], 0, v[4:5]
	s_mov_b32 s45, m0
	s_mov_b32 m0, s41
	s_nop 0
	global_load_lds_dwordx4 v[158:159], off
	s_mov_b32 m0, s45
	v_lshl_add_u64 v[158:159], s[48:49], 0, v[4:5]
	s_mov_b32 s45, m0
	s_mov_b32 m0, s42
	s_nop 0
	global_load_lds_dwordx4 v[158:159], off
	s_mov_b32 m0, s45
	v_lshl_add_u64 v[158:159], s[46:47], 0, v[146:147]
	s_mov_b32 s45, m0
	s_mov_b32 m0, s43
	s_nop 0
	global_load_lds_dwordx4 v[158:159], off
	s_mov_b32 m0, s45
	v_lshl_add_u64 v[158:159], s[48:49], 0, v[146:147]
	s_mov_b32 s45, m0
	s_mov_b32 m0, s44
	s_nop 0
	global_load_lds_dwordx4 v[158:159], off
	s_mov_b32 m0, s45
	ds_read_b128 v[158:161], v7 offset:32768
	ds_read_b128 v[162:165], v7 offset:34816
	ds_read_b128 v[166:169], v7 offset:36864
	ds_read_b128 v[178:181], v7 offset:38912
	ds_read_b128 v[174:177], v6
	ds_read_b128 v[218:221], v6 offset:2048
	ds_read_b128 v[222:225], v6 offset:4096
	ds_read_b128 v[226:229], v6 offset:6144
	s_waitcnt lgkmcnt(3)
	v_mfma_f32_16x16x32_bf16 v[40:43], v[158:161], v[174:177], v[40:43]
	v_mfma_f32_16x16x32_bf16 v[44:47], v[162:165], v[174:177], v[44:47]
	v_mfma_f32_16x16x32_bf16 v[48:51], v[166:169], v[174:177], v[48:51]
	v_mfma_f32_16x16x32_bf16 v[174:177], v[178:181], v[174:177], v[214:217]
	s_nop 2
	ds_read_b128 v[214:217], v6 offset:8192
	s_waitcnt lgkmcnt(3)
	v_mfma_f32_16x16x32_bf16 v[56:59], v[158:161], v[218:221], v[56:59]
	v_mfma_f32_16x16x32_bf16 v[60:63], v[162:165], v[218:221], v[60:63]
	v_mfma_f32_16x16x32_bf16 v[64:67], v[166:169], v[218:221], v[64:67]
	v_mfma_f32_16x16x32_bf16 v[170:173], v[178:181], v[218:221], v[170:173]
	ds_read_b128 v[218:221], v6 offset:10240
	s_waitcnt lgkmcnt(3)
	v_mfma_f32_16x16x32_bf16 v[72:75], v[158:161], v[222:225], v[72:75]
	v_mfma_f32_16x16x32_bf16 v[76:79], v[162:165], v[222:225], v[76:79]
	v_mfma_f32_16x16x32_bf16 v[80:83], v[166:169], v[222:225], v[80:83]
	v_mfma_f32_16x16x32_bf16 v[32:35], v[178:181], v[222:225], v[32:35]
	ds_read_b128 v[222:225], v6 offset:12288
	s_waitcnt lgkmcnt(3)
	v_mfma_f32_16x16x32_bf16 v[88:91], v[158:161], v[226:229], v[88:91]
	v_mfma_f32_16x16x32_bf16 v[92:95], v[162:165], v[226:229], v[92:95]
	v_mfma_f32_16x16x32_bf16 v[96:99], v[166:169], v[226:229], v[96:99]
	v_mfma_f32_16x16x32_bf16 v[36:39], v[178:181], v[226:229], v[36:39]
	ds_read_b128 v[226:229], v6 offset:14336
	s_waitcnt lgkmcnt(3)
	v_mfma_f32_16x16x32_bf16 v[104:107], v[158:161], v[214:217], v[104:107]
	v_mfma_f32_16x16x32_bf16 v[108:111], v[162:165], v[214:217], v[108:111]
	v_mfma_f32_16x16x32_bf16 v[112:115], v[166:169], v[214:217], v[112:115]
	v_mfma_f32_16x16x32_bf16 v[52:55], v[178:181], v[214:217], v[52:55]
	s_waitcnt lgkmcnt(2)
	v_mfma_f32_16x16x32_bf16 v[116:119], v[158:161], v[218:221], v[116:119]
	v_mfma_f32_16x16x32_bf16 v[120:123], v[162:165], v[218:221], v[120:123]
	v_mfma_f32_16x16x32_bf16 v[124:127], v[166:169], v[218:221], v[124:127]
	v_mfma_f32_16x16x32_bf16 v[68:71], v[178:181], v[218:221], v[68:71]
	s_waitcnt lgkmcnt(1)
	v_mfma_f32_16x16x32_bf16 v[132:135], v[162:165], v[222:225], v[132:135]
	v_mfma_f32_16x16x32_bf16 v[84:87], v[178:181], v[222:225], v[84:87]
	s_waitcnt lgkmcnt(0)
	v_mfma_f32_16x16x32_bf16 v[100:103], v[158:161], v[226:229], v[100:103]
	v_mfma_f32_16x16x32_bf16 v[150:153], v[166:169], v[226:229], v[150:153]
	v_mfma_f32_16x16x32_bf16 v[154:157], v[178:181], v[226:229], v[154:157]
	v_mfma_f32_16x16x32_bf16 v[128:131], v[158:161], v[222:225], v[128:131]
	v_mfma_f32_16x16x32_bf16 v[136:139], v[166:169], v[222:225], v[136:139]
	v_mfma_f32_16x16x32_bf16 v[140:143], v[162:165], v[226:229], v[140:143]
	ds_read_b128 v[158:161], v7 offset:33792
	ds_read_b128 v[162:165], v7 offset:35840
	ds_read_b128 v[166:169], v7 offset:37888
	ds_read_b128 v[214:217], v7 offset:39936
	ds_read_b128 v[178:181], v6 offset:1024
	ds_read_b128 v[218:221], v6 offset:3072
	ds_read_b128 v[222:225], v6 offset:5120
	ds_read_b128 v[226:229], v6 offset:7168
	s_waitcnt lgkmcnt(3)
	v_mfma_f32_16x16x32_bf16 v[40:43], v[158:161], v[178:181], v[40:43]
	v_mfma_f32_16x16x32_bf16 v[44:47], v[162:165], v[178:181], v[44:47]
	v_mfma_f32_16x16x32_bf16 v[48:51], v[166:169], v[178:181], v[48:51]
	v_mfma_f32_16x16x32_bf16 v[174:177], v[214:217], v[178:181], v[174:177]
	ds_read_b128 v[178:181], v6 offset:9216
	s_waitcnt lgkmcnt(3)
	v_mfma_f32_16x16x32_bf16 v[56:59], v[158:161], v[218:221], v[56:59]
	v_mfma_f32_16x16x32_bf16 v[60:63], v[162:165], v[218:221], v[60:63]
	v_mfma_f32_16x16x32_bf16 v[64:67], v[166:169], v[218:221], v[64:67]
	v_mfma_f32_16x16x32_bf16 v[170:173], v[214:217], v[218:221], v[170:173]
	ds_read_b128 v[218:221], v6 offset:11264
	s_waitcnt lgkmcnt(3)
	v_mfma_f32_16x16x32_bf16 v[72:75], v[158:161], v[222:225], v[72:75]
	v_mfma_f32_16x16x32_bf16 v[76:79], v[162:165], v[222:225], v[76:79]
	v_mfma_f32_16x16x32_bf16 v[80:83], v[166:169], v[222:225], v[80:83]
	v_mfma_f32_16x16x32_bf16 v[32:35], v[214:217], v[222:225], v[32:35]
	ds_read_b128 v[222:225], v6 offset:13312
	s_waitcnt lgkmcnt(3)
	v_mfma_f32_16x16x32_bf16 v[88:91], v[158:161], v[226:229], v[88:91]
	v_mfma_f32_16x16x32_bf16 v[92:95], v[162:165], v[226:229], v[92:95]
	v_mfma_f32_16x16x32_bf16 v[96:99], v[166:169], v[226:229], v[96:99]
	v_mfma_f32_16x16x32_bf16 v[36:39], v[214:217], v[226:229], v[36:39]
	ds_read_b128 v[226:229], v6 offset:15360
	s_waitcnt lgkmcnt(3)
	v_mfma_f32_16x16x32_bf16 v[104:107], v[158:161], v[178:181], v[104:107]
	v_mfma_f32_16x16x32_bf16 v[108:111], v[162:165], v[178:181], v[108:111]
	v_mfma_f32_16x16x32_bf16 v[112:115], v[166:169], v[178:181], v[112:115]
	v_mfma_f32_16x16x32_bf16 v[52:55], v[214:217], v[178:181], v[52:55]
	s_waitcnt lgkmcnt(2)
	v_mfma_f32_16x16x32_bf16 v[116:119], v[158:161], v[218:221], v[116:119]
	v_mfma_f32_16x16x32_bf16 v[120:123], v[162:165], v[218:221], v[120:123]
	v_mfma_f32_16x16x32_bf16 v[124:127], v[166:169], v[218:221], v[124:127]
	v_mfma_f32_16x16x32_bf16 v[68:71], v[214:217], v[218:221], v[68:71]
	s_waitcnt lgkmcnt(1)
	v_mfma_f32_16x16x32_bf16 v[132:135], v[162:165], v[222:225], v[132:135]
	v_mfma_f32_16x16x32_bf16 v[84:87], v[214:217], v[222:225], v[84:87]
	s_waitcnt lgkmcnt(0)
	v_mfma_f32_16x16x32_bf16 v[100:103], v[158:161], v[226:229], v[100:103]
	v_mfma_f32_16x16x32_bf16 v[150:153], v[166:169], v[226:229], v[150:153]
	v_mfma_f32_16x16x32_bf16 v[154:157], v[214:217], v[226:229], v[154:157]
	v_mfma_f32_16x16x32_bf16 v[128:131], v[158:161], v[222:225], v[128:131]
	v_mfma_f32_16x16x32_bf16 v[136:139], v[166:169], v[222:225], v[136:139]
	v_mfma_f32_16x16x32_bf16 v[140:143], v[162:165], v[226:229], v[140:143]
	s_add_u32 s46, s16, 0x200
	s_addc_u32 s47, s17, 0
	s_add_u32 s48, s18, 0x200
	s_waitcnt vmcnt(0)
	s_barrier
	s_addc_u32 s49, s19, 0
	s_mov_b32 s45, 0x280
	ds_read_b128 v[158:161], v8
	ds_read_b128 v[162:165], v12
	ds_read_b128 v[166:169], v9
	ds_read_b128 v[178:181], v13
	ds_read_b128 v[214:217], v11
	ds_read_b128 v[218:221], v10
	ds_read_b128 v[222:225], v14
	ds_read_b128 v[226:229], v15
	s_branch .Lmy_rot_r_r2b
.Lmy_rr_r2b:
	ds_read_b128 v[158:161], v8
	ds_read_b128 v[162:165], v12
	v_mfma_f32_16x16x32_bf16 v[128:131], v[166:169], v[222:225], v[128:131]
	v_mfma_f32_16x16x32_bf16 v[100:103], v[166:169], v[226:229], v[100:103]
	ds_read_b128 v[166:169], v9
	v_mfma_f32_16x16x32_bf16 v[132:135], v[178:181], v[222:225], v[132:135]
	v_mfma_f32_16x16x32_bf16 v[140:143], v[178:181], v[226:229], v[140:143]
	ds_read_b128 v[178:181], v13
	v_mfma_f32_16x16x32_bf16 v[136:139], v[214:217], v[222:225], v[136:139]
	v_mfma_f32_16x16x32_bf16 v[150:153], v[214:217], v[226:229], v[150:153]
	ds_read_b128 v[214:217], v11
	v_mfma_f32_16x16x32_bf16 v[84:87], v[218:221], v[222:225], v[84:87]
	v_mfma_f32_16x16x32_bf16 v[154:157], v[218:221], v[226:229], v[154:157]
	ds_read_b128 v[218:221], v10
	ds_read_b128 v[222:225], v14
	ds_read_b128 v[226:229], v15
.Lmy_rot_r_r2b:
	s_waitcnt lgkmcnt(6)
	v_mfma_f32_16x16x32_bf16 v[40:43], v[158:161], v[162:165], v[40:43]
	s_waitcnt lgkmcnt(5)
	v_mfma_f32_16x16x32_bf16 v[44:47], v[166:169], v[162:165], v[44:47]
	s_waitcnt lgkmcnt(4)
	s_mov_b32 m0, s1
	v_mfma_f32_16x16x32_bf16 v[56:59], v[158:161], v[178:181], v[56:59]
	global_load_lds_dwordx4 v0, s[46:47]
	v_mfma_f32_16x16x32_bf16 v[60:63], v[166:169], v[178:181], v[60:63]
	s_waitcnt lgkmcnt(3)
	v_mfma_f32_16x16x32_bf16 v[48:51], v[214:217], v[162:165], v[48:51]
	v_mfma_f32_16x16x32_bf16 v[64:67], v[214:217], v[178:181], v[64:67]
	s_waitcnt lgkmcnt(2)
	s_mov_b32 m0, s30
	v_mfma_f32_16x16x32_bf16 v[174:177], v[218:221], v[162:165], v[174:177]
	global_load_lds_dwordx4 v0, s[48:49]
	ds_read_b128 v[162:165], v16
	v_mfma_f32_16x16x32_bf16 v[170:173], v[218:221], v[178:181], v[170:173]
	ds_read_b128 v[178:181], v17
	s_waitcnt lgkmcnt(3)
	v_mfma_f32_16x16x32_bf16 v[72:75], v[158:161], v[222:225], v[72:75]
	v_mfma_f32_16x16x32_bf16 v[76:79], v[166:169], v[222:225], v[76:79]
	s_mov_b32 m0, s31
	v_mfma_f32_16x16x32_bf16 v[80:83], v[214:217], v[222:225], v[80:83]
	global_load_lds_dwordx4 v2, s[46:47]
	v_mfma_f32_16x16x32_bf16 v[32:35], v[218:221], v[222:225], v[32:35]
	ds_read_b128 v[222:225], v18
	s_waitcnt lgkmcnt(3)
	v_mfma_f32_16x16x32_bf16 v[88:91], v[158:161], v[226:229], v[88:91]
	v_mfma_f32_16x16x32_bf16 v[92:95], v[166:169], v[226:229], v[92:95]
	s_mov_b32 m0, s34
	v_mfma_f32_16x16x32_bf16 v[96:99], v[214:217], v[226:229], v[96:99]
	global_load_lds_dwordx4 v2, s[48:49]
	v_mfma_f32_16x16x32_bf16 v[36:39], v[218:221], v[226:229], v[36:39]
	ds_read_b128 v[226:229], v19
	s_waitcnt lgkmcnt(3)
	v_mfma_f32_16x16x32_bf16 v[108:111], v[166:169], v[162:165], v[108:111]
	s_waitcnt lgkmcnt(2)
	v_mfma_f32_16x16x32_bf16 v[120:123], v[166:169], v[178:181], v[120:123]
	s_waitcnt lgkmcnt(1)
	s_mov_b32 m0, s35
	v_mfma_f32_16x16x32_bf16 v[132:135], v[166:169], v[222:225], v[132:135]
	global_load_lds_dwordx4 v4, s[46:47]
	s_waitcnt lgkmcnt(0)
	v_mfma_f32_16x16x32_bf16 v[140:143], v[166:169], v[226:229], v[140:143]
	ds_read_b128 v[166:169], v20
	v_mfma_f32_16x16x32_bf16 v[104:107], v[158:161], v[162:165], v[104:107]
	v_mfma_f32_16x16x32_bf16 v[116:119], v[158:161], v[178:181], v[116:119]
	s_mov_b32 m0, s36
	v_mfma_f32_16x16x32_bf16 v[128:131], v[158:161], v[222:225], v[128:131]
	global_load_lds_dwordx4 v4, s[48:49]
	v_mfma_f32_16x16x32_bf16 v[100:103], v[158:161], v[226:229], v[100:103]
	ds_read_b128 v[158:161], v24
	v_mfma_f32_16x16x32_bf16 v[124:127], v[214:217], v[178:181], v[124:127]
	v_mfma_f32_16x16x32_bf16 v[68:71], v[218:221], v[178:181], v[68:71]
	ds_read_b128 v[178:181], v21
	s_mov_b32 m0, s37
	v_mfma_f32_16x16x32_bf16 v[112:115], v[214:217], v[162:165], v[112:115]
	global_load_lds_dwordx4 v146, s[46:47]
	v_mfma_f32_16x16x32_bf16 v[52:55], v[218:221], v[162:165], v[52:55]
	ds_read_b128 v[162:165], v25
	v_mfma_f32_16x16x32_bf16 v[136:139], v[214:217], v[222:225], v[136:139]
	v_mfma_f32_16x16x32_bf16 v[84:87], v[218:221], v[222:225], v[84:87]
	ds_read_b128 v[222:225], v26
	s_mov_b32 m0, s38
	v_mfma_f32_16x16x32_bf16 v[150:153], v[214:217], v[226:229], v[150:153]
	global_load_lds_dwordx4 v146, s[48:49]
	ds_read_b128 v[214:217], v23
	v_mfma_f32_16x16x32_bf16 v[154:157], v[218:221], v[226:229], v[154:157]
	ds_read_b128 v[218:221], v22
	ds_read_b128 v[226:229], v27
	s_waitcnt lgkmcnt(6)
	v_mfma_f32_16x16x32_bf16 v[40:43], v[166:169], v[158:161], v[40:43]
	s_waitcnt lgkmcnt(5)
	v_mfma_f32_16x16x32_bf16 v[44:47], v[178:181], v[158:161], v[44:47]
	s_waitcnt lgkmcnt(4)
	v_mfma_f32_16x16x32_bf16 v[56:59], v[166:169], v[162:165], v[56:59]
	v_mfma_f32_16x16x32_bf16 v[60:63], v[178:181], v[162:165], v[60:63]
	s_waitcnt lgkmcnt(3)
	v_mfma_f32_16x16x32_bf16 v[72:75], v[166:169], v[222:225], v[72:75]
	v_mfma_f32_16x16x32_bf16 v[76:79], v[178:181], v[222:225], v[76:79]
	s_waitcnt lgkmcnt(2)
	v_mfma_f32_16x16x32_bf16 v[48:51], v[214:217], v[158:161], v[48:51]
	s_waitcnt lgkmcnt(1)
	v_mfma_f32_16x16x32_bf16 v[174:177], v[218:221], v[158:161], v[174:177]
	ds_read_b128 v[158:161], v28
	v_mfma_f32_16x16x32_bf16 v[64:67], v[214:217], v[162:165], v[64:67]
	v_mfma_f32_16x16x32_bf16 v[170:173], v[218:221], v[162:165], v[170:173]
	ds_read_b128 v[162:165], v29
	v_mfma_f32_16x16x32_bf16 v[80:83], v[214:217], v[222:225], v[80:83]
	v_mfma_f32_16x16x32_bf16 v[32:35], v[218:221], v[222:225], v[32:35]
	ds_read_b128 v[222:225], v30
	s_waitcnt lgkmcnt(3)
	v_mfma_f32_16x16x32_bf16 v[88:91], v[166:169], v[226:229], v[88:91]
	v_mfma_f32_16x16x32_bf16 v[92:95], v[178:181], v[226:229], v[92:95]
	v_mfma_f32_16x16x32_bf16 v[96:99], v[214:217], v[226:229], v[96:99]
	v_mfma_f32_16x16x32_bf16 v[36:39], v[218:221], v[226:229], v[36:39]
	ds_read_b128 v[226:229], v31
	s_waitcnt lgkmcnt(3)
	v_mfma_f32_16x16x32_bf16 v[104:107], v[166:169], v[158:161], v[104:107]
	v_mfma_f32_16x16x32_bf16 v[108:111], v[178:181], v[158:161], v[108:111]
	v_mfma_f32_16x16x32_bf16 v[112:115], v[214:217], v[158:161], v[112:115]
	v_mfma_f32_16x16x32_bf16 v[52:55], v[218:221], v[158:161], v[52:55]
	s_waitcnt lgkmcnt(2)
	v_mfma_f32_16x16x32_bf16 v[116:119], v[166:169], v[162:165], v[116:119]
	v_mfma_f32_16x16x32_bf16 v[120:123], v[178:181], v[162:165], v[120:123]
	v_mfma_f32_16x16x32_bf16 v[124:127], v[214:217], v[162:165], v[124:127]
	v_mfma_f32_16x16x32_bf16 v[68:71], v[218:221], v[162:165], v[68:71]
	s_add_u32 s46, s16, s45
	s_addc_u32 s47, s17, 0
	s_add_u32 s48, s18, s45
	s_addc_u32 s49, s19, 0
	s_add_u32 s45, s45, 0x80
	s_waitcnt vmcnt(0)
	s_waitcnt lgkmcnt(0)
	s_barrier
	ds_read_b128 v[158:161], v7 offset:32768
	ds_read_b128 v[162:165], v6
	v_mfma_f32_16x16x32_bf16 v[128:131], v[166:169], v[222:225], v[128:131]
	v_mfma_f32_16x16x32_bf16 v[100:103], v[166:169], v[226:229], v[100:103]
	ds_read_b128 v[166:169], v7 offset:34816
	v_mfma_f32_16x16x32_bf16 v[132:135], v[178:181], v[222:225], v[132:135]
	v_mfma_f32_16x16x32_bf16 v[140:143], v[178:181], v[226:229], v[140:143]
	ds_read_b128 v[178:181], v6 offset:2048
	v_mfma_f32_16x16x32_bf16 v[136:139], v[214:217], v[222:225], v[136:139]
	v_mfma_f32_16x16x32_bf16 v[150:153], v[214:217], v[226:229], v[150:153]
	ds_read_b128 v[214:217], v7 offset:36864
	v_mfma_f32_16x16x32_bf16 v[84:87], v[218:221], v[222:225], v[84:87]
	v_mfma_f32_16x16x32_bf16 v[154:157], v[218:221], v[226:229], v[154:157]
	ds_read_b128 v[218:221], v7 offset:38912
	ds_read_b128 v[222:225], v6 offset:4096
	ds_read_b128 v[226:229], v6 offset:6144
	s_waitcnt lgkmcnt(6)
	v_mfma_f32_16x16x32_bf16 v[40:43], v[158:161], v[162:165], v[40:43]
	s_waitcnt lgkmcnt(5)
	v_mfma_f32_16x16x32_bf16 v[44:47], v[166:169], v[162:165], v[44:47]
	s_waitcnt lgkmcnt(4)
	s_mov_b32 m0, s25
	v_mfma_f32_16x16x32_bf16 v[56:59], v[158:161], v[178:181], v[56:59]
	global_load_lds_dwordx4 v0, s[46:47]
	v_mfma_f32_16x16x32_bf16 v[60:63], v[166:169], v[178:181], v[60:63]
	s_waitcnt lgkmcnt(3)
	v_mfma_f32_16x16x32_bf16 v[48:51], v[214:217], v[162:165], v[48:51]
	v_mfma_f32_16x16x32_bf16 v[64:67], v[214:217], v[178:181], v[64:67]
	s_waitcnt lgkmcnt(2)
	s_mov_b32 m0, s24
	v_mfma_f32_16x16x32_bf16 v[174:177], v[218:221], v[162:165], v[174:177]
	global_load_lds_dwordx4 v0, s[48:49]
	ds_read_b128 v[162:165], v6 offset:8192
	v_mfma_f32_16x16x32_bf16 v[170:173], v[218:221], v[178:181], v[170:173]
	ds_read_b128 v[178:181], v6 offset:10240
	s_waitcnt lgkmcnt(3)
	v_mfma_f32_16x16x32_bf16 v[72:75], v[158:161], v[222:225], v[72:75]
	v_mfma_f32_16x16x32_bf16 v[76:79], v[166:169], v[222:225], v[76:79]
	s_mov_b32 m0, s39
	v_mfma_f32_16x16x32_bf16 v[80:83], v[214:217], v[222:225], v[80:83]
	global_load_lds_dwordx4 v2, s[46:47]
	v_mfma_f32_16x16x32_bf16 v[32:35], v[218:221], v[222:225], v[32:35]
	ds_read_b128 v[222:225], v6 offset:12288
	s_waitcnt lgkmcnt(3)
	v_mfma_f32_16x16x32_bf16 v[88:91], v[158:161], v[226:229], v[88:91]
	v_mfma_f32_16x16x32_bf16 v[92:95], v[166:169], v[226:229], v[92:95]
	s_mov_b32 m0, s40
	v_mfma_f32_16x16x32_bf16 v[96:99], v[214:217], v[226:229], v[96:99]
	global_load_lds_dwordx4 v2, s[48:49]
	v_mfma_f32_16x16x32_bf16 v[36:39], v[218:221], v[226:229], v[36:39]
	ds_read_b128 v[226:229], v6 offset:14336
	s_waitcnt lgkmcnt(3)
	v_mfma_f32_16x16x32_bf16 v[108:111], v[166:169], v[162:165], v[108:111]
	s_waitcnt lgkmcnt(2)
	v_mfma_f32_16x16x32_bf16 v[120:123], v[166:169], v[178:181], v[120:123]
	s_waitcnt lgkmcnt(1)
	s_mov_b32 m0, s41
	v_mfma_f32_16x16x32_bf16 v[132:135], v[166:169], v[222:225], v[132:135]
	global_load_lds_dwordx4 v4, s[46:47]
	s_waitcnt lgkmcnt(0)
	v_mfma_f32_16x16x32_bf16 v[140:143], v[166:169], v[226:229], v[140:143]
	ds_read_b128 v[166:169], v7 offset:33792
	v_mfma_f32_16x16x32_bf16 v[104:107], v[158:161], v[162:165], v[104:107]
	v_mfma_f32_16x16x32_bf16 v[116:119], v[158:161], v[178:181], v[116:119]
	s_mov_b32 m0, s42
	v_mfma_f32_16x16x32_bf16 v[128:131], v[158:161], v[222:225], v[128:131]
	global_load_lds_dwordx4 v4, s[48:49]
	v_mfma_f32_16x16x32_bf16 v[100:103], v[158:161], v[226:229], v[100:103]
	ds_read_b128 v[158:161], v6 offset:1024
	v_mfma_f32_16x16x32_bf16 v[124:127], v[214:217], v[178:181], v[124:127]
	v_mfma_f32_16x16x32_bf16 v[68:71], v[218:221], v[178:181], v[68:71]
	ds_read_b128 v[178:181], v7 offset:35840
	s_mov_b32 m0, s43
	v_mfma_f32_16x16x32_bf16 v[112:115], v[214:217], v[162:165], v[112:115]
	global_load_lds_dwordx4 v146, s[46:47]
	v_mfma_f32_16x16x32_bf16 v[52:55], v[218:221], v[162:165], v[52:55]
	ds_read_b128 v[162:165], v6 offset:3072
	v_mfma_f32_16x16x32_bf16 v[136:139], v[214:217], v[222:225], v[136:139]
	v_mfma_f32_16x16x32_bf16 v[84:87], v[218:221], v[222:225], v[84:87]
	ds_read_b128 v[222:225], v6 offset:5120
	s_mov_b32 m0, s44
	v_mfma_f32_16x16x32_bf16 v[150:153], v[214:217], v[226:229], v[150:153]
	global_load_lds_dwordx4 v146, s[48:49]
	ds_read_b128 v[214:217], v7 offset:37888
	v_mfma_f32_16x16x32_bf16 v[154:157], v[218:221], v[226:229], v[154:157]
	ds_read_b128 v[218:221], v7 offset:39936
	ds_read_b128 v[226:229], v6 offset:7168
	s_waitcnt lgkmcnt(6)
	v_mfma_f32_16x16x32_bf16 v[40:43], v[166:169], v[158:161], v[40:43]
	s_waitcnt lgkmcnt(5)
	v_mfma_f32_16x16x32_bf16 v[44:47], v[178:181], v[158:161], v[44:47]
	s_waitcnt lgkmcnt(4)
	v_mfma_f32_16x16x32_bf16 v[56:59], v[166:169], v[162:165], v[56:59]
	v_mfma_f32_16x16x32_bf16 v[60:63], v[178:181], v[162:165], v[60:63]
	s_waitcnt lgkmcnt(3)
	v_mfma_f32_16x16x32_bf16 v[72:75], v[166:169], v[222:225], v[72:75]
	v_mfma_f32_16x16x32_bf16 v[76:79], v[178:181], v[222:225], v[76:79]
	s_waitcnt lgkmcnt(2)
	v_mfma_f32_16x16x32_bf16 v[48:51], v[214:217], v[158:161], v[48:51]
	s_waitcnt lgkmcnt(1)
	v_mfma_f32_16x16x32_bf16 v[174:177], v[218:221], v[158:161], v[174:177]
	ds_read_b128 v[158:161], v6 offset:9216
	v_mfma_f32_16x16x32_bf16 v[64:67], v[214:217], v[162:165], v[64:67]
	v_mfma_f32_16x16x32_bf16 v[170:173], v[218:221], v[162:165], v[170:173]
	ds_read_b128 v[162:165], v6 offset:11264
	v_mfma_f32_16x16x32_bf16 v[80:83], v[214:217], v[222:225], v[80:83]
	v_mfma_f32_16x16x32_bf16 v[32:35], v[218:221], v[222:225], v[32:35]
	ds_read_b128 v[222:225], v6 offset:13312
	s_waitcnt lgkmcnt(3)
	v_mfma_f32_16x16x32_bf16 v[88:91], v[166:169], v[226:229], v[88:91]
	v_mfma_f32_16x16x32_bf16 v[92:95], v[178:181], v[226:229], v[92:95]
	v_mfma_f32_16x16x32_bf16 v[96:99], v[214:217], v[226:229], v[96:99]
	v_mfma_f32_16x16x32_bf16 v[36:39], v[218:221], v[226:229], v[36:39]
	ds_read_b128 v[226:229], v6 offset:15360
	s_waitcnt lgkmcnt(3)
	v_mfma_f32_16x16x32_bf16 v[104:107], v[166:169], v[158:161], v[104:107]
	v_mfma_f32_16x16x32_bf16 v[108:111], v[178:181], v[158:161], v[108:111]
	v_mfma_f32_16x16x32_bf16 v[112:115], v[214:217], v[158:161], v[112:115]
	v_mfma_f32_16x16x32_bf16 v[52:55], v[218:221], v[158:161], v[52:55]
	s_waitcnt lgkmcnt(2)
	v_mfma_f32_16x16x32_bf16 v[116:119], v[166:169], v[162:165], v[116:119]
	v_mfma_f32_16x16x32_bf16 v[120:123], v[178:181], v[162:165], v[120:123]
	v_mfma_f32_16x16x32_bf16 v[124:127], v[214:217], v[162:165], v[124:127]
	v_mfma_f32_16x16x32_bf16 v[68:71], v[218:221], v[162:165], v[68:71]
	s_add_u32 s46, s16, s45
	s_addc_u32 s47, s17, 0
	s_add_u32 s48, s18, s45
	s_addc_u32 s49, s19, 0
	s_add_u32 s45, s45, 0x80
	s_cmp_lg_u32 s45, 0xf80
	s_waitcnt vmcnt(0)
	s_waitcnt lgkmcnt(0)
	s_barrier
	s_cbranch_scc1 .Lmy_rr_r2b
	v_mfma_f32_16x16x32_bf16 v[128:131], v[166:169], v[222:225], v[128:131]
	v_mfma_f32_16x16x32_bf16 v[100:103], v[166:169], v[226:229], v[100:103]
	v_mfma_f32_16x16x32_bf16 v[132:135], v[178:181], v[222:225], v[132:135]
	v_mfma_f32_16x16x32_bf16 v[140:143], v[178:181], v[226:229], v[140:143]
	v_mfma_f32_16x16x32_bf16 v[136:139], v[214:217], v[222:225], v[136:139]
	v_mfma_f32_16x16x32_bf16 v[150:153], v[214:217], v[226:229], v[150:153]
	v_mfma_f32_16x16x32_bf16 v[84:87], v[218:221], v[222:225], v[84:87]
	v_mfma_f32_16x16x32_bf16 v[154:157], v[218:221], v[226:229], v[154:157]
	s_nop 15
	s_nop 15
	v_lshl_add_u64 v[158:159], s[46:47], 0, v[0:1]
	s_mov_b32 s45, m0
	s_mov_b32 m0, s1
	s_nop 0
	global_load_lds_dwordx4 v[158:159], off
	s_mov_b32 m0, s45
	v_lshl_add_u64 v[158:159], s[48:49], 0, v[0:1]
	s_mov_b32 s45, m0
	s_mov_b32 m0, s30
	s_nop 0
	global_load_lds_dwordx4 v[158:159], off
	s_mov_b32 m0, s45
	v_lshl_add_u64 v[158:159], s[46:47], 0, v[2:3]
	s_mov_b32 s45, m0
	s_mov_b32 m0, s31
	s_nop 0
	global_load_lds_dwordx4 v[158:159], off
	s_mov_b32 m0, s45
	v_lshl_add_u64 v[158:159], s[48:49], 0, v[2:3]
	s_mov_b32 s45, m0
	s_mov_b32 m0, s34
	s_nop 0
	global_load_lds_dwordx4 v[158:159], off
	s_mov_b32 m0, s45
	v_lshl_add_u64 v[158:159], s[46:47], 0, v[4:5]
	s_mov_b32 s45, m0
	s_mov_b32 m0, s35
	s_nop 0
	global_load_lds_dwordx4 v[158:159], off
	s_mov_b32 m0, s45
	v_lshl_add_u64 v[158:159], s[48:49], 0, v[4:5]
	s_mov_b32 s45, m0
	s_mov_b32 m0, s36
	s_nop 0
	global_load_lds_dwordx4 v[158:159], off
	s_mov_b32 m0, s45
	v_lshl_add_u64 v[158:159], s[46:47], 0, v[146:147]
	s_mov_b32 s45, m0
	s_mov_b32 m0, s37
	s_nop 0
	global_load_lds_dwordx4 v[158:159], off
	s_mov_b32 m0, s45
	v_lshl_add_u64 v[158:159], s[48:49], 0, v[146:147]
	s_mov_b32 s45, m0
	s_mov_b32 m0, s38
	s_nop 0
	global_load_lds_dwordx4 v[158:159], off
	s_mov_b32 m0, s45
	ds_read_b128 v[158:161], v8
	ds_read_b128 v[162:165], v9
	ds_read_b128 v[166:169], v11
	ds_read_b128 v[214:217], v10
	ds_read_b128 v[178:181], v12
	ds_read_b128 v[218:221], v13
	ds_read_b128 v[222:225], v14
	ds_read_b128 v[226:229], v15
	s_waitcnt lgkmcnt(3)
	v_mfma_f32_16x16x32_bf16 v[40:43], v[158:161], v[178:181], v[40:43]
	v_mfma_f32_16x16x32_bf16 v[44:47], v[162:165], v[178:181], v[44:47]
	v_mfma_f32_16x16x32_bf16 v[48:51], v[166:169], v[178:181], v[48:51]
	v_mfma_f32_16x16x32_bf16 v[174:177], v[214:217], v[178:181], v[174:177]
	ds_read_b128 v[178:181], v16
	s_waitcnt lgkmcnt(3)
	v_mfma_f32_16x16x32_bf16 v[56:59], v[158:161], v[218:221], v[56:59]
	v_mfma_f32_16x16x32_bf16 v[60:63], v[162:165], v[218:221], v[60:63]
	v_mfma_f32_16x16x32_bf16 v[64:67], v[166:169], v[218:221], v[64:67]
	v_mfma_f32_16x16x32_bf16 v[170:173], v[214:217], v[218:221], v[170:173]
	ds_read_b128 v[218:221], v17
	s_waitcnt lgkmcnt(3)
	v_mfma_f32_16x16x32_bf16 v[72:75], v[158:161], v[222:225], v[72:75]
	v_mfma_f32_16x16x32_bf16 v[76:79], v[162:165], v[222:225], v[76:79]
	v_mfma_f32_16x16x32_bf16 v[80:83], v[166:169], v[222:225], v[80:83]
	v_mfma_f32_16x16x32_bf16 v[32:35], v[214:217], v[222:225], v[32:35]
	ds_read_b128 v[222:225], v18
	s_waitcnt lgkmcnt(3)
	v_mfma_f32_16x16x32_bf16 v[88:91], v[158:161], v[226:229], v[88:91]
	v_mfma_f32_16x16x32_bf16 v[92:95], v[162:165], v[226:229], v[92:95]
	v_mfma_f32_16x16x32_bf16 v[96:99], v[166:169], v[226:229], v[96:99]
	v_mfma_f32_16x16x32_bf16 v[36:39], v[214:217], v[226:229], v[36:39]
	ds_read_b128 v[226:229], v19
	s_waitcnt lgkmcnt(3)
	v_mfma_f32_16x16x32_bf16 v[104:107], v[158:161], v[178:181], v[104:107]
	v_mfma_f32_16x16x32_bf16 v[108:111], v[162:165], v[178:181], v[108:111]
	v_mfma_f32_16x16x32_bf16 v[112:115], v[166:169], v[178:181], v[112:115]
	v_mfma_f32_16x16x32_bf16 v[52:55], v[214:217], v[178:181], v[52:55]
	s_waitcnt lgkmcnt(2)
	v_mfma_f32_16x16x32_bf16 v[116:119], v[158:161], v[218:221], v[116:119]
	v_mfma_f32_16x16x32_bf16 v[120:123], v[162:165], v[218:221], v[120:123]
	v_mfma_f32_16x16x32_bf16 v[124:127], v[166:169], v[218:221], v[124:127]
	v_mfma_f32_16x16x32_bf16 v[68:71], v[214:217], v[218:221], v[68:71]
	s_waitcnt lgkmcnt(1)
	v_mfma_f32_16x16x32_bf16 v[132:135], v[162:165], v[222:225], v[132:135]
	v_mfma_f32_16x16x32_bf16 v[84:87], v[214:217], v[222:225], v[84:87]
	s_waitcnt lgkmcnt(0)
	v_mfma_f32_16x16x32_bf16 v[100:103], v[158:161], v[226:229], v[100:103]
	v_mfma_f32_16x16x32_bf16 v[150:153], v[166:169], v[226:229], v[150:153]
	v_mfma_f32_16x16x32_bf16 v[154:157], v[214:217], v[226:229], v[154:157]
	v_mfma_f32_16x16x32_bf16 v[128:131], v[158:161], v[222:225], v[128:131]
	v_mfma_f32_16x16x32_bf16 v[136:139], v[166:169], v[222:225], v[136:139]
	v_mfma_f32_16x16x32_bf16 v[140:143], v[162:165], v[226:229], v[140:143]
	ds_read_b128 v[158:161], v20
	ds_read_b128 v[162:165], v21
	ds_read_b128 v[166:169], v23
	ds_read_b128 v[214:217], v22
	ds_read_b128 v[178:181], v24
	ds_read_b128 v[218:221], v25
	ds_read_b128 v[222:225], v26
	ds_read_b128 v[226:229], v27
	s_waitcnt lgkmcnt(3)
	v_mfma_f32_16x16x32_bf16 v[40:43], v[158:161], v[178:181], v[40:43]
	v_mfma_f32_16x16x32_bf16 v[44:47], v[162:165], v[178:181], v[44:47]
	v_mfma_f32_16x16x32_bf16 v[48:51], v[166:169], v[178:181], v[48:51]
	v_mfma_f32_16x16x32_bf16 v[174:177], v[214:217], v[178:181], v[174:177]
	ds_read_b128 v[178:181], v28
	s_waitcnt lgkmcnt(3)
	v_mfma_f32_16x16x32_bf16 v[56:59], v[158:161], v[218:221], v[56:59]
	v_mfma_f32_16x16x32_bf16 v[60:63], v[162:165], v[218:221], v[60:63]
	v_mfma_f32_16x16x32_bf16 v[64:67], v[166:169], v[218:221], v[64:67]
	v_mfma_f32_16x16x32_bf16 v[170:173], v[214:217], v[218:221], v[170:173]
	ds_read_b128 v[218:221], v29
	s_waitcnt lgkmcnt(3)
	v_mfma_f32_16x16x32_bf16 v[72:75], v[158:161], v[222:225], v[72:75]
	v_mfma_f32_16x16x32_bf16 v[76:79], v[162:165], v[222:225], v[76:79]
	v_mfma_f32_16x16x32_bf16 v[80:83], v[166:169], v[222:225], v[80:83]
	v_mfma_f32_16x16x32_bf16 v[32:35], v[214:217], v[222:225], v[32:35]
	ds_read_b128 v[222:225], v30
	s_waitcnt lgkmcnt(3)
	v_mfma_f32_16x16x32_bf16 v[88:91], v[158:161], v[226:229], v[88:91]
	v_mfma_f32_16x16x32_bf16 v[92:95], v[162:165], v[226:229], v[92:95]
	v_mfma_f32_16x16x32_bf16 v[96:99], v[166:169], v[226:229], v[96:99]
	v_mfma_f32_16x16x32_bf16 v[36:39], v[214:217], v[226:229], v[36:39]
	ds_read_b128 v[226:229], v31
	s_waitcnt lgkmcnt(3)
	v_mfma_f32_16x16x32_bf16 v[104:107], v[158:161], v[178:181], v[104:107]
	v_mfma_f32_16x16x32_bf16 v[108:111], v[162:165], v[178:181], v[108:111]
	v_mfma_f32_16x16x32_bf16 v[112:115], v[166:169], v[178:181], v[112:115]
	v_mfma_f32_16x16x32_bf16 v[52:55], v[214:217], v[178:181], v[52:55]
	s_waitcnt lgkmcnt(2)
	v_mfma_f32_16x16x32_bf16 v[116:119], v[158:161], v[218:221], v[116:119]
	v_mfma_f32_16x16x32_bf16 v[120:123], v[162:165], v[218:221], v[120:123]
	v_mfma_f32_16x16x32_bf16 v[124:127], v[166:169], v[218:221], v[124:127]
	v_mfma_f32_16x16x32_bf16 v[68:71], v[214:217], v[218:221], v[68:71]
	s_waitcnt lgkmcnt(1)
	v_mfma_f32_16x16x32_bf16 v[132:135], v[162:165], v[222:225], v[132:135]
	v_mfma_f32_16x16x32_bf16 v[84:87], v[214:217], v[222:225], v[84:87]
	s_waitcnt lgkmcnt(0)
	v_mfma_f32_16x16x32_bf16 v[100:103], v[158:161], v[226:229], v[100:103]
	v_mfma_f32_16x16x32_bf16 v[150:153], v[166:169], v[226:229], v[150:153]
	v_mfma_f32_16x16x32_bf16 v[154:157], v[214:217], v[226:229], v[154:157]
	v_mfma_f32_16x16x32_bf16 v[128:131], v[158:161], v[222:225], v[128:131]
	v_mfma_f32_16x16x32_bf16 v[136:139], v[166:169], v[222:225], v[136:139]
	v_mfma_f32_16x16x32_bf16 v[140:143], v[162:165], v[226:229], v[140:143]
	s_add_u32 s16, s16, 0xf80
	s_addc_u32 s17, s17, 0
	s_add_u32 s18, s18, 0xf80
	s_waitcnt vmcnt(0)
	s_barrier
	s_addc_u32 s19, s19, 0
	v_lshl_add_u64 v[158:159], s[16:17], 0, v[0:1]
	s_mov_b32 s45, m0
	s_mov_b32 m0, s25
	s_nop 0
	global_load_lds_dwordx4 v[158:159], off
	s_mov_b32 m0, s45
	v_lshl_add_u64 v[158:159], s[18:19], 0, v[0:1]
	s_mov_b32 s25, m0
	s_mov_b32 m0, s24
	s_nop 0
	global_load_lds_dwordx4 v[158:159], off
	s_mov_b32 m0, s25
	v_lshl_add_u64 v[158:159], s[16:17], 0, v[2:3]
	s_mov_b32 s24, m0
	s_mov_b32 m0, s39
	s_nop 0
	global_load_lds_dwordx4 v[158:159], off
	s_mov_b32 m0, s24
	v_lshl_add_u64 v[158:159], s[18:19], 0, v[2:3]
	s_mov_b32 s24, m0
	s_mov_b32 m0, s40
	s_nop 0
	global_load_lds_dwordx4 v[158:159], off
	s_mov_b32 m0, s24
	v_lshl_add_u64 v[158:159], s[16:17], 0, v[4:5]
	s_mov_b32 s24, m0
	s_mov_b32 m0, s41
	s_nop 0
	global_load_lds_dwordx4 v[158:159], off
	s_mov_b32 m0, s24
	v_lshl_add_u64 v[158:159], s[18:19], 0, v[4:5]
	s_mov_b32 s24, m0
	s_mov_b32 m0, s42
	s_nop 0
	global_load_lds_dwordx4 v[158:159], off
	s_mov_b32 m0, s24
	v_lshl_add_u64 v[158:159], s[16:17], 0, v[146:147]
	s_mov_b32 s16, m0
	s_mov_b32 m0, s43
	s_nop 0
	global_load_lds_dwordx4 v[158:159], off
	s_mov_b32 m0, s16
	v_lshl_add_u64 v[158:159], s[18:19], 0, v[146:147]
	s_mov_b32 s16, m0
	s_mov_b32 m0, s44
	s_nop 0
	global_load_lds_dwordx4 v[158:159], off
	s_mov_b32 m0, s16
	ds_read_b128 v[158:161], v7 offset:32768
	ds_read_b128 v[162:165], v7 offset:34816
	ds_read_b128 v[166:169], v7 offset:36864
	ds_read_b128 v[214:217], v7 offset:38912
	ds_read_b128 v[178:181], v6
	ds_read_b128 v[218:221], v6 offset:2048
	ds_read_b128 v[222:225], v6 offset:4096
	ds_read_b128 v[226:229], v6 offset:6144
	s_waitcnt lgkmcnt(3)
	v_mfma_f32_16x16x32_bf16 v[40:43], v[158:161], v[178:181], v[40:43]
	v_mfma_f32_16x16x32_bf16 v[44:47], v[162:165], v[178:181], v[44:47]
	v_mfma_f32_16x16x32_bf16 v[48:51], v[166:169], v[178:181], v[48:51]
	v_mfma_f32_16x16x32_bf16 v[174:177], v[214:217], v[178:181], v[174:177]
	ds_read_b128 v[178:181], v6 offset:8192
	s_waitcnt lgkmcnt(3)
	v_mfma_f32_16x16x32_bf16 v[56:59], v[158:161], v[218:221], v[56:59]
	v_mfma_f32_16x16x32_bf16 v[60:63], v[162:165], v[218:221], v[60:63]
	v_mfma_f32_16x16x32_bf16 v[64:67], v[166:169], v[218:221], v[64:67]
	v_mfma_f32_16x16x32_bf16 v[170:173], v[214:217], v[218:221], v[170:173]
	ds_read_b128 v[218:221], v6 offset:10240
	s_waitcnt lgkmcnt(3)
	v_mfma_f32_16x16x32_bf16 v[72:75], v[158:161], v[222:225], v[72:75]
	v_mfma_f32_16x16x32_bf16 v[76:79], v[162:165], v[222:225], v[76:79]
	v_mfma_f32_16x16x32_bf16 v[80:83], v[166:169], v[222:225], v[80:83]
	v_mfma_f32_16x16x32_bf16 v[32:35], v[214:217], v[222:225], v[32:35]
	ds_read_b128 v[222:225], v6 offset:12288
	s_waitcnt lgkmcnt(3)
	v_mfma_f32_16x16x32_bf16 v[88:91], v[158:161], v[226:229], v[88:91]
	v_mfma_f32_16x16x32_bf16 v[92:95], v[162:165], v[226:229], v[92:95]
	v_mfma_f32_16x16x32_bf16 v[96:99], v[166:169], v[226:229], v[96:99]
	v_mfma_f32_16x16x32_bf16 v[36:39], v[214:217], v[226:229], v[36:39]
	ds_read_b128 v[226:229], v6 offset:14336
	s_waitcnt lgkmcnt(3)
	v_mfma_f32_16x16x32_bf16 v[104:107], v[158:161], v[178:181], v[104:107]
	v_mfma_f32_16x16x32_bf16 v[108:111], v[162:165], v[178:181], v[108:111]
	v_mfma_f32_16x16x32_bf16 v[112:115], v[166:169], v[178:181], v[112:115]
	v_mfma_f32_16x16x32_bf16 v[52:55], v[214:217], v[178:181], v[52:55]
	s_waitcnt lgkmcnt(2)
	v_mfma_f32_16x16x32_bf16 v[116:119], v[158:161], v[218:221], v[116:119]
	v_mfma_f32_16x16x32_bf16 v[120:123], v[162:165], v[218:221], v[120:123]
	v_mfma_f32_16x16x32_bf16 v[124:127], v[166:169], v[218:221], v[124:127]
	v_mfma_f32_16x16x32_bf16 v[68:71], v[214:217], v[218:221], v[68:71]
	s_waitcnt lgkmcnt(1)
	v_mfma_f32_16x16x32_bf16 v[132:135], v[162:165], v[222:225], v[132:135]
	v_mfma_f32_16x16x32_bf16 v[84:87], v[214:217], v[222:225], v[84:87]
	s_waitcnt lgkmcnt(0)
	v_mfma_f32_16x16x32_bf16 v[100:103], v[158:161], v[226:229], v[100:103]
	v_mfma_f32_16x16x32_bf16 v[150:153], v[166:169], v[226:229], v[150:153]
	v_mfma_f32_16x16x32_bf16 v[154:157], v[214:217], v[226:229], v[154:157]
	v_mfma_f32_16x16x32_bf16 v[128:131], v[158:161], v[222:225], v[128:131]
	v_mfma_f32_16x16x32_bf16 v[136:139], v[166:169], v[222:225], v[136:139]
	v_mfma_f32_16x16x32_bf16 v[140:143], v[162:165], v[226:229], v[140:143]
	ds_read_b128 v[158:161], v7 offset:33792
	ds_read_b128 v[162:165], v7 offset:35840
	ds_read_b128 v[166:169], v7 offset:37888
	ds_read_b128 v[214:217], v7 offset:39936
	ds_read_b128 v[178:181], v6 offset:1024
	ds_read_b128 v[218:221], v6 offset:3072
	ds_read_b128 v[222:225], v6 offset:5120
	ds_read_b128 v[226:229], v6 offset:7168
	s_waitcnt lgkmcnt(3)
	v_mfma_f32_16x16x32_bf16 v[40:43], v[158:161], v[178:181], v[40:43]
	v_mfma_f32_16x16x32_bf16 v[44:47], v[162:165], v[178:181], v[44:47]
	v_mfma_f32_16x16x32_bf16 v[48:51], v[166:169], v[178:181], v[48:51]
	v_mfma_f32_16x16x32_bf16 v[174:177], v[214:217], v[178:181], v[174:177]
	ds_read_b128 v[178:181], v6 offset:9216
	s_waitcnt lgkmcnt(3)
	v_mfma_f32_16x16x32_bf16 v[56:59], v[158:161], v[218:221], v[56:59]
	v_mfma_f32_16x16x32_bf16 v[60:63], v[162:165], v[218:221], v[60:63]
	v_mfma_f32_16x16x32_bf16 v[64:67], v[166:169], v[218:221], v[64:67]
	v_mfma_f32_16x16x32_bf16 v[170:173], v[214:217], v[218:221], v[170:173]
	ds_read_b128 v[218:221], v6 offset:11264
	s_waitcnt lgkmcnt(3)
	v_mfma_f32_16x16x32_bf16 v[72:75], v[158:161], v[222:225], v[72:75]
	v_mfma_f32_16x16x32_bf16 v[76:79], v[162:165], v[222:225], v[76:79]
	v_mfma_f32_16x16x32_bf16 v[80:83], v[166:169], v[222:225], v[80:83]
	v_mfma_f32_16x16x32_bf16 v[32:35], v[214:217], v[222:225], v[32:35]
	ds_read_b128 v[222:225], v6 offset:13312
	s_waitcnt lgkmcnt(3)
	v_mfma_f32_16x16x32_bf16 v[88:91], v[158:161], v[226:229], v[88:91]
	v_mfma_f32_16x16x32_bf16 v[92:95], v[162:165], v[226:229], v[92:95]
	v_mfma_f32_16x16x32_bf16 v[96:99], v[166:169], v[226:229], v[96:99]
	v_mfma_f32_16x16x32_bf16 v[36:39], v[214:217], v[226:229], v[36:39]
	ds_read_b128 v[226:229], v6 offset:15360
	s_waitcnt lgkmcnt(3)
	v_mfma_f32_16x16x32_bf16 v[104:107], v[158:161], v[178:181], v[104:107]
	v_mfma_f32_16x16x32_bf16 v[108:111], v[162:165], v[178:181], v[108:111]
	v_mfma_f32_16x16x32_bf16 v[112:115], v[166:169], v[178:181], v[112:115]
	v_mfma_f32_16x16x32_bf16 v[52:55], v[214:217], v[178:181], v[52:55]
	s_waitcnt lgkmcnt(2)
	v_mfma_f32_16x16x32_bf16 v[116:119], v[158:161], v[218:221], v[116:119]
	v_mfma_f32_16x16x32_bf16 v[120:123], v[162:165], v[218:221], v[120:123]
	v_mfma_f32_16x16x32_bf16 v[124:127], v[166:169], v[218:221], v[124:127]
	v_mfma_f32_16x16x32_bf16 v[68:71], v[214:217], v[218:221], v[68:71]
	s_waitcnt lgkmcnt(1)
	v_mfma_f32_16x16x32_bf16 v[132:135], v[162:165], v[222:225], v[132:135]
	v_mfma_f32_16x16x32_bf16 v[84:87], v[214:217], v[222:225], v[84:87]
	s_waitcnt lgkmcnt(0)
	v_mfma_f32_16x16x32_bf16 v[100:103], v[158:161], v[226:229], v[100:103]
	v_mfma_f32_16x16x32_bf16 v[150:153], v[166:169], v[226:229], v[150:153]
	v_mfma_f32_16x16x32_bf16 v[154:157], v[214:217], v[226:229], v[154:157]
	v_mfma_f32_16x16x32_bf16 v[128:131], v[158:161], v[222:225], v[128:131]
	v_mfma_f32_16x16x32_bf16 v[136:139], v[166:169], v[222:225], v[136:139]
	v_mfma_f32_16x16x32_bf16 v[140:143], v[162:165], v[226:229], v[140:143]
	s_waitcnt vmcnt(0)
	s_barrier
	v_lshl_add_u64 v[6:7], s[20:21], 0, v[0:1]
	s_mov_b32 s16, m0
	s_mov_b32 m0, s1
	s_nop 0
	global_load_lds_dwordx4 v[6:7], off
	s_mov_b32 m0, s16
	v_lshl_add_u64 v[0:1], s[22:23], 0, v[0:1]
	s_mov_b32 s1, m0
	s_mov_b32 m0, s30
	s_nop 0
	global_load_lds_dwordx4 v[0:1], off
	s_mov_b32 m0, s1
	v_lshl_add_u64 v[0:1], s[20:21], 0, v[2:3]
	s_mov_b32 s1, m0
	s_mov_b32 m0, s31
	s_nop 0
	global_load_lds_dwordx4 v[0:1], off
	s_mov_b32 m0, s1
	v_lshl_add_u64 v[0:1], s[22:23], 0, v[2:3]
	s_mov_b32 s1, m0
	s_mov_b32 m0, s34
	s_nop 0
	global_load_lds_dwordx4 v[0:1], off
	s_mov_b32 m0, s1
	v_lshl_add_u64 v[0:1], s[20:21], 0, v[4:5]
	s_mov_b32 s1, m0
	s_mov_b32 m0, s35
	s_nop 0
	global_load_lds_dwordx4 v[0:1], off
	s_mov_b32 m0, s1
	v_lshl_add_u64 v[0:1], s[22:23], 0, v[4:5]
	s_mov_b32 s1, m0
	s_mov_b32 m0, s36
	s_nop 0
	global_load_lds_dwordx4 v[0:1], off
	s_mov_b32 m0, s1
	v_lshl_add_u64 v[0:1], s[20:21], 0, v[146:147]
	s_mov_b32 s1, m0
	s_mov_b32 m0, s37
	s_nop 0
	global_load_lds_dwordx4 v[0:1], off
	s_mov_b32 m0, s1
	v_lshl_add_u64 v[0:1], s[22:23], 0, v[146:147]
	s_mov_b32 s1, m0
	s_mov_b32 m0, s38
	s_nop 0
	global_load_lds_dwordx4 v[0:1], off
	s_mov_b32 m0, s1
	ds_read_b128 v[0:3], v8
	ds_read_b128 v[4:7], v9
	ds_read_b128 v[158:161], v11
	ds_read_b128 v[8:11], v10
	ds_read_b128 v[162:165], v12
	ds_read_b128 v[166:169], v13
	ds_read_b128 v[178:181], v14
	ds_read_b128 v[12:15], v15
	s_waitcnt lgkmcnt(3)
	v_mfma_f32_16x16x32_bf16 v[40:43], v[0:3], v[162:165], v[40:43]
	v_mfma_f32_16x16x32_bf16 v[44:47], v[4:7], v[162:165], v[44:47]
	v_mfma_f32_16x16x32_bf16 v[48:51], v[158:161], v[162:165], v[48:51]
	v_mfma_f32_16x16x32_bf16 v[162:165], v[8:11], v[162:165], v[174:177]
	s_nop 2
	ds_read_b128 v[174:177], v16
	s_waitcnt lgkmcnt(3)
	v_mfma_f32_16x16x32_bf16 v[56:59], v[0:3], v[166:169], v[56:59]
	v_mfma_f32_16x16x32_bf16 v[60:63], v[4:7], v[166:169], v[60:63]
	v_mfma_f32_16x16x32_bf16 v[64:67], v[158:161], v[166:169], v[64:67]
	v_mfma_f32_16x16x32_bf16 v[166:169], v[8:11], v[166:169], v[170:173]
	s_nop 2
	ds_read_b128 v[170:173], v17
	s_waitcnt lgkmcnt(3)
	v_mfma_f32_16x16x32_bf16 v[72:75], v[0:3], v[178:181], v[72:75]
	v_mfma_f32_16x16x32_bf16 v[76:79], v[4:7], v[178:181], v[76:79]
	v_mfma_f32_16x16x32_bf16 v[80:83], v[158:161], v[178:181], v[80:83]
	v_mfma_f32_16x16x32_bf16 v[32:35], v[8:11], v[178:181], v[32:35]
	ds_read_b128 v[178:181], v18
	s_waitcnt lgkmcnt(3)
	v_mfma_f32_16x16x32_bf16 v[214:217], v[0:3], v[12:15], v[88:91]
	v_mfma_f32_16x16x32_bf16 v[218:221], v[4:7], v[12:15], v[92:95]
	v_mfma_f32_16x16x32_bf16 v[222:225], v[158:161], v[12:15], v[96:99]
	v_mfma_f32_16x16x32_bf16 v[12:15], v[8:11], v[12:15], v[36:39]
	ds_read_b128 v[16:19], v19
	s_waitcnt lgkmcnt(3)
	v_mfma_f32_16x16x32_bf16 v[36:39], v[0:3], v[174:177], v[104:107]
	v_mfma_f32_16x16x32_bf16 v[226:229], v[4:7], v[174:177], v[108:111]
	v_mfma_f32_16x16x32_bf16 v[112:115], v[158:161], v[174:177], v[112:115]
	s_waitcnt lgkmcnt(2)
	v_mfma_f32_16x16x32_bf16 v[116:119], v[0:3], v[170:173], v[116:119]
	v_mfma_f32_16x16x32_bf16 v[120:123], v[4:7], v[170:173], v[120:123]
	v_mfma_f32_16x16x32_bf16 v[124:127], v[158:161], v[170:173], v[124:127]
	s_waitcnt lgkmcnt(1)
	v_mfma_f32_16x16x32_bf16 v[128:131], v[0:3], v[178:181], v[128:131]
	v_mfma_f32_16x16x32_bf16 v[132:135], v[4:7], v[178:181], v[132:135]
	s_waitcnt lgkmcnt(0)
	v_mfma_f32_16x16x32_bf16 v[0:3], v[0:3], v[16:19], v[100:103]
	v_mfma_f32_16x16x32_bf16 v[4:7], v[4:7], v[16:19], v[140:143]
	v_mfma_f32_16x16x32_bf16 v[140:143], v[158:161], v[16:19], v[150:153]
	v_mfma_f32_16x16x32_bf16 v[150:153], v[8:11], v[16:19], v[154:157]
	v_mfma_f32_16x16x32_bf16 v[174:177], v[8:11], v[174:177], v[52:55]
	v_mfma_f32_16x16x32_bf16 v[170:173], v[8:11], v[170:173], v[68:71]
	v_mfma_f32_16x16x32_bf16 v[136:139], v[158:161], v[178:181], v[136:139]
	v_mfma_f32_16x16x32_bf16 v[178:181], v[8:11], v[178:181], v[84:87]
	ds_read_b128 v[8:11], v20
	ds_read_b128 v[154:157], v21
	ds_read_b128 v[158:161], v23
	ds_read_b128 v[230:233], v22
	ds_read_b128 v[16:19], v24
	ds_read_b128 v[20:23], v25
	ds_read_b128 v[52:55], v26
	ds_read_b128 v[24:27], v27
	s_waitcnt lgkmcnt(3)
	v_mfma_f32_16x16x32_bf16 v[234:237], v[8:11], v[16:19], v[40:43]
	v_mfma_f32_16x16x32_bf16 v[238:241], v[154:157], v[16:19], v[44:47]
	v_mfma_f32_16x16x32_bf16 v[242:245], v[158:161], v[16:19], v[48:51]
	v_mfma_f32_16x16x32_bf16 v[162:165], v[230:233], v[16:19], v[162:165]
	ds_read_b128 v[16:19], v28
	s_waitcnt lgkmcnt(3)
	v_mfma_f32_16x16x32_bf16 v[108:111], v[8:11], v[20:23], v[56:59]
	v_mfma_f32_16x16x32_bf16 v[104:107], v[154:157], v[20:23], v[60:63]
	v_mfma_f32_16x16x32_bf16 v[100:103], v[158:161], v[20:23], v[64:67]
	v_mfma_f32_16x16x32_bf16 v[96:99], v[230:233], v[20:23], v[166:169]
	ds_read_b128 v[20:23], v29
	s_waitcnt lgkmcnt(3)
	v_mfma_f32_16x16x32_bf16 v[92:95], v[8:11], v[52:55], v[72:75]
	v_mfma_f32_16x16x32_bf16 v[88:91], v[154:157], v[52:55], v[76:79]
	v_mfma_f32_16x16x32_bf16 v[84:87], v[158:161], v[52:55], v[80:83]
	v_mfma_f32_16x16x32_bf16 v[80:83], v[230:233], v[52:55], v[32:35]
	ds_read_b128 v[166:169], v30
	s_waitcnt lgkmcnt(3)
	v_mfma_f32_16x16x32_bf16 v[76:79], v[8:11], v[24:27], v[214:217]
	v_mfma_f32_16x16x32_bf16 v[72:75], v[154:157], v[24:27], v[218:221]
	v_mfma_f32_16x16x32_bf16 v[68:71], v[158:161], v[24:27], v[222:225]
	v_mfma_f32_16x16x32_bf16 v[64:67], v[230:233], v[24:27], v[12:15]
	ds_read_b128 v[214:217], v31
	s_waitcnt lgkmcnt(3)
	v_mfma_f32_16x16x32_bf16 v[60:63], v[8:11], v[16:19], v[36:39]
	v_mfma_f32_16x16x32_bf16 v[56:59], v[154:157], v[16:19], v[226:229]
	v_mfma_f32_16x16x32_bf16 v[52:55], v[158:161], v[16:19], v[112:115]
	v_mfma_f32_16x16x32_bf16 v[48:51], v[230:233], v[16:19], v[174:177]
	s_waitcnt lgkmcnt(2)
	v_mfma_f32_16x16x32_bf16 v[44:47], v[8:11], v[20:23], v[116:119]
	v_mfma_f32_16x16x32_bf16 v[40:43], v[154:157], v[20:23], v[120:123]
	v_mfma_f32_16x16x32_bf16 v[36:39], v[158:161], v[20:23], v[124:127]
	v_mfma_f32_16x16x32_bf16 v[32:35], v[230:233], v[20:23], v[170:173]
	s_waitcnt lgkmcnt(1)
	v_mfma_f32_16x16x32_bf16 v[28:31], v[8:11], v[166:169], v[128:131]
	v_mfma_f32_16x16x32_bf16 v[24:27], v[154:157], v[166:169], v[132:135]
	v_mfma_f32_16x16x32_bf16 v[20:23], v[158:161], v[166:169], v[136:139]
	v_mfma_f32_16x16x32_bf16 v[16:19], v[230:233], v[166:169], v[178:181]
	s_waitcnt lgkmcnt(0)
	v_mfma_f32_16x16x32_bf16 v[12:15], v[8:11], v[214:217], v[0:3]
	v_mfma_f32_16x16x32_bf16 v[8:11], v[154:157], v[214:217], v[4:7]
	v_mfma_f32_16x16x32_bf16 v[4:7], v[158:161], v[214:217], v[140:143]
	v_mfma_f32_16x16x32_bf16 v[0:3], v[230:233], v[214:217], v[150:153]
	v_mov_b32_e32 v145, v184
	s_waitcnt vmcnt(0)
	s_barrier
	s_lshl_b32 s18, s0, 8
	s_lshl_b32 s16, s14, 8
	v_and_b32_e32 v151, 15, v145
	v_ashrrev_i32_e32 v112, 1, v145
	v_and_b32_e32 v153, 0xffffff80, v112
	v_or_b32_e32 v112, s18, v151
	v_add_u32_e32 v112, v112, v153
	v_ashrrev_i32_e32 v113, 31, v112
	v_lshlrev_b64 v[112:113], 13, v[112:113]
	v_bfe_u32 v150, v145, 6, 2
	v_lshl_add_u64 v[112:113], s[2:3], 0, v[112:113]
	s_ashr_i32 s17, s16, 31
	v_bfe_u32 v152, v145, 4, 2
	v_lshl_add_u64 v[112:113], s[16:17], 2, v[112:113]
	v_lshlrev_b32_e32 v146, 8, v150
	v_lshl_add_u64 v[112:113], v[112:113], 0, v[146:147]
	v_lshlrev_b32_e32 v146, 4, v152
	v_lshl_add_u64 v[154:155], v[112:113], 0, v[146:147]
	global_load_dwordx4 v[120:123], v[154:155], off offset:192
	global_load_dwordx4 v[128:131], v[154:155], off offset:128
	global_load_dwordx4 v[136:139], v[154:155], off offset:64
	global_load_dwordx4 v[140:143], v[154:155], off
	v_add_co_u32_e32 v112, vcc, s66, v154
	v_lshlrev_b32_e32 v158, 2, v152
	s_nop 0
	v_addc_co_u32_e32 v113, vcc, 0, v155, vcc
	global_load_dwordx4 v[132:135], v[112:113], off
	global_load_dwordx4 v[124:127], v[112:113], off offset:64
	global_load_dwordx4 v[116:119], v[112:113], off offset:128
	v_cmp_lt_i32_e32 vcc, v188, v186
	global_load_dwordx4 v[112:115], v[112:113], off offset:192
	v_cmp_eq_u32_e64 s[0:1], 0, v152
	v_cndmask_b32_e32 v146, v185, v188, vcc
	v_cmp_lt_i32_e32 vcc, v187, v186
	v_lshlrev_b32_e32 v149, 2, v146
	v_lshlrev_b32_e32 v157, 6, v150
	v_cndmask_b32_e32 v156, v185, v187, vcc
	v_lshlrev_b32_e32 v146, 2, v156
	v_or_b32_e32 v156, v153, v151
	v_add_u32_e32 v152, s18, v156
	v_ashrrev_i32_e32 v153, 31, v152
	v_lshl_or_b32 v182, v150, 10, v204
	v_or3_b32 v150, v157, s16, v158
	v_lshlrev_b64 v[158:159], 13, v[152:153]
	v_ashrrev_i32_e32 v151, 31, v150
	v_lshlrev_b64 v[160:161], 12, v[152:153]
	v_lshl_add_u64 v[158:159], s[2:3], 0, v[158:159]
	v_lshl_add_u64 v[160:161], s[4:5], 0, v[160:161]
	v_lshl_add_u64 v[166:167], v[150:151], 2, v[158:159]
	v_lshl_add_u64 v[168:169], v[150:151], 1, v[160:161]
	s_waitcnt vmcnt(7)
	v_pk_add_f32 v[158:159], v[162:163], v[120:121]
	s_waitcnt vmcnt(6)
	v_pk_add_f32 v[120:121], v[242:243], v[128:129]
	s_waitcnt vmcnt(5)
	v_pk_add_f32 v[128:129], v[238:239], v[136:137]
	s_waitcnt vmcnt(4)
	v_pk_add_f32 v[136:137], v[234:235], v[140:141]
	v_pk_add_f32 v[160:161], v[164:165], v[122:123]
	v_pk_add_f32 v[122:123], v[244:245], v[130:131]
	v_pk_add_f32 v[130:131], v[240:241], v[138:139]
	v_pk_add_f32 v[138:139], v[236:237], v[142:143]
	v_pk_mul_f32 v[172:173], v[128:129], v[128:129]
	v_pk_mul_f32 v[178:179], v[136:137], v[136:137]
	v_pk_mul_f32 v[162:163], v[120:121], v[120:121]
	v_pk_mul_f32 v[174:175], v[130:131], v[130:131]
	v_cvt_pk_bf16_f32 v176, v136, v137
	v_pk_mul_f32 v[180:181], v[138:139], v[138:139]
	global_store_dwordx4 v[166:167], v[136:139], off
	v_add_f32_e32 v153, v172, v173
	v_add_f32_e32 v157, v178, v179
	v_pk_mul_f32 v[136:137], v[158:159], v[158:159]
	v_pk_mul_f32 v[164:165], v[122:123], v[122:123]
	v_cvt_pk_bf16_f32 v177, v138, v139
	v_pk_mul_f32 v[138:139], v[160:161], v[160:161]
	v_add_f32_e32 v162, v162, v163
	v_add_f32_e32 v136, v136, v137
	v_add_f32_e32 v137, v174, v153
	v_add_f32_e32 v153, v180, v157
	v_add_f32_e32 v157, v164, v162
	v_add_f32_e32 v136, v138, v136
	v_add_f32_e32 v137, v175, v137
	v_add_f32_e32 v138, v181, v153
	v_add_f32_e32 v153, v165, v157
	v_add_f32_e32 v137, v138, v137
	v_add_f32_e32 v137, v137, v153
	v_add_f32_e32 v136, v139, v136
	v_add_f32_e32 v136, v137, v136
	ds_bpermute_b32 v137, v149, v136
	v_cvt_pk_bf16_f32 v170, v128, v129
	v_cvt_pk_bf16_f32 v171, v130, v131
	v_cvt_pk_bf16_f32 v142, v120, v121
	global_store_dwordx2 v[168:169], v[176:177], off
	global_store_dwordx4 v[166:167], v[128:131], off offset:64
	global_store_dwordx2 v[168:169], v[170:171], off offset:32
	global_store_dwordx4 v[166:167], v[120:123], off offset:128
	v_cvt_pk_bf16_f32 v140, v158, v159
	v_cvt_pk_bf16_f32 v141, v160, v161
	s_waitcnt lgkmcnt(0)
	v_add_f32_e32 v120, v136, v137
	ds_bpermute_b32 v121, v146, v120
	v_cvt_pk_bf16_f32 v143, v122, v123
	v_lshl_add_u32 v153, v156, 2, v182
	global_store_dwordx2 v[168:169], v[142:143], off offset:64
	global_store_dwordx4 v[166:167], v[158:161], off offset:192
	global_store_dwordx2 v[168:169], v[140:141], off offset:96
	s_and_saveexec_b64 s[16:17], s[0:1]
	s_cbranch_execz .LBB0_156
	s_waitcnt lgkmcnt(0)
	v_add_f32_e32 v120, v120, v121
	ds_write_b32 v153, v120

.LBB0_252:
	s_mul_i32 s16, s19, 0x300000
	s_mul_hi_i32 s17, s19, 0x300000
	s_add_u32 s16, s22, s16
	s_addc_u32 s17, s23, s17
	s_mul_hi_i32 s19, s18, 0x300000
	s_mul_i32 s18, s18, 0x300000
	s_add_u32 s18, s24, s18
	s_addc_u32 s19, s25, s19
	s_add_u32 s44, s0, 0x80
	v_and_b32_e32 v8, 48, v7
	v_lshlrev_b32_e32 v9, 6, v7
	v_lshlrev_b32_e32 v7, 2, v7
	s_addc_u32 s45, s1, 0
	v_and_b32_e32 v10, 0x3c0, v9
	v_and_b32_e32 v149, 32, v7
	s_add_u32 s46, s14, 0x80
	v_or_b32_e32 v145, v10, v8
	v_bitop3_b32 v12, v10, v149, v8 bitop3:0x36
	s_waitcnt vmcnt(0)
	s_barrier
	v_lshlrev_b32_e32 v8, 13, v6
	s_addc_u32 s47, s15, 0
	s_add_i32 s38, s27, 0x10000
	v_lshl_add_u64 v[6:7], s[44:45], 0, v[0:1]
	s_mov_b32 s39, m0
	s_mov_b32 m0, s38
	s_nop 0
	global_load_lds_dwordx4 v[6:7], off
	s_mov_b32 m0, s39
	s_add_i32 s37, s27, 0x18000
	v_lshl_add_u64 v[6:7], s[46:47], 0, v[0:1]
	s_mov_b32 s39, m0
	s_mov_b32 m0, s37
	s_nop 0
	global_load_lds_dwordx4 v[6:7], off
	s_mov_b32 m0, s39
	v_lshl_add_u64 v[6:7], s[44:45], 0, v[2:3]
	s_add_i32 s39, s27, 0x12000
	s_mov_b32 s40, m0
	s_mov_b32 m0, s39
	s_nop 0
	global_load_lds_dwordx4 v[6:7], off
	s_mov_b32 m0, s40
	v_lshl_add_u64 v[6:7], s[46:47], 0, v[2:3]
	s_add_i32 s40, s27, 0x1a000
	s_mov_b32 s41, m0
	s_mov_b32 m0, s40
	s_nop 0
	global_load_lds_dwordx4 v[6:7], off
	s_mov_b32 m0, s41
	v_lshl_add_u64 v[6:7], s[44:45], 0, v[4:5]
	s_add_i32 s41, s27, 0x14000
	s_mov_b32 s42, m0
	s_mov_b32 m0, s41
	s_nop 0
	global_load_lds_dwordx4 v[6:7], off
	s_mov_b32 m0, s42
	v_lshl_add_u64 v[6:7], s[46:47], 0, v[4:5]
	s_add_i32 s42, s27, 0x1c000
	s_mov_b32 s43, m0
	s_mov_b32 m0, s42
	s_nop 0
	global_load_lds_dwordx4 v[6:7], off
	s_mov_b32 m0, s43
	v_lshl_add_u64 v[6:7], s[44:45], 0, v[146:147]
	s_add_i32 s43, s27, 0x16000
	s_mov_b32 s44, m0
	s_mov_b32 m0, s43
	s_nop 0
	global_load_lds_dwordx4 v[6:7], off
	s_mov_b32 m0, s44
	v_lshl_add_u64 v[6:7], s[46:47], 0, v[146:147]
	s_add_i32 s44, s27, 0x1e000
	s_mov_b32 s45, m0
	s_mov_b32 m0, s44
	s_nop 0
	global_load_lds_dwordx4 v[6:7], off
	s_mov_b32 m0, s45
	v_and_b32_e32 v182, 0xffffc000, v9
	v_or_b32_e32 v183, 0x800, v182
	v_or_b32_e32 v189, 0x1000, v182
	v_or_b32_e32 v199, 0x1800, v182
	v_or_b32_e32 v200, 0x2000, v182
	v_or_b32_e32 v201, 0x2800, v182
	v_or_b32_e32 v203, 0x3000, v182
	v_or_b32_e32 v206, 0x3800, v182
	s_movk_i32 s45, 0x6000
	v_and_or_b32 v7, v8, s45, v12
	ds_read_b128 v[8:11], v7 offset:32768
	v_or_b32_e32 v6, v12, v182
	ds_read_b128 v[12:15], v7 offset:34816
	ds_read_b128 v[16:19], v7 offset:36864
	ds_read_b128 v[24:27], v7 offset:38912
	ds_read_b128 v[20:23], v6
	ds_read_b128 v[28:31], v6 offset:2048
	ds_read_b128 v[32:35], v6 offset:4096
	ds_read_b128 v[36:39], v6 offset:6144
	s_waitcnt lgkmcnt(3)
	v_mfma_f32_16x16x32_bf16 v[40:43], v[8:11], v[20:23], 0
	v_mfma_f32_16x16x32_bf16 v[44:47], v[12:15], v[20:23], 0
	v_mfma_f32_16x16x32_bf16 v[48:51], v[16:19], v[20:23], 0
	v_mfma_f32_16x16x32_bf16 v[20:23], v[24:27], v[20:23], 0
	ds_read_b128 v[52:55], v6 offset:8192
	s_waitcnt lgkmcnt(3)
	v_mfma_f32_16x16x32_bf16 v[56:59], v[8:11], v[28:31], 0
	v_mfma_f32_16x16x32_bf16 v[60:63], v[12:15], v[28:31], 0
	v_mfma_f32_16x16x32_bf16 v[64:67], v[16:19], v[28:31], 0
	v_mfma_f32_16x16x32_bf16 v[28:31], v[24:27], v[28:31], 0
	ds_read_b128 v[68:71], v6 offset:10240
	s_waitcnt lgkmcnt(3)
	v_mfma_f32_16x16x32_bf16 v[72:75], v[8:11], v[32:35], 0
	v_mfma_f32_16x16x32_bf16 v[76:79], v[12:15], v[32:35], 0
	v_mfma_f32_16x16x32_bf16 v[80:83], v[16:19], v[32:35], 0
	v_mfma_f32_16x16x32_bf16 v[32:35], v[24:27], v[32:35], 0
	ds_read_b128 v[84:87], v6 offset:12288
	s_waitcnt lgkmcnt(3)
	v_mfma_f32_16x16x32_bf16 v[88:91], v[8:11], v[36:39], 0
	v_mfma_f32_16x16x32_bf16 v[92:95], v[12:15], v[36:39], 0
	v_mfma_f32_16x16x32_bf16 v[96:99], v[16:19], v[36:39], 0
	v_mfma_f32_16x16x32_bf16 v[36:39], v[24:27], v[36:39], 0
	ds_read_b128 v[100:103], v6 offset:14336
	s_waitcnt lgkmcnt(3)
	v_mfma_f32_16x16x32_bf16 v[104:107], v[8:11], v[52:55], 0
	v_mfma_f32_16x16x32_bf16 v[108:111], v[12:15], v[52:55], 0
	v_mfma_f32_16x16x32_bf16 v[112:115], v[16:19], v[52:55], 0
	v_mfma_f32_16x16x32_bf16 v[52:55], v[24:27], v[52:55], 0
	s_waitcnt lgkmcnt(2)
	v_mfma_f32_16x16x32_bf16 v[116:119], v[8:11], v[68:71], 0
	v_mfma_f32_16x16x32_bf16 v[120:123], v[12:15], v[68:71], 0
	v_mfma_f32_16x16x32_bf16 v[124:127], v[16:19], v[68:71], 0
	v_mfma_f32_16x16x32_bf16 v[68:71], v[24:27], v[68:71], 0
	s_waitcnt lgkmcnt(1)
	v_mfma_f32_16x16x32_bf16 v[128:131], v[8:11], v[84:87], 0
	v_mfma_f32_16x16x32_bf16 v[132:135], v[12:15], v[84:87], 0
	v_mfma_f32_16x16x32_bf16 v[136:139], v[16:19], v[84:87], 0
	v_mfma_f32_16x16x32_bf16 v[84:87], v[24:27], v[84:87], 0
	s_waitcnt lgkmcnt(0)
	v_mfma_f32_16x16x32_bf16 v[8:11], v[8:11], v[100:103], 0
	v_mfma_f32_16x16x32_bf16 v[12:15], v[12:15], v[100:103], 0
	v_mfma_f32_16x16x32_bf16 v[16:19], v[16:19], v[100:103], 0
	v_mfma_f32_16x16x32_bf16 v[24:27], v[24:27], v[100:103], 0
	ds_read_b128 v[100:103], v7 offset:33792
	ds_read_b128 v[140:143], v7 offset:35840
	ds_read_b128 v[150:153], v7 offset:37888
	ds_read_b128 v[158:161], v7 offset:39936
	ds_read_b128 v[154:157], v6 offset:1024
	ds_read_b128 v[162:165], v6 offset:3072
	ds_read_b128 v[166:169], v6 offset:5120
	ds_read_b128 v[170:173], v6 offset:7168
	s_waitcnt lgkmcnt(3)
	v_mfma_f32_16x16x32_bf16 v[40:43], v[100:103], v[154:157], v[40:43]
	v_mfma_f32_16x16x32_bf16 v[44:47], v[140:143], v[154:157], v[44:47]
	v_mfma_f32_16x16x32_bf16 v[48:51], v[150:153], v[154:157], v[48:51]
	v_mfma_f32_16x16x32_bf16 v[20:23], v[158:161], v[154:157], v[20:23]
	ds_read_b128 v[154:157], v6 offset:9216
	s_waitcnt lgkmcnt(3)
	v_mfma_f32_16x16x32_bf16 v[56:59], v[100:103], v[162:165], v[56:59]
	v_mfma_f32_16x16x32_bf16 v[60:63], v[140:143], v[162:165], v[60:63]
	v_mfma_f32_16x16x32_bf16 v[64:67], v[150:153], v[162:165], v[64:67]
	v_mfma_f32_16x16x32_bf16 v[28:31], v[158:161], v[162:165], v[28:31]
	ds_read_b128 v[162:165], v6 offset:11264
	s_waitcnt lgkmcnt(3)
	v_mfma_f32_16x16x32_bf16 v[72:75], v[100:103], v[166:169], v[72:75]
	v_mfma_f32_16x16x32_bf16 v[76:79], v[140:143], v[166:169], v[76:79]
	v_mfma_f32_16x16x32_bf16 v[80:83], v[150:153], v[166:169], v[80:83]
	v_mfma_f32_16x16x32_bf16 v[32:35], v[158:161], v[166:169], v[32:35]
	ds_read_b128 v[166:169], v6 offset:13312
	s_waitcnt lgkmcnt(3)
	v_mfma_f32_16x16x32_bf16 v[88:91], v[100:103], v[170:173], v[88:91]
	v_mfma_f32_16x16x32_bf16 v[92:95], v[140:143], v[170:173], v[92:95]
	v_mfma_f32_16x16x32_bf16 v[96:99], v[150:153], v[170:173], v[96:99]
	v_mfma_f32_16x16x32_bf16 v[36:39], v[158:161], v[170:173], v[36:39]
	ds_read_b128 v[170:173], v6 offset:15360
	s_waitcnt lgkmcnt(3)
	v_mfma_f32_16x16x32_bf16 v[104:107], v[100:103], v[154:157], v[104:107]
	v_mfma_f32_16x16x32_bf16 v[108:111], v[140:143], v[154:157], v[108:111]
	v_mfma_f32_16x16x32_bf16 v[112:115], v[150:153], v[154:157], v[112:115]
	v_mfma_f32_16x16x32_bf16 v[52:55], v[158:161], v[154:157], v[52:55]
	s_waitcnt lgkmcnt(2)
	v_mfma_f32_16x16x32_bf16 v[116:119], v[100:103], v[162:165], v[116:119]
	v_mfma_f32_16x16x32_bf16 v[120:123], v[140:143], v[162:165], v[120:123]
	v_mfma_f32_16x16x32_bf16 v[124:127], v[150:153], v[162:165], v[124:127]
	v_mfma_f32_16x16x32_bf16 v[68:71], v[158:161], v[162:165], v[68:71]
	s_waitcnt lgkmcnt(1)
	v_mfma_f32_16x16x32_bf16 v[128:131], v[100:103], v[166:169], v[128:131]
	v_mfma_f32_16x16x32_bf16 v[132:135], v[140:143], v[166:169], v[132:135]
	v_mfma_f32_16x16x32_bf16 v[136:139], v[150:153], v[166:169], v[136:139]
	v_mfma_f32_16x16x32_bf16 v[84:87], v[158:161], v[166:169], v[84:87]
	s_waitcnt lgkmcnt(0)
	v_mfma_f32_16x16x32_bf16 v[100:103], v[100:103], v[170:173], v[8:11]
	v_mfma_f32_16x16x32_bf16 v[150:153], v[150:153], v[170:173], v[16:19]
	v_mfma_f32_16x16x32_bf16 v[24:27], v[158:161], v[170:173], v[24:27]
	v_mfma_f32_16x16x32_bf16 v[140:143], v[140:143], v[170:173], v[12:15]
	s_add_u32 s46, s0, 0x100
	s_addc_u32 s47, s1, 0
	s_add_u32 s48, s14, 0x100
	s_waitcnt vmcnt(0)
	s_barrier
	s_addc_u32 s49, s15, 0
	v_lshl_add_u64 v[8:9], s[46:47], 0, v[0:1]
	s_mov_b32 s45, m0
	s_mov_b32 m0, s27
	s_nop 0
	global_load_lds_dwordx4 v[8:9], off
	s_mov_b32 m0, s45
	v_lshl_add_u64 v[8:9], s[48:49], 0, v[0:1]
	s_mov_b32 s45, m0
	s_mov_b32 m0, s28
	s_nop 0
	global_load_lds_dwordx4 v[8:9], off
	s_mov_b32 m0, s45
	v_lshl_add_u64 v[8:9], s[46:47], 0, v[2:3]
	s_mov_b32 s45, m0
	s_mov_b32 m0, s29
	s_nop 0
	global_load_lds_dwordx4 v[8:9], off
	s_mov_b32 m0, s45
	v_lshl_add_u64 v[8:9], s[48:49], 0, v[2:3]
	s_mov_b32 s45, m0
	s_mov_b32 m0, s30
	s_nop 0
	global_load_lds_dwordx4 v[8:9], off
	s_mov_b32 m0, s45
	v_lshl_add_u64 v[8:9], s[46:47], 0, v[4:5]
	s_mov_b32 s45, m0
	s_mov_b32 m0, s31
	s_nop 0
	global_load_lds_dwordx4 v[8:9], off
	s_mov_b32 m0, s45
	v_lshl_add_u64 v[8:9], s[48:49], 0, v[4:5]
	s_mov_b32 s45, m0
	s_mov_b32 m0, s34
	s_nop 0
	global_load_lds_dwordx4 v[8:9], off
	s_mov_b32 m0, s45
	v_lshl_add_u64 v[8:9], s[46:47], 0, v[146:147]
	s_mov_b32 s45, m0
	s_mov_b32 m0, s35
	s_nop 0
	global_load_lds_dwordx4 v[8:9], off
	s_mov_b32 m0, s45
	v_lshl_add_u64 v[8:9], s[48:49], 0, v[146:147]
	s_mov_b32 s45, m0
	s_mov_b32 m0, s36
	s_nop 0
	global_load_lds_dwordx4 v[8:9], off
	s_mov_b32 m0, s45
	v_or_b32_e32 v8, 0x18000, v7
	v_or_b32_e32 v9, 0x18800, v7
	v_or_b32_e32 v11, 0x19000, v7
	v_or_b32_e32 v10, 0x19800, v7
	ds_read_b128 v[154:157], v8
	ds_read_b128 v[158:161], v9
	ds_read_b128 v[162:165], v11
	ds_read_b128 v[166:169], v10
	v_bitop3_b32 v207, v145, s33, v149 bitop3:0xde
	v_add_u32_e32 v12, v207, v182
	ds_read_b128 v[16:19], v12
	v_add_u32_e32 v13, v207, v183
	v_add_u32_e32 v14, v207, v189
	v_add_u32_e32 v15, v207, v199
	ds_read_b128 v[170:173], v13
	ds_read_b128 v[174:177], v14
	ds_read_b128 v[178:181], v15
	s_waitcnt lgkmcnt(3)
	v_mfma_f32_16x16x32_bf16 v[40:43], v[154:157], v[16:19], v[40:43]
	v_mfma_f32_16x16x32_bf16 v[44:47], v[158:161], v[16:19], v[44:47]
	v_mfma_f32_16x16x32_bf16 v[48:51], v[162:165], v[16:19], v[48:51]
	v_mfma_f32_16x16x32_bf16 v[214:217], v[166:169], v[16:19], v[20:23]
	v_add_u32_e32 v16, v207, v200
	v_add_u32_e32 v17, v207, v201
	v_add_u32_e32 v18, v207, v203
	v_add_u32_e32 v19, v207, v206
	ds_read_b128 v[20:23], v16
	s_waitcnt lgkmcnt(3)
	v_mfma_f32_16x16x32_bf16 v[56:59], v[154:157], v[170:173], v[56:59]
	v_mfma_f32_16x16x32_bf16 v[60:63], v[158:161], v[170:173], v[60:63]
	v_mfma_f32_16x16x32_bf16 v[64:67], v[162:165], v[170:173], v[64:67]
	v_mfma_f32_16x16x32_bf16 v[170:173], v[166:169], v[170:173], v[28:31]
	s_nop 2
	ds_read_b128 v[28:31], v17
	s_waitcnt lgkmcnt(3)
	v_mfma_f32_16x16x32_bf16 v[72:75], v[154:157], v[174:177], v[72:75]
	v_mfma_f32_16x16x32_bf16 v[76:79], v[158:161], v[174:177], v[76:79]
	v_mfma_f32_16x16x32_bf16 v[80:83], v[162:165], v[174:177], v[80:83]
	v_mfma_f32_16x16x32_bf16 v[32:35], v[166:169], v[174:177], v[32:35]
	ds_read_b128 v[174:177], v18
	s_waitcnt lgkmcnt(3)
	v_mfma_f32_16x16x32_bf16 v[88:91], v[154:157], v[178:181], v[88:91]
	v_mfma_f32_16x16x32_bf16 v[92:95], v[158:161], v[178:181], v[92:95]
	v_mfma_f32_16x16x32_bf16 v[96:99], v[162:165], v[178:181], v[96:99]
	v_mfma_f32_16x16x32_bf16 v[36:39], v[166:169], v[178:181], v[36:39]
	ds_read_b128 v[178:181], v19
	s_waitcnt lgkmcnt(3)
	v_mfma_f32_16x16x32_bf16 v[104:107], v[154:157], v[20:23], v[104:107]
	v_mfma_f32_16x16x32_bf16 v[108:111], v[158:161], v[20:23], v[108:111]
	v_mfma_f32_16x16x32_bf16 v[112:115], v[162:165], v[20:23], v[112:115]
	v_mfma_f32_16x16x32_bf16 v[52:55], v[166:169], v[20:23], v[52:55]
	s_waitcnt lgkmcnt(2)
	v_mfma_f32_16x16x32_bf16 v[116:119], v[154:157], v[28:31], v[116:119]
	v_mfma_f32_16x16x32_bf16 v[120:123], v[158:161], v[28:31], v[120:123]
	v_mfma_f32_16x16x32_bf16 v[124:127], v[162:165], v[28:31], v[124:127]
	v_mfma_f32_16x16x32_bf16 v[68:71], v[166:169], v[28:31], v[68:71]
	s_waitcnt lgkmcnt(1)
	v_mfma_f32_16x16x32_bf16 v[128:131], v[154:157], v[174:177], v[128:131]
	v_mfma_f32_16x16x32_bf16 v[132:135], v[158:161], v[174:177], v[132:135]
	v_mfma_f32_16x16x32_bf16 v[84:87], v[166:169], v[174:177], v[84:87]
	s_waitcnt lgkmcnt(0)
	v_mfma_f32_16x16x32_bf16 v[100:103], v[154:157], v[178:181], v[100:103]
	v_mfma_f32_16x16x32_bf16 v[150:153], v[162:165], v[178:181], v[150:153]
	v_mfma_f32_16x16x32_bf16 v[154:157], v[166:169], v[178:181], v[24:27]
	v_mfma_f32_16x16x32_bf16 v[136:139], v[162:165], v[174:177], v[136:139]
	v_mfma_f32_16x16x32_bf16 v[140:143], v[158:161], v[178:181], v[140:143]
	v_or_b32_e32 v20, 0x18400, v7
	v_or_b32_e32 v21, 0x18c00, v7
	v_or_b32_e32 v23, 0x19400, v7
	v_or_b32_e32 v22, 0x19c00, v7
	ds_read_b128 v[158:161], v20
	ds_read_b128 v[162:165], v21
	ds_read_b128 v[166:169], v23
	ds_read_b128 v[174:177], v22
	s_mov_b32 s45, 0x10400
	v_bitop3_b32 v145, v145, s45, v149 bitop3:0xde
	v_add_u32_e32 v24, v145, v182
	ds_read_b128 v[28:31], v24
	v_add_u32_e32 v25, v145, v183
	v_add_u32_e32 v26, v145, v189
	v_add_u32_e32 v27, v145, v199
	ds_read_b128 v[178:181], v25
	ds_read_b128 v[218:221], v26
	ds_read_b128 v[222:225], v27
	s_waitcnt lgkmcnt(3)
	v_mfma_f32_16x16x32_bf16 v[40:43], v[158:161], v[28:31], v[40:43]
	v_mfma_f32_16x16x32_bf16 v[44:47], v[162:165], v[28:31], v[44:47]
	v_mfma_f32_16x16x32_bf16 v[48:51], v[166:169], v[28:31], v[48:51]
	v_mfma_f32_16x16x32_bf16 v[214:217], v[174:177], v[28:31], v[214:217]
	v_add_u32_e32 v28, v145, v200
	v_add_u32_e32 v29, v145, v201
	v_add_u32_e32 v30, v145, v203
	v_add_u32_e32 v31, v145, v206
	ds_read_b128 v[226:229], v28
	s_waitcnt lgkmcnt(3)
	v_mfma_f32_16x16x32_bf16 v[56:59], v[158:161], v[178:181], v[56:59]
	v_mfma_f32_16x16x32_bf16 v[60:63], v[162:165], v[178:181], v[60:63]
	v_mfma_f32_16x16x32_bf16 v[64:67], v[166:169], v[178:181], v[64:67]
	v_mfma_f32_16x16x32_bf16 v[170:173], v[174:177], v[178:181], v[170:173]
	ds_read_b128 v[178:181], v29
	s_waitcnt lgkmcnt(3)
	v_mfma_f32_16x16x32_bf16 v[72:75], v[158:161], v[218:221], v[72:75]
	v_mfma_f32_16x16x32_bf16 v[76:79], v[162:165], v[218:221], v[76:79]
	v_mfma_f32_16x16x32_bf16 v[80:83], v[166:169], v[218:221], v[80:83]
	v_mfma_f32_16x16x32_bf16 v[32:35], v[174:177], v[218:221], v[32:35]
	ds_read_b128 v[218:221], v30
	s_waitcnt lgkmcnt(3)
	v_mfma_f32_16x16x32_bf16 v[88:91], v[158:161], v[222:225], v[88:91]
	v_mfma_f32_16x16x32_bf16 v[92:95], v[162:165], v[222:225], v[92:95]
	v_mfma_f32_16x16x32_bf16 v[96:99], v[166:169], v[222:225], v[96:99]
	v_mfma_f32_16x16x32_bf16 v[36:39], v[174:177], v[222:225], v[36:39]
	ds_read_b128 v[222:225], v31
	s_waitcnt lgkmcnt(3)
	v_mfma_f32_16x16x32_bf16 v[104:107], v[158:161], v[226:229], v[104:107]
	v_mfma_f32_16x16x32_bf16 v[108:111], v[162:165], v[226:229], v[108:111]
	v_mfma_f32_16x16x32_bf16 v[112:115], v[166:169], v[226:229], v[112:115]
	v_mfma_f32_16x16x32_bf16 v[52:55], v[174:177], v[226:229], v[52:55]
	s_waitcnt lgkmcnt(2)
	v_mfma_f32_16x16x32_bf16 v[116:119], v[158:161], v[178:181], v[116:119]
	v_mfma_f32_16x16x32_bf16 v[120:123], v[162:165], v[178:181], v[120:123]
	v_mfma_f32_16x16x32_bf16 v[124:127], v[166:169], v[178:181], v[124:127]
	v_mfma_f32_16x16x32_bf16 v[68:71], v[174:177], v[178:181], v[68:71]
	s_waitcnt lgkmcnt(1)
	v_mfma_f32_16x16x32_bf16 v[132:135], v[162:165], v[218:221], v[132:135]
	v_mfma_f32_16x16x32_bf16 v[84:87], v[174:177], v[218:221], v[84:87]
	s_waitcnt lgkmcnt(0)
	v_mfma_f32_16x16x32_bf16 v[100:103], v[158:161], v[222:225], v[100:103]
	v_mfma_f32_16x16x32_bf16 v[150:153], v[166:169], v[222:225], v[150:153]
	v_mfma_f32_16x16x32_bf16 v[154:157], v[174:177], v[222:225], v[154:157]
	v_mfma_f32_16x16x32_bf16 v[128:131], v[158:161], v[218:221], v[128:131]
	v_mfma_f32_16x16x32_bf16 v[136:139], v[166:169], v[218:221], v[136:139]
	v_mfma_f32_16x16x32_bf16 v[140:143], v[162:165], v[222:225], v[140:143]
	s_add_u32 s46, s0, 0x180
	s_addc_u32 s47, s1, 0
	s_add_u32 s48, s14, 0x180
	s_waitcnt vmcnt(0)
	s_barrier
	s_addc_u32 s49, s15, 0
	v_lshl_add_u64 v[158:159], s[46:47], 0, v[0:1]
	s_mov_b32 s45, m0
	s_mov_b32 m0, s38
	s_nop 0
	global_load_lds_dwordx4 v[158:159], off
	s_mov_b32 m0, s45
	v_lshl_add_u64 v[158:159], s[48:49], 0, v[0:1]
	s_mov_b32 s45, m0
	s_mov_b32 m0, s37
	s_nop 0
	global_load_lds_dwordx4 v[158:159], off
	s_mov_b32 m0, s45
	v_lshl_add_u64 v[158:159], s[46:47], 0, v[2:3]
	s_mov_b32 s45, m0
	s_mov_b32 m0, s39
	s_nop 0
	global_load_lds_dwordx4 v[158:159], off
	s_mov_b32 m0, s45
	v_lshl_add_u64 v[158:159], s[48:49], 0, v[2:3]
	s_mov_b32 s45, m0
	s_mov_b32 m0, s40
	s_nop 0
	global_load_lds_dwordx4 v[158:159], off
	s_mov_b32 m0, s45
	v_lshl_add_u64 v[158:159], s[46:47], 0, v[4:5]
	s_mov_b32 s45, m0
	s_mov_b32 m0, s41
	s_nop 0
	global_load_lds_dwordx4 v[158:159], off
	s_mov_b32 m0, s45
	v_lshl_add_u64 v[158:159], s[48:49], 0, v[4:5]
	s_mov_b32 s45, m0
	s_mov_b32 m0, s42
	s_nop 0
	global_load_lds_dwordx4 v[158:159], off
	s_mov_b32 m0, s45
	v_lshl_add_u64 v[158:159], s[46:47], 0, v[146:147]
	s_mov_b32 s45, m0
	s_mov_b32 m0, s43
	s_nop 0
	global_load_lds_dwordx4 v[158:159], off
	s_mov_b32 m0, s45
	v_lshl_add_u64 v[158:159], s[48:49], 0, v[146:147]
	s_mov_b32 s45, m0
	s_mov_b32 m0, s44
	s_nop 0
	global_load_lds_dwordx4 v[158:159], off
	s_mov_b32 m0, s45
	ds_read_b128 v[158:161], v7 offset:32768
	ds_read_b128 v[162:165], v7 offset:34816
	ds_read_b128 v[166:169], v7 offset:36864
	ds_read_b128 v[178:181], v7 offset:38912
	ds_read_b128 v[174:177], v6
	ds_read_b128 v[218:221], v6 offset:2048
	ds_read_b128 v[222:225], v6 offset:4096
	ds_read_b128 v[226:229], v6 offset:6144
	s_waitcnt lgkmcnt(3)
	v_mfma_f32_16x16x32_bf16 v[40:43], v[158:161], v[174:177], v[40:43]
	v_mfma_f32_16x16x32_bf16 v[44:47], v[162:165], v[174:177], v[44:47]
	v_mfma_f32_16x16x32_bf16 v[48:51], v[166:169], v[174:177], v[48:51]
	v_mfma_f32_16x16x32_bf16 v[174:177], v[178:181], v[174:177], v[214:217]
	s_nop 2
	ds_read_b128 v[214:217], v6 offset:8192
	s_waitcnt lgkmcnt(3)
	v_mfma_f32_16x16x32_bf16 v[56:59], v[158:161], v[218:221], v[56:59]
	v_mfma_f32_16x16x32_bf16 v[60:63], v[162:165], v[218:221], v[60:63]
	v_mfma_f32_16x16x32_bf16 v[64:67], v[166:169], v[218:221], v[64:67]
	v_mfma_f32_16x16x32_bf16 v[170:173], v[178:181], v[218:221], v[170:173]
	ds_read_b128 v[218:221], v6 offset:10240
	s_waitcnt lgkmcnt(3)
	v_mfma_f32_16x16x32_bf16 v[72:75], v[158:161], v[222:225], v[72:75]
	v_mfma_f32_16x16x32_bf16 v[76:79], v[162:165], v[222:225], v[76:79]
	v_mfma_f32_16x16x32_bf16 v[80:83], v[166:169], v[222:225], v[80:83]
	v_mfma_f32_16x16x32_bf16 v[32:35], v[178:181], v[222:225], v[32:35]
	ds_read_b128 v[222:225], v6 offset:12288
	s_waitcnt lgkmcnt(3)
	v_mfma_f32_16x16x32_bf16 v[88:91], v[158:161], v[226:229], v[88:91]
	v_mfma_f32_16x16x32_bf16 v[92:95], v[162:165], v[226:229], v[92:95]
	v_mfma_f32_16x16x32_bf16 v[96:99], v[166:169], v[226:229], v[96:99]
	v_mfma_f32_16x16x32_bf16 v[36:39], v[178:181], v[226:229], v[36:39]
	ds_read_b128 v[226:229], v6 offset:14336
	s_waitcnt lgkmcnt(3)
	v_mfma_f32_16x16x32_bf16 v[104:107], v[158:161], v[214:217], v[104:107]
	v_mfma_f32_16x16x32_bf16 v[108:111], v[162:165], v[214:217], v[108:111]
	v_mfma_f32_16x16x32_bf16 v[112:115], v[166:169], v[214:217], v[112:115]
	v_mfma_f32_16x16x32_bf16 v[52:55], v[178:181], v[214:217], v[52:55]
	s_waitcnt lgkmcnt(2)
	v_mfma_f32_16x16x32_bf16 v[116:119], v[158:161], v[218:221], v[116:119]
	v_mfma_f32_16x16x32_bf16 v[120:123], v[162:165], v[218:221], v[120:123]
	v_mfma_f32_16x16x32_bf16 v[124:127], v[166:169], v[218:221], v[124:127]
	v_mfma_f32_16x16x32_bf16 v[68:71], v[178:181], v[218:221], v[68:71]
	s_waitcnt lgkmcnt(1)
	v_mfma_f32_16x16x32_bf16 v[132:135], v[162:165], v[222:225], v[132:135]
	v_mfma_f32_16x16x32_bf16 v[84:87], v[178:181], v[222:225], v[84:87]
	s_waitcnt lgkmcnt(0)
	v_mfma_f32_16x16x32_bf16 v[100:103], v[158:161], v[226:229], v[100:103]
	v_mfma_f32_16x16x32_bf16 v[150:153], v[166:169], v[226:229], v[150:153]
	v_mfma_f32_16x16x32_bf16 v[154:157], v[178:181], v[226:229], v[154:157]
	v_mfma_f32_16x16x32_bf16 v[128:131], v[158:161], v[222:225], v[128:131]
	v_mfma_f32_16x16x32_bf16 v[136:139], v[166:169], v[222:225], v[136:139]
	v_mfma_f32_16x16x32_bf16 v[140:143], v[162:165], v[226:229], v[140:143]
	ds_read_b128 v[158:161], v7 offset:33792
	ds_read_b128 v[162:165], v7 offset:35840
	ds_read_b128 v[166:169], v7 offset:37888
	ds_read_b128 v[214:217], v7 offset:39936
	ds_read_b128 v[178:181], v6 offset:1024
	ds_read_b128 v[218:221], v6 offset:3072
	ds_read_b128 v[222:225], v6 offset:5120
	ds_read_b128 v[226:229], v6 offset:7168
	s_waitcnt lgkmcnt(3)
	v_mfma_f32_16x16x32_bf16 v[40:43], v[158:161], v[178:181], v[40:43]
	v_mfma_f32_16x16x32_bf16 v[44:47], v[162:165], v[178:181], v[44:47]
	v_mfma_f32_16x16x32_bf16 v[48:51], v[166:169], v[178:181], v[48:51]
	v_mfma_f32_16x16x32_bf16 v[174:177], v[214:217], v[178:181], v[174:177]
	ds_read_b128 v[178:181], v6 offset:9216
	s_waitcnt lgkmcnt(3)
	v_mfma_f32_16x16x32_bf16 v[56:59], v[158:161], v[218:221], v[56:59]
	v_mfma_f32_16x16x32_bf16 v[60:63], v[162:165], v[218:221], v[60:63]
	v_mfma_f32_16x16x32_bf16 v[64:67], v[166:169], v[218:221], v[64:67]
	v_mfma_f32_16x16x32_bf16 v[170:173], v[214:217], v[218:221], v[170:173]
	ds_read_b128 v[218:221], v6 offset:11264
	s_waitcnt lgkmcnt(3)
	v_mfma_f32_16x16x32_bf16 v[72:75], v[158:161], v[222:225], v[72:75]
	v_mfma_f32_16x16x32_bf16 v[76:79], v[162:165], v[222:225], v[76:79]
	v_mfma_f32_16x16x32_bf16 v[80:83], v[166:169], v[222:225], v[80:83]
	v_mfma_f32_16x16x32_bf16 v[32:35], v[214:217], v[222:225], v[32:35]
	ds_read_b128 v[222:225], v6 offset:13312
	s_waitcnt lgkmcnt(3)
	v_mfma_f32_16x16x32_bf16 v[88:91], v[158:161], v[226:229], v[88:91]
	v_mfma_f32_16x16x32_bf16 v[92:95], v[162:165], v[226:229], v[92:95]
	v_mfma_f32_16x16x32_bf16 v[96:99], v[166:169], v[226:229], v[96:99]
	v_mfma_f32_16x16x32_bf16 v[36:39], v[214:217], v[226:229], v[36:39]
	ds_read_b128 v[226:229], v6 offset:15360
	s_waitcnt lgkmcnt(3)
	v_mfma_f32_16x16x32_bf16 v[104:107], v[158:161], v[178:181], v[104:107]
	v_mfma_f32_16x16x32_bf16 v[108:111], v[162:165], v[178:181], v[108:111]
	v_mfma_f32_16x16x32_bf16 v[112:115], v[166:169], v[178:181], v[112:115]
	v_mfma_f32_16x16x32_bf16 v[52:55], v[214:217], v[178:181], v[52:55]
	s_waitcnt lgkmcnt(2)
	v_mfma_f32_16x16x32_bf16 v[116:119], v[158:161], v[218:221], v[116:119]
	v_mfma_f32_16x16x32_bf16 v[120:123], v[162:165], v[218:221], v[120:123]
	v_mfma_f32_16x16x32_bf16 v[124:127], v[166:169], v[218:221], v[124:127]
	v_mfma_f32_16x16x32_bf16 v[68:71], v[214:217], v[218:221], v[68:71]
	s_waitcnt lgkmcnt(1)
	v_mfma_f32_16x16x32_bf16 v[132:135], v[162:165], v[222:225], v[132:135]
	v_mfma_f32_16x16x32_bf16 v[84:87], v[214:217], v[222:225], v[84:87]
	s_waitcnt lgkmcnt(0)
	v_mfma_f32_16x16x32_bf16 v[100:103], v[158:161], v[226:229], v[100:103]
	v_mfma_f32_16x16x32_bf16 v[150:153], v[166:169], v[226:229], v[150:153]
	v_mfma_f32_16x16x32_bf16 v[154:157], v[214:217], v[226:229], v[154:157]
	v_mfma_f32_16x16x32_bf16 v[128:131], v[158:161], v[222:225], v[128:131]
	v_mfma_f32_16x16x32_bf16 v[136:139], v[166:169], v[222:225], v[136:139]
	v_mfma_f32_16x16x32_bf16 v[140:143], v[162:165], v[226:229], v[140:143]
	s_add_u32 s46, s0, 0x200
	s_addc_u32 s47, s1, 0
	s_add_u32 s48, s14, 0x200
	s_waitcnt vmcnt(0)
	s_barrier
	s_addc_u32 s49, s15, 0
	s_mov_b32 s45, 0x280
	ds_read_b128 v[158:161], v8
	ds_read_b128 v[162:165], v12
	ds_read_b128 v[166:169], v9
	ds_read_b128 v[178:181], v13
	ds_read_b128 v[214:217], v11
	ds_read_b128 v[218:221], v10
	ds_read_b128 v[222:225], v14
	ds_read_b128 v[226:229], v15
	s_branch .Lmy_rot_r_r6b

.Lmy_rot_r_r6b:
	s_waitcnt lgkmcnt(6)
	v_mfma_f32_16x16x32_bf16 v[40:43], v[158:161], v[162:165], v[40:43]
	s_waitcnt lgkmcnt(5)
	v_mfma_f32_16x16x32_bf16 v[44:47], v[166:169], v[162:165], v[44:47]
	s_waitcnt lgkmcnt(4)
	s_mov_b32 m0, s27
	v_mfma_f32_16x16x32_bf16 v[56:59], v[158:161], v[178:181], v[56:59]
	global_load_lds_dwordx4 v0, s[46:47]
	v_mfma_f32_16x16x32_bf16 v[60:63], v[166:169], v[178:181], v[60:63]
	s_waitcnt lgkmcnt(3)
	v_mfma_f32_16x16x32_bf16 v[48:51], v[214:217], v[162:165], v[48:51]
	v_mfma_f32_16x16x32_bf16 v[64:67], v[214:217], v[178:181], v[64:67]
	s_waitcnt lgkmcnt(2)
	s_mov_b32 m0, s28
	v_mfma_f32_16x16x32_bf16 v[174:177], v[218:221], v[162:165], v[174:177]
	global_load_lds_dwordx4 v0, s[48:49]
	ds_read_b128 v[162:165], v16
	v_mfma_f32_16x16x32_bf16 v[170:173], v[218:221], v[178:181], v[170:173]
	ds_read_b128 v[178:181], v17
	s_waitcnt lgkmcnt(3)
	v_mfma_f32_16x16x32_bf16 v[72:75], v[158:161], v[222:225], v[72:75]
	v_mfma_f32_16x16x32_bf16 v[76:79], v[166:169], v[222:225], v[76:79]
	s_mov_b32 m0, s29
	v_mfma_f32_16x16x32_bf16 v[80:83], v[214:217], v[222:225], v[80:83]
	global_load_lds_dwordx4 v2, s[46:47]
	v_mfma_f32_16x16x32_bf16 v[32:35], v[218:221], v[222:225], v[32:35]
	ds_read_b128 v[222:225], v18
	s_waitcnt lgkmcnt(3)
	v_mfma_f32_16x16x32_bf16 v[88:91], v[158:161], v[226:229], v[88:91]
	v_mfma_f32_16x16x32_bf16 v[92:95], v[166:169], v[226:229], v[92:95]
	s_mov_b32 m0, s30
	v_mfma_f32_16x16x32_bf16 v[96:99], v[214:217], v[226:229], v[96:99]
	global_load_lds_dwordx4 v2, s[48:49]
	v_mfma_f32_16x16x32_bf16 v[36:39], v[218:221], v[226:229], v[36:39]
	ds_read_b128 v[226:229], v19
	s_waitcnt lgkmcnt(3)
	v_mfma_f32_16x16x32_bf16 v[108:111], v[166:169], v[162:165], v[108:111]
	s_waitcnt lgkmcnt(2)
	v_mfma_f32_16x16x32_bf16 v[120:123], v[166:169], v[178:181], v[120:123]
	s_waitcnt lgkmcnt(1)
	s_mov_b32 m0, s31
	v_mfma_f32_16x16x32_bf16 v[132:135], v[166:169], v[222:225], v[132:135]
	global_load_lds_dwordx4 v4, s[46:47]
	s_waitcnt lgkmcnt(0)
	v_mfma_f32_16x16x32_bf16 v[140:143], v[166:169], v[226:229], v[140:143]
	ds_read_b128 v[166:169], v20
	v_mfma_f32_16x16x32_bf16 v[104:107], v[158:161], v[162:165], v[104:107]
	v_mfma_f32_16x16x32_bf16 v[116:119], v[158:161], v[178:181], v[116:119]
	s_mov_b32 m0, s34
	v_mfma_f32_16x16x32_bf16 v[128:131], v[158:161], v[222:225], v[128:131]
	global_load_lds_dwordx4 v4, s[48:49]
	v_mfma_f32_16x16x32_bf16 v[100:103], v[158:161], v[226:229], v[100:103]
	ds_read_b128 v[158:161], v24
	v_mfma_f32_16x16x32_bf16 v[124:127], v[214:217], v[178:181], v[124:127]
	v_mfma_f32_16x16x32_bf16 v[68:71], v[218:221], v[178:181], v[68:71]
	ds_read_b128 v[178:181], v21
	s_mov_b32 m0, s35
	v_mfma_f32_16x16x32_bf16 v[112:115], v[214:217], v[162:165], v[112:115]
	global_load_lds_dwordx4 v146, s[46:47]
	v_mfma_f32_16x16x32_bf16 v[52:55], v[218:221], v[162:165], v[52:55]
	ds_read_b128 v[162:165], v25
	v_mfma_f32_16x16x32_bf16 v[136:139], v[214:217], v[222:225], v[136:139]
	v_mfma_f32_16x16x32_bf16 v[84:87], v[218:221], v[222:225], v[84:87]
	ds_read_b128 v[222:225], v26
	s_mov_b32 m0, s36
	v_mfma_f32_16x16x32_bf16 v[150:153], v[214:217], v[226:229], v[150:153]
	global_load_lds_dwordx4 v146, s[48:49]
	ds_read_b128 v[214:217], v23
	v_mfma_f32_16x16x32_bf16 v[154:157], v[218:221], v[226:229], v[154:157]
	ds_read_b128 v[218:221], v22
	ds_read_b128 v[226:229], v27
	s_waitcnt lgkmcnt(6)
	v_mfma_f32_16x16x32_bf16 v[40:43], v[166:169], v[158:161], v[40:43]
	s_waitcnt lgkmcnt(5)
	v_mfma_f32_16x16x32_bf16 v[44:47], v[178:181], v[158:161], v[44:47]
	s_waitcnt lgkmcnt(4)
	v_mfma_f32_16x16x32_bf16 v[56:59], v[166:169], v[162:165], v[56:59]
	v_mfma_f32_16x16x32_bf16 v[60:63], v[178:181], v[162:165], v[60:63]
	s_waitcnt lgkmcnt(3)
	v_mfma_f32_16x16x32_bf16 v[72:75], v[166:169], v[222:225], v[72:75]
	v_mfma_f32_16x16x32_bf16 v[76:79], v[178:181], v[222:225], v[76:79]
	s_waitcnt lgkmcnt(2)
	v_mfma_f32_16x16x32_bf16 v[48:51], v[214:217], v[158:161], v[48:51]
	s_waitcnt lgkmcnt(1)
	v_mfma_f32_16x16x32_bf16 v[174:177], v[218:221], v[158:161], v[174:177]
	ds_read_b128 v[158:161], v28
	v_mfma_f32_16x16x32_bf16 v[64:67], v[214:217], v[162:165], v[64:67]
	v_mfma_f32_16x16x32_bf16 v[170:173], v[218:221], v[162:165], v[170:173]
	ds_read_b128 v[162:165], v29
	v_mfma_f32_16x16x32_bf16 v[80:83], v[214:217], v[222:225], v[80:83]
	v_mfma_f32_16x16x32_bf16 v[32:35], v[218:221], v[222:225], v[32:35]
	ds_read_b128 v[222:225], v30
	s_waitcnt lgkmcnt(3)
	v_mfma_f32_16x16x32_bf16 v[88:91], v[166:169], v[226:229], v[88:91]
	v_mfma_f32_16x16x32_bf16 v[92:95], v[178:181], v[226:229], v[92:95]
	v_mfma_f32_16x16x32_bf16 v[96:99], v[214:217], v[226:229], v[96:99]
	v_mfma_f32_16x16x32_bf16 v[36:39], v[218:221], v[226:229], v[36:39]
	ds_read_b128 v[226:229], v31
	s_waitcnt lgkmcnt(3)
	v_mfma_f32_16x16x32_bf16 v[104:107], v[166:169], v[158:161], v[104:107]
	v_mfma_f32_16x16x32_bf16 v[108:111], v[178:181], v[158:161], v[108:111]
	v_mfma_f32_16x16x32_bf16 v[112:115], v[214:217], v[158:161], v[112:115]
	v_mfma_f32_16x16x32_bf16 v[52:55], v[218:221], v[158:161], v[52:55]
	s_waitcnt lgkmcnt(2)
	v_mfma_f32_16x16x32_bf16 v[116:119], v[166:169], v[162:165], v[116:119]
	v_mfma_f32_16x16x32_bf16 v[120:123], v[178:181], v[162:165], v[120:123]
	v_mfma_f32_16x16x32_bf16 v[124:127], v[214:217], v[162:165], v[124:127]
	v_mfma_f32_16x16x32_bf16 v[68:71], v[218:221], v[162:165], v[68:71]
	s_add_u32 s46, s0, s45
	s_addc_u32 s47, s1, 0
	s_add_u32 s48, s14, s45
	s_addc_u32 s49, s15, 0
	s_add_u32 s45, s45, 0x80
	s_waitcnt vmcnt(0)
	s_waitcnt lgkmcnt(0)
	s_barrier
	ds_read_b128 v[158:161], v7 offset:32768
	ds_read_b128 v[162:165], v6
	v_mfma_f32_16x16x32_bf16 v[128:131], v[166:169], v[222:225], v[128:131]
	v_mfma_f32_16x16x32_bf16 v[100:103], v[166:169], v[226:229], v[100:103]
	ds_read_b128 v[166:169], v7 offset:34816
	v_mfma_f32_16x16x32_bf16 v[132:135], v[178:181], v[222:225], v[132:135]
	v_mfma_f32_16x16x32_bf16 v[140:143], v[178:181], v[226:229], v[140:143]
	ds_read_b128 v[178:181], v6 offset:2048
	v_mfma_f32_16x16x32_bf16 v[136:139], v[214:217], v[222:225], v[136:139]
	v_mfma_f32_16x16x32_bf16 v[150:153], v[214:217], v[226:229], v[150:153]
	ds_read_b128 v[214:217], v7 offset:36864
	v_mfma_f32_16x16x32_bf16 v[84:87], v[218:221], v[222:225], v[84:87]
	v_mfma_f32_16x16x32_bf16 v[154:157], v[218:221], v[226:229], v[154:157]
	ds_read_b128 v[218:221], v7 offset:38912
	ds_read_b128 v[222:225], v6 offset:4096
	ds_read_b128 v[226:229], v6 offset:6144
	s_waitcnt lgkmcnt(6)
	v_mfma_f32_16x16x32_bf16 v[40:43], v[158:161], v[162:165], v[40:43]
	s_waitcnt lgkmcnt(5)
	v_mfma_f32_16x16x32_bf16 v[44:47], v[166:169], v[162:165], v[44:47]
	s_waitcnt lgkmcnt(4)
	s_mov_b32 m0, s38
	v_mfma_f32_16x16x32_bf16 v[56:59], v[158:161], v[178:181], v[56:59]
	global_load_lds_dwordx4 v0, s[46:47]
	v_mfma_f32_16x16x32_bf16 v[60:63], v[166:169], v[178:181], v[60:63]
	s_waitcnt lgkmcnt(3)
	v_mfma_f32_16x16x32_bf16 v[48:51], v[214:217], v[162:165], v[48:51]
	v_mfma_f32_16x16x32_bf16 v[64:67], v[214:217], v[178:181], v[64:67]
	s_waitcnt lgkmcnt(2)
	s_mov_b32 m0, s37
	v_mfma_f32_16x16x32_bf16 v[174:177], v[218:221], v[162:165], v[174:177]
	global_load_lds_dwordx4 v0, s[48:49]
	ds_read_b128 v[162:165], v6 offset:8192
	v_mfma_f32_16x16x32_bf16 v[170:173], v[218:221], v[178:181], v[170:173]
	ds_read_b128 v[178:181], v6 offset:10240
	s_waitcnt lgkmcnt(3)
	v_mfma_f32_16x16x32_bf16 v[72:75], v[158:161], v[222:225], v[72:75]
	v_mfma_f32_16x16x32_bf16 v[76:79], v[166:169], v[222:225], v[76:79]
	s_mov_b32 m0, s39
	v_mfma_f32_16x16x32_bf16 v[80:83], v[214:217], v[222:225], v[80:83]
	global_load_lds_dwordx4 v2, s[46:47]
	v_mfma_f32_16x16x32_bf16 v[32:35], v[218:221], v[222:225], v[32:35]
	ds_read_b128 v[222:225], v6 offset:12288
	s_waitcnt lgkmcnt(3)
	v_mfma_f32_16x16x32_bf16 v[88:91], v[158:161], v[226:229], v[88:91]
	v_mfma_f32_16x16x32_bf16 v[92:95], v[166:169], v[226:229], v[92:95]
	s_mov_b32 m0, s40
	v_mfma_f32_16x16x32_bf16 v[96:99], v[214:217], v[226:229], v[96:99]
	global_load_lds_dwordx4 v2, s[48:49]
	v_mfma_f32_16x16x32_bf16 v[36:39], v[218:221], v[226:229], v[36:39]
	ds_read_b128 v[226:229], v6 offset:14336
	s_waitcnt lgkmcnt(3)
	v_mfma_f32_16x16x32_bf16 v[108:111], v[166:169], v[162:165], v[108:111]
	s_waitcnt lgkmcnt(2)
	v_mfma_f32_16x16x32_bf16 v[120:123], v[166:169], v[178:181], v[120:123]
	s_waitcnt lgkmcnt(1)
	s_mov_b32 m0, s41
	v_mfma_f32_16x16x32_bf16 v[132:135], v[166:169], v[222:225], v[132:135]
	global_load_lds_dwordx4 v4, s[46:47]
	s_waitcnt lgkmcnt(0)
	v_mfma_f32_16x16x32_bf16 v[140:143], v[166:169], v[226:229], v[140:143]
	ds_read_b128 v[166:169], v7 offset:33792
	v_mfma_f32_16x16x32_bf16 v[104:107], v[158:161], v[162:165], v[104:107]
	v_mfma_f32_16x16x32_bf16 v[116:119], v[158:161], v[178:181], v[116:119]
	s_mov_b32 m0, s42
	v_mfma_f32_16x16x32_bf16 v[128:131], v[158:161], v[222:225], v[128:131]
	global_load_lds_dwordx4 v4, s[48:49]
	v_mfma_f32_16x16x32_bf16 v[100:103], v[158:161], v[226:229], v[100:103]
	ds_read_b128 v[158:161], v6 offset:1024
	v_mfma_f32_16x16x32_bf16 v[124:127], v[214:217], v[178:181], v[124:127]
	v_mfma_f32_16x16x32_bf16 v[68:71], v[218:221], v[178:181], v[68:71]
	ds_read_b128 v[178:181], v7 offset:35840
	s_mov_b32 m0, s43
	v_mfma_f32_16x16x32_bf16 v[112:115], v[214:217], v[162:165], v[112:115]
	global_load_lds_dwordx4 v146, s[46:47]
	v_mfma_f32_16x16x32_bf16 v[52:55], v[218:221], v[162:165], v[52:55]
	ds_read_b128 v[162:165], v6 offset:3072
	v_mfma_f32_16x16x32_bf16 v[136:139], v[214:217], v[222:225], v[136:139]
	v_mfma_f32_16x16x32_bf16 v[84:87], v[218:221], v[222:225], v[84:87]
	ds_read_b128 v[222:225], v6 offset:5120
	s_mov_b32 m0, s44
	v_mfma_f32_16x16x32_bf16 v[150:153], v[214:217], v[226:229], v[150:153]
	global_load_lds_dwordx4 v146, s[48:49]
	ds_read_b128 v[214:217], v7 offset:37888
	v_mfma_f32_16x16x32_bf16 v[154:157], v[218:221], v[226:229], v[154:157]
	ds_read_b128 v[218:221], v7 offset:39936
	ds_read_b128 v[226:229], v6 offset:7168
	s_waitcnt lgkmcnt(6)
	v_mfma_f32_16x16x32_bf16 v[40:43], v[166:169], v[158:161], v[40:43]
	s_waitcnt lgkmcnt(5)
	v_mfma_f32_16x16x32_bf16 v[44:47], v[178:181], v[158:161], v[44:47]
	s_waitcnt lgkmcnt(4)
	v_mfma_f32_16x16x32_bf16 v[56:59], v[166:169], v[162:165], v[56:59]
	v_mfma_f32_16x16x32_bf16 v[60:63], v[178:181], v[162:165], v[60:63]
	s_waitcnt lgkmcnt(3)
	v_mfma_f32_16x16x32_bf16 v[72:75], v[166:169], v[222:225], v[72:75]
	v_mfma_f32_16x16x32_bf16 v[76:79], v[178:181], v[222:225], v[76:79]
	s_waitcnt lgkmcnt(2)
	v_mfma_f32_16x16x32_bf16 v[48:51], v[214:217], v[158:161], v[48:51]
	s_waitcnt lgkmcnt(1)
	v_mfma_f32_16x16x32_bf16 v[174:177], v[218:221], v[158:161], v[174:177]
	ds_read_b128 v[158:161], v6 offset:9216
	v_mfma_f32_16x16x32_bf16 v[64:67], v[214:217], v[162:165], v[64:67]
	v_mfma_f32_16x16x32_bf16 v[170:173], v[218:221], v[162:165], v[170:173]
	ds_read_b128 v[162:165], v6 offset:11264
	v_mfma_f32_16x16x32_bf16 v[80:83], v[214:217], v[222:225], v[80:83]
	v_mfma_f32_16x16x32_bf16 v[32:35], v[218:221], v[222:225], v[32:35]
	ds_read_b128 v[222:225], v6 offset:13312
	s_waitcnt lgkmcnt(3)
	v_mfma_f32_16x16x32_bf16 v[88:91], v[166:169], v[226:229], v[88:91]
	v_mfma_f32_16x16x32_bf16 v[92:95], v[178:181], v[226:229], v[92:95]
	v_mfma_f32_16x16x32_bf16 v[96:99], v[214:217], v[226:229], v[96:99]
	v_mfma_f32_16x16x32_bf16 v[36:39], v[218:221], v[226:229], v[36:39]
	ds_read_b128 v[226:229], v6 offset:15360
	s_waitcnt lgkmcnt(3)
	v_mfma_f32_16x16x32_bf16 v[104:107], v[166:169], v[158:161], v[104:107]
	v_mfma_f32_16x16x32_bf16 v[108:111], v[178:181], v[158:161], v[108:111]
	v_mfma_f32_16x16x32_bf16 v[112:115], v[214:217], v[158:161], v[112:115]
	v_mfma_f32_16x16x32_bf16 v[52:55], v[218:221], v[158:161], v[52:55]
	s_waitcnt lgkmcnt(2)
	v_mfma_f32_16x16x32_bf16 v[116:119], v[166:169], v[162:165], v[116:119]
	v_mfma_f32_16x16x32_bf16 v[120:123], v[178:181], v[162:165], v[120:123]
	v_mfma_f32_16x16x32_bf16 v[124:127], v[214:217], v[162:165], v[124:127]
	v_mfma_f32_16x16x32_bf16 v[68:71], v[218:221], v[162:165], v[68:71]
	s_add_u32 s46, s0, s45
	s_addc_u32 s47, s1, 0
	s_add_u32 s48, s14, s45
	s_addc_u32 s49, s15, 0
	s_add_u32 s45, s45, 0x80
	s_cmp_lg_u32 s45, 0x2f80
	s_waitcnt vmcnt(0)
	s_waitcnt lgkmcnt(0)
	s_barrier
	s_cbranch_scc1 .Lmy_rr_r6b
	v_mfma_f32_16x16x32_bf16 v[128:131], v[166:169], v[222:225], v[128:131]
	v_mfma_f32_16x16x32_bf16 v[100:103], v[166:169], v[226:229], v[100:103]
	v_mfma_f32_16x16x32_bf16 v[132:135], v[178:181], v[222:225], v[132:135]
	v_mfma_f32_16x16x32_bf16 v[140:143], v[178:181], v[226:229], v[140:143]
	v_mfma_f32_16x16x32_bf16 v[136:139], v[214:217], v[222:225], v[136:139]
	v_mfma_f32_16x16x32_bf16 v[150:153], v[214:217], v[226:229], v[150:153]
	v_mfma_f32_16x16x32_bf16 v[84:87], v[218:221], v[222:225], v[84:87]
	v_mfma_f32_16x16x32_bf16 v[154:157], v[218:221], v[226:229], v[154:157]
	s_nop 15
	s_nop 15
	v_lshl_add_u64 v[158:159], s[46:47], 0, v[0:1]
	s_mov_b32 s45, m0
	s_mov_b32 m0, s27
	s_nop 0
	global_load_lds_dwordx4 v[158:159], off
	s_mov_b32 m0, s45
	v_lshl_add_u64 v[158:159], s[48:49], 0, v[0:1]
	s_mov_b32 s45, m0
	s_mov_b32 m0, s28
	s_nop 0
	global_load_lds_dwordx4 v[158:159], off
	s_mov_b32 m0, s45
	v_lshl_add_u64 v[158:159], s[46:47], 0, v[2:3]
	s_mov_b32 s45, m0
	s_mov_b32 m0, s29
	s_nop 0
	global_load_lds_dwordx4 v[158:159], off
	s_mov_b32 m0, s45
	v_lshl_add_u64 v[158:159], s[48:49], 0, v[2:3]
	s_mov_b32 s45, m0
	s_mov_b32 m0, s30
	s_nop 0
	global_load_lds_dwordx4 v[158:159], off
	s_mov_b32 m0, s45
	v_lshl_add_u64 v[158:159], s[46:47], 0, v[4:5]
	s_mov_b32 s45, m0
	s_mov_b32 m0, s31
	s_nop 0
	global_load_lds_dwordx4 v[158:159], off
	s_mov_b32 m0, s45
	v_lshl_add_u64 v[158:159], s[48:49], 0, v[4:5]
	s_mov_b32 s45, m0
	s_mov_b32 m0, s34
	s_nop 0
	global_load_lds_dwordx4 v[158:159], off
	s_mov_b32 m0, s45
	v_lshl_add_u64 v[158:159], s[46:47], 0, v[146:147]
	s_mov_b32 s45, m0
	s_mov_b32 m0, s35
	s_nop 0
	global_load_lds_dwordx4 v[158:159], off
	s_mov_b32 m0, s45
	v_lshl_add_u64 v[158:159], s[48:49], 0, v[146:147]
	s_mov_b32 s45, m0
	s_mov_b32 m0, s36
	s_nop 0
	global_load_lds_dwordx4 v[158:159], off
	s_mov_b32 m0, s45
	ds_read_b128 v[158:161], v8
	ds_read_b128 v[162:165], v9
	ds_read_b128 v[166:169], v11
	ds_read_b128 v[214:217], v10
	ds_read_b128 v[178:181], v12
	ds_read_b128 v[218:221], v13
	ds_read_b128 v[222:225], v14
	ds_read_b128 v[226:229], v15
	s_waitcnt lgkmcnt(3)
	v_mfma_f32_16x16x32_bf16 v[40:43], v[158:161], v[178:181], v[40:43]
	v_mfma_f32_16x16x32_bf16 v[44:47], v[162:165], v[178:181], v[44:47]
	v_mfma_f32_16x16x32_bf16 v[48:51], v[166:169], v[178:181], v[48:51]
	v_mfma_f32_16x16x32_bf16 v[174:177], v[214:217], v[178:181], v[174:177]
	ds_read_b128 v[178:181], v16
	s_waitcnt lgkmcnt(3)
	v_mfma_f32_16x16x32_bf16 v[56:59], v[158:161], v[218:221], v[56:59]
	v_mfma_f32_16x16x32_bf16 v[60:63], v[162:165], v[218:221], v[60:63]
	v_mfma_f32_16x16x32_bf16 v[64:67], v[166:169], v[218:221], v[64:67]
	v_mfma_f32_16x16x32_bf16 v[170:173], v[214:217], v[218:221], v[170:173]
	ds_read_b128 v[218:221], v17
	s_waitcnt lgkmcnt(3)
	v_mfma_f32_16x16x32_bf16 v[72:75], v[158:161], v[222:225], v[72:75]
	v_mfma_f32_16x16x32_bf16 v[76:79], v[162:165], v[222:225], v[76:79]
	v_mfma_f32_16x16x32_bf16 v[80:83], v[166:169], v[222:225], v[80:83]
	v_mfma_f32_16x16x32_bf16 v[32:35], v[214:217], v[222:225], v[32:35]
	ds_read_b128 v[222:225], v18
	s_waitcnt lgkmcnt(3)
	v_mfma_f32_16x16x32_bf16 v[88:91], v[158:161], v[226:229], v[88:91]
	v_mfma_f32_16x16x32_bf16 v[92:95], v[162:165], v[226:229], v[92:95]
	v_mfma_f32_16x16x32_bf16 v[96:99], v[166:169], v[226:229], v[96:99]
	v_mfma_f32_16x16x32_bf16 v[36:39], v[214:217], v[226:229], v[36:39]
	ds_read_b128 v[226:229], v19
	s_waitcnt lgkmcnt(3)
	v_mfma_f32_16x16x32_bf16 v[104:107], v[158:161], v[178:181], v[104:107]
	v_mfma_f32_16x16x32_bf16 v[108:111], v[162:165], v[178:181], v[108:111]
	v_mfma_f32_16x16x32_bf16 v[112:115], v[166:169], v[178:181], v[112:115]
	v_mfma_f32_16x16x32_bf16 v[52:55], v[214:217], v[178:181], v[52:55]
	s_waitcnt lgkmcnt(2)
	v_mfma_f32_16x16x32_bf16 v[116:119], v[158:161], v[218:221], v[116:119]
	v_mfma_f32_16x16x32_bf16 v[120:123], v[162:165], v[218:221], v[120:123]
	v_mfma_f32_16x16x32_bf16 v[124:127], v[166:169], v[218:221], v[124:127]
	v_mfma_f32_16x16x32_bf16 v[68:71], v[214:217], v[218:221], v[68:71]
	s_waitcnt lgkmcnt(1)
	v_mfma_f32_16x16x32_bf16 v[132:135], v[162:165], v[222:225], v[132:135]
	v_mfma_f32_16x16x32_bf16 v[84:87], v[214:217], v[222:225], v[84:87]
	s_waitcnt lgkmcnt(0)
	v_mfma_f32_16x16x32_bf16 v[100:103], v[158:161], v[226:229], v[100:103]
	v_mfma_f32_16x16x32_bf16 v[150:153], v[166:169], v[226:229], v[150:153]
	v_mfma_f32_16x16x32_bf16 v[154:157], v[214:217], v[226:229], v[154:157]
	v_mfma_f32_16x16x32_bf16 v[128:131], v[158:161], v[222:225], v[128:131]
	v_mfma_f32_16x16x32_bf16 v[136:139], v[166:169], v[222:225], v[136:139]
	v_mfma_f32_16x16x32_bf16 v[140:143], v[162:165], v[226:229], v[140:143]
	ds_read_b128 v[158:161], v20
	ds_read_b128 v[162:165], v21
	ds_read_b128 v[166:169], v23
	ds_read_b128 v[214:217], v22
	ds_read_b128 v[178:181], v24
	ds_read_b128 v[218:221], v25
	ds_read_b128 v[222:225], v26
	ds_read_b128 v[226:229], v27
	s_waitcnt lgkmcnt(3)
	v_mfma_f32_16x16x32_bf16 v[40:43], v[158:161], v[178:181], v[40:43]
	v_mfma_f32_16x16x32_bf16 v[44:47], v[162:165], v[178:181], v[44:47]
	v_mfma_f32_16x16x32_bf16 v[48:51], v[166:169], v[178:181], v[48:51]
	v_mfma_f32_16x16x32_bf16 v[174:177], v[214:217], v[178:181], v[174:177]
	ds_read_b128 v[178:181], v28
	s_waitcnt lgkmcnt(3)
	v_mfma_f32_16x16x32_bf16 v[56:59], v[158:161], v[218:221], v[56:59]
	v_mfma_f32_16x16x32_bf16 v[60:63], v[162:165], v[218:221], v[60:63]
	v_mfma_f32_16x16x32_bf16 v[64:67], v[166:169], v[218:221], v[64:67]
	v_mfma_f32_16x16x32_bf16 v[170:173], v[214:217], v[218:221], v[170:173]
	ds_read_b128 v[218:221], v29
	s_waitcnt lgkmcnt(3)
	v_mfma_f32_16x16x32_bf16 v[72:75], v[158:161], v[222:225], v[72:75]
	v_mfma_f32_16x16x32_bf16 v[76:79], v[162:165], v[222:225], v[76:79]
	v_mfma_f32_16x16x32_bf16 v[80:83], v[166:169], v[222:225], v[80:83]
	v_mfma_f32_16x16x32_bf16 v[32:35], v[214:217], v[222:225], v[32:35]
	ds_read_b128 v[222:225], v30
	s_waitcnt lgkmcnt(3)
	v_mfma_f32_16x16x32_bf16 v[88:91], v[158:161], v[226:229], v[88:91]
	v_mfma_f32_16x16x32_bf16 v[92:95], v[162:165], v[226:229], v[92:95]
	v_mfma_f32_16x16x32_bf16 v[96:99], v[166:169], v[226:229], v[96:99]
	v_mfma_f32_16x16x32_bf16 v[36:39], v[214:217], v[226:229], v[36:39]
	ds_read_b128 v[226:229], v31
	s_waitcnt lgkmcnt(3)
	v_mfma_f32_16x16x32_bf16 v[104:107], v[158:161], v[178:181], v[104:107]
	v_mfma_f32_16x16x32_bf16 v[108:111], v[162:165], v[178:181], v[108:111]
	v_mfma_f32_16x16x32_bf16 v[112:115], v[166:169], v[178:181], v[112:115]
	v_mfma_f32_16x16x32_bf16 v[52:55], v[214:217], v[178:181], v[52:55]
	s_waitcnt lgkmcnt(2)
	v_mfma_f32_16x16x32_bf16 v[116:119], v[158:161], v[218:221], v[116:119]
	v_mfma_f32_16x16x32_bf16 v[120:123], v[162:165], v[218:221], v[120:123]
	v_mfma_f32_16x16x32_bf16 v[124:127], v[166:169], v[218:221], v[124:127]
	v_mfma_f32_16x16x32_bf16 v[68:71], v[214:217], v[218:221], v[68:71]
	s_waitcnt lgkmcnt(1)
	v_mfma_f32_16x16x32_bf16 v[132:135], v[162:165], v[222:225], v[132:135]
	v_mfma_f32_16x16x32_bf16 v[84:87], v[214:217], v[222:225], v[84:87]
	s_waitcnt lgkmcnt(0)
	v_mfma_f32_16x16x32_bf16 v[100:103], v[158:161], v[226:229], v[100:103]
	v_mfma_f32_16x16x32_bf16 v[150:153], v[166:169], v[226:229], v[150:153]
	v_mfma_f32_16x16x32_bf16 v[154:157], v[214:217], v[226:229], v[154:157]
	v_mfma_f32_16x16x32_bf16 v[128:131], v[158:161], v[222:225], v[128:131]
	v_mfma_f32_16x16x32_bf16 v[136:139], v[166:169], v[222:225], v[136:139]
	v_mfma_f32_16x16x32_bf16 v[140:143], v[162:165], v[226:229], v[140:143]
	s_add_u32 s0, s0, 0x2f80
	s_addc_u32 s1, s1, 0
	s_add_u32 s14, s14, 0x2f80
	s_waitcnt vmcnt(0)
	s_barrier
	s_addc_u32 s15, s15, 0
	v_lshl_add_u64 v[158:159], s[0:1], 0, v[0:1]
	s_mov_b32 s45, m0
	s_mov_b32 m0, s38
	s_nop 0
	global_load_lds_dwordx4 v[158:159], off
	s_mov_b32 m0, s45
	v_lshl_add_u64 v[158:159], s[14:15], 0, v[0:1]
	s_mov_b32 s38, m0
	s_mov_b32 m0, s37
	s_nop 0
	global_load_lds_dwordx4 v[158:159], off
	s_mov_b32 m0, s38
	v_lshl_add_u64 v[158:159], s[0:1], 0, v[2:3]
	s_mov_b32 s37, m0
	s_mov_b32 m0, s39
	s_nop 0
	global_load_lds_dwordx4 v[158:159], off
	s_mov_b32 m0, s37
	v_lshl_add_u64 v[158:159], s[14:15], 0, v[2:3]
	s_mov_b32 s37, m0
	s_mov_b32 m0, s40
	s_nop 0
	global_load_lds_dwordx4 v[158:159], off
	s_mov_b32 m0, s37
	v_lshl_add_u64 v[158:159], s[0:1], 0, v[4:5]
	s_mov_b32 s37, m0
	s_mov_b32 m0, s41
	s_nop 0
	global_load_lds_dwordx4 v[158:159], off
	s_mov_b32 m0, s37
	v_lshl_add_u64 v[158:159], s[14:15], 0, v[4:5]
	s_mov_b32 s37, m0
	s_mov_b32 m0, s42
	s_nop 0
	global_load_lds_dwordx4 v[158:159], off
	s_mov_b32 m0, s37
	v_lshl_add_u64 v[158:159], s[0:1], 0, v[146:147]
	s_mov_b32 s0, m0
	s_mov_b32 m0, s43
	s_nop 0
	global_load_lds_dwordx4 v[158:159], off
	s_mov_b32 m0, s0
	v_lshl_add_u64 v[158:159], s[14:15], 0, v[146:147]
	s_mov_b32 s0, m0
	s_mov_b32 m0, s44
	s_nop 0
	global_load_lds_dwordx4 v[158:159], off
	s_mov_b32 m0, s0
	ds_read_b128 v[158:161], v7 offset:32768
	ds_read_b128 v[162:165], v7 offset:34816
	ds_read_b128 v[166:169], v7 offset:36864
	ds_read_b128 v[214:217], v7 offset:38912
	ds_read_b128 v[178:181], v6
	ds_read_b128 v[218:221], v6 offset:2048
	ds_read_b128 v[222:225], v6 offset:4096
	ds_read_b128 v[226:229], v6 offset:6144
	s_waitcnt lgkmcnt(3)
	v_mfma_f32_16x16x32_bf16 v[40:43], v[158:161], v[178:181], v[40:43]
	v_mfma_f32_16x16x32_bf16 v[44:47], v[162:165], v[178:181], v[44:47]
	v_mfma_f32_16x16x32_bf16 v[48:51], v[166:169], v[178:181], v[48:51]
	v_mfma_f32_16x16x32_bf16 v[174:177], v[214:217], v[178:181], v[174:177]
	ds_read_b128 v[178:181], v6 offset:8192
	s_waitcnt lgkmcnt(3)
	v_mfma_f32_16x16x32_bf16 v[56:59], v[158:161], v[218:221], v[56:59]
	v_mfma_f32_16x16x32_bf16 v[60:63], v[162:165], v[218:221], v[60:63]
	v_mfma_f32_16x16x32_bf16 v[64:67], v[166:169], v[218:221], v[64:67]
	v_mfma_f32_16x16x32_bf16 v[170:173], v[214:217], v[218:221], v[170:173]
	ds_read_b128 v[218:221], v6 offset:10240
	s_waitcnt lgkmcnt(3)
	v_mfma_f32_16x16x32_bf16 v[72:75], v[158:161], v[222:225], v[72:75]
	v_mfma_f32_16x16x32_bf16 v[76:79], v[162:165], v[222:225], v[76:79]
	v_mfma_f32_16x16x32_bf16 v[80:83], v[166:169], v[222:225], v[80:83]
	v_mfma_f32_16x16x32_bf16 v[32:35], v[214:217], v[222:225], v[32:35]
	ds_read_b128 v[222:225], v6 offset:12288
	s_waitcnt lgkmcnt(3)
	v_mfma_f32_16x16x32_bf16 v[88:91], v[158:161], v[226:229], v[88:91]
	v_mfma_f32_16x16x32_bf16 v[92:95], v[162:165], v[226:229], v[92:95]
	v_mfma_f32_16x16x32_bf16 v[96:99], v[166:169], v[226:229], v[96:99]
	v_mfma_f32_16x16x32_bf16 v[36:39], v[214:217], v[226:229], v[36:39]
	ds_read_b128 v[226:229], v6 offset:14336
	s_waitcnt lgkmcnt(3)
	v_mfma_f32_16x16x32_bf16 v[104:107], v[158:161], v[178:181], v[104:107]
	v_mfma_f32_16x16x32_bf16 v[108:111], v[162:165], v[178:181], v[108:111]
	v_mfma_f32_16x16x32_bf16 v[112:115], v[166:169], v[178:181], v[112:115]
	v_mfma_f32_16x16x32_bf16 v[52:55], v[214:217], v[178:181], v[52:55]
	s_waitcnt lgkmcnt(2)
	v_mfma_f32_16x16x32_bf16 v[116:119], v[158:161], v[218:221], v[116:119]
	v_mfma_f32_16x16x32_bf16 v[120:123], v[162:165], v[218:221], v[120:123]
	v_mfma_f32_16x16x32_bf16 v[124:127], v[166:169], v[218:221], v[124:127]
	v_mfma_f32_16x16x32_bf16 v[68:71], v[214:217], v[218:221], v[68:71]
	s_waitcnt lgkmcnt(1)
	v_mfma_f32_16x16x32_bf16 v[132:135], v[162:165], v[222:225], v[132:135]
	v_mfma_f32_16x16x32_bf16 v[84:87], v[214:217], v[222:225], v[84:87]
	s_waitcnt lgkmcnt(0)
	v_mfma_f32_16x16x32_bf16 v[100:103], v[158:161], v[226:229], v[100:103]
	v_mfma_f32_16x16x32_bf16 v[150:153], v[166:169], v[226:229], v[150:153]
	v_mfma_f32_16x16x32_bf16 v[154:157], v[214:217], v[226:229], v[154:157]
	v_mfma_f32_16x16x32_bf16 v[128:131], v[158:161], v[222:225], v[128:131]
	v_mfma_f32_16x16x32_bf16 v[136:139], v[166:169], v[222:225], v[136:139]
	v_mfma_f32_16x16x32_bf16 v[140:143], v[162:165], v[226:229], v[140:143]
	ds_read_b128 v[158:161], v7 offset:33792
	ds_read_b128 v[162:165], v7 offset:35840
	ds_read_b128 v[166:169], v7 offset:37888
	ds_read_b128 v[214:217], v7 offset:39936
	ds_read_b128 v[178:181], v6 offset:1024
	ds_read_b128 v[218:221], v6 offset:3072
	ds_read_b128 v[222:225], v6 offset:5120
	ds_read_b128 v[226:229], v6 offset:7168
	s_waitcnt lgkmcnt(3)
	v_mfma_f32_16x16x32_bf16 v[40:43], v[158:161], v[178:181], v[40:43]
	v_mfma_f32_16x16x32_bf16 v[44:47], v[162:165], v[178:181], v[44:47]
	v_mfma_f32_16x16x32_bf16 v[48:51], v[166:169], v[178:181], v[48:51]
	v_mfma_f32_16x16x32_bf16 v[174:177], v[214:217], v[178:181], v[174:177]
	ds_read_b128 v[178:181], v6 offset:9216
	s_waitcnt lgkmcnt(3)
	v_mfma_f32_16x16x32_bf16 v[56:59], v[158:161], v[218:221], v[56:59]
	v_mfma_f32_16x16x32_bf16 v[60:63], v[162:165], v[218:221], v[60:63]
	v_mfma_f32_16x16x32_bf16 v[64:67], v[166:169], v[218:221], v[64:67]
	v_mfma_f32_16x16x32_bf16 v[170:173], v[214:217], v[218:221], v[170:173]
	ds_read_b128 v[218:221], v6 offset:11264
	s_waitcnt lgkmcnt(3)
	v_mfma_f32_16x16x32_bf16 v[72:75], v[158:161], v[222:225], v[72:75]
	v_mfma_f32_16x16x32_bf16 v[76:79], v[162:165], v[222:225], v[76:79]
	v_mfma_f32_16x16x32_bf16 v[80:83], v[166:169], v[222:225], v[80:83]
	v_mfma_f32_16x16x32_bf16 v[32:35], v[214:217], v[222:225], v[32:35]
	ds_read_b128 v[222:225], v6 offset:13312
	s_waitcnt lgkmcnt(3)
	v_mfma_f32_16x16x32_bf16 v[88:91], v[158:161], v[226:229], v[88:91]
	v_mfma_f32_16x16x32_bf16 v[92:95], v[162:165], v[226:229], v[92:95]
	v_mfma_f32_16x16x32_bf16 v[96:99], v[166:169], v[226:229], v[96:99]
	v_mfma_f32_16x16x32_bf16 v[36:39], v[214:217], v[226:229], v[36:39]
	ds_read_b128 v[226:229], v6 offset:15360
	s_waitcnt lgkmcnt(3)
	v_mfma_f32_16x16x32_bf16 v[104:107], v[158:161], v[178:181], v[104:107]
	v_mfma_f32_16x16x32_bf16 v[108:111], v[162:165], v[178:181], v[108:111]
	v_mfma_f32_16x16x32_bf16 v[112:115], v[166:169], v[178:181], v[112:115]
	v_mfma_f32_16x16x32_bf16 v[52:55], v[214:217], v[178:181], v[52:55]
	s_waitcnt lgkmcnt(2)
	v_mfma_f32_16x16x32_bf16 v[116:119], v[158:161], v[218:221], v[116:119]
	v_mfma_f32_16x16x32_bf16 v[120:123], v[162:165], v[218:221], v[120:123]
	v_mfma_f32_16x16x32_bf16 v[124:127], v[166:169], v[218:221], v[124:127]
	v_mfma_f32_16x16x32_bf16 v[68:71], v[214:217], v[218:221], v[68:71]
	s_waitcnt lgkmcnt(1)
	v_mfma_f32_16x16x32_bf16 v[132:135], v[162:165], v[222:225], v[132:135]
	v_mfma_f32_16x16x32_bf16 v[84:87], v[214:217], v[222:225], v[84:87]
	s_waitcnt lgkmcnt(0)
	v_mfma_f32_16x16x32_bf16 v[100:103], v[158:161], v[226:229], v[100:103]
	v_mfma_f32_16x16x32_bf16 v[150:153], v[166:169], v[226:229], v[150:153]
	v_mfma_f32_16x16x32_bf16 v[154:157], v[214:217], v[226:229], v[154:157]
	v_mfma_f32_16x16x32_bf16 v[128:131], v[158:161], v[222:225], v[128:131]
	v_mfma_f32_16x16x32_bf16 v[136:139], v[166:169], v[222:225], v[136:139]
	v_mfma_f32_16x16x32_bf16 v[140:143], v[162:165], v[226:229], v[140:143]
	s_waitcnt vmcnt(0)
	s_barrier
	v_lshl_add_u64 v[6:7], s[16:17], 0, v[0:1]
	s_mov_b32 s0, m0
	s_mov_b32 m0, s27
	s_nop 0
	global_load_lds_dwordx4 v[6:7], off
	s_mov_b32 m0, s0
	v_lshl_add_u64 v[0:1], s[18:19], 0, v[0:1]
	s_mov_b32 s0, m0
	s_mov_b32 m0, s28
	s_nop 0
	global_load_lds_dwordx4 v[0:1], off
	s_mov_b32 m0, s0
	v_lshl_add_u64 v[0:1], s[16:17], 0, v[2:3]
	s_mov_b32 s0, m0
	s_mov_b32 m0, s29
	s_nop 0
	global_load_lds_dwordx4 v[0:1], off
	s_mov_b32 m0, s0
	v_lshl_add_u64 v[0:1], s[18:19], 0, v[2:3]
	s_mov_b32 s0, m0
	s_mov_b32 m0, s30
	s_nop 0
	global_load_lds_dwordx4 v[0:1], off
	s_mov_b32 m0, s0
	v_lshl_add_u64 v[0:1], s[16:17], 0, v[4:5]
	s_mov_b32 s0, m0
	s_mov_b32 m0, s31
	s_nop 0
	global_load_lds_dwordx4 v[0:1], off
	s_mov_b32 m0, s0
	v_lshl_add_u64 v[0:1], s[18:19], 0, v[4:5]
	s_mov_b32 s0, m0
	s_mov_b32 m0, s34
	s_nop 0
	global_load_lds_dwordx4 v[0:1], off
	s_mov_b32 m0, s0
	v_lshl_add_u64 v[0:1], s[16:17], 0, v[146:147]
	s_mov_b32 s0, m0
	s_mov_b32 m0, s35
	s_nop 0
	global_load_lds_dwordx4 v[0:1], off
	s_mov_b32 m0, s0
	v_lshl_add_u64 v[0:1], s[18:19], 0, v[146:147]
	s_mov_b32 s0, m0
	s_mov_b32 m0, s36
	s_nop 0
	global_load_lds_dwordx4 v[0:1], off
	s_mov_b32 m0, s0
	ds_read_b128 v[0:3], v8
	ds_read_b128 v[4:7], v9
	ds_read_b128 v[158:161], v11
	ds_read_b128 v[8:11], v10
	ds_read_b128 v[162:165], v12
	ds_read_b128 v[166:169], v13
	ds_read_b128 v[178:181], v14
	ds_read_b128 v[12:15], v15
	s_waitcnt lgkmcnt(3)
	v_mfma_f32_16x16x32_bf16 v[40:43], v[0:3], v[162:165], v[40:43]
	v_mfma_f32_16x16x32_bf16 v[44:47], v[4:7], v[162:165], v[44:47]
	v_mfma_f32_16x16x32_bf16 v[48:51], v[158:161], v[162:165], v[48:51]
	v_mfma_f32_16x16x32_bf16 v[162:165], v[8:11], v[162:165], v[174:177]
	s_nop 2
	ds_read_b128 v[174:177], v16
	s_waitcnt lgkmcnt(3)
	v_mfma_f32_16x16x32_bf16 v[56:59], v[0:3], v[166:169], v[56:59]
	v_mfma_f32_16x16x32_bf16 v[60:63], v[4:7], v[166:169], v[60:63]
	v_mfma_f32_16x16x32_bf16 v[64:67], v[158:161], v[166:169], v[64:67]
	v_mfma_f32_16x16x32_bf16 v[166:169], v[8:11], v[166:169], v[170:173]
	s_nop 2
	ds_read_b128 v[170:173], v17
	s_waitcnt lgkmcnt(3)
	v_mfma_f32_16x16x32_bf16 v[72:75], v[0:3], v[178:181], v[72:75]
	v_mfma_f32_16x16x32_bf16 v[76:79], v[4:7], v[178:181], v[76:79]
	v_mfma_f32_16x16x32_bf16 v[80:83], v[158:161], v[178:181], v[80:83]
	v_mfma_f32_16x16x32_bf16 v[32:35], v[8:11], v[178:181], v[32:35]
	ds_read_b128 v[178:181], v18
	s_waitcnt lgkmcnt(3)
	v_mfma_f32_16x16x32_bf16 v[214:217], v[0:3], v[12:15], v[88:91]
	v_mfma_f32_16x16x32_bf16 v[218:221], v[4:7], v[12:15], v[92:95]
	v_mfma_f32_16x16x32_bf16 v[222:225], v[158:161], v[12:15], v[96:99]
	v_mfma_f32_16x16x32_bf16 v[12:15], v[8:11], v[12:15], v[36:39]
	ds_read_b128 v[16:19], v19
	s_waitcnt lgkmcnt(3)
	v_mfma_f32_16x16x32_bf16 v[36:39], v[0:3], v[174:177], v[104:107]
	v_mfma_f32_16x16x32_bf16 v[226:229], v[4:7], v[174:177], v[108:111]
	v_mfma_f32_16x16x32_bf16 v[112:115], v[158:161], v[174:177], v[112:115]
	s_waitcnt lgkmcnt(2)
	v_mfma_f32_16x16x32_bf16 v[116:119], v[0:3], v[170:173], v[116:119]
	v_mfma_f32_16x16x32_bf16 v[120:123], v[4:7], v[170:173], v[120:123]
	v_mfma_f32_16x16x32_bf16 v[124:127], v[158:161], v[170:173], v[124:127]
	s_waitcnt lgkmcnt(1)
	v_mfma_f32_16x16x32_bf16 v[128:131], v[0:3], v[178:181], v[128:131]
	v_mfma_f32_16x16x32_bf16 v[132:135], v[4:7], v[178:181], v[132:135]
	s_waitcnt lgkmcnt(0)
	v_mfma_f32_16x16x32_bf16 v[0:3], v[0:3], v[16:19], v[100:103]
	v_mfma_f32_16x16x32_bf16 v[4:7], v[4:7], v[16:19], v[140:143]
	v_mfma_f32_16x16x32_bf16 v[140:143], v[158:161], v[16:19], v[150:153]
	v_mfma_f32_16x16x32_bf16 v[150:153], v[8:11], v[16:19], v[154:157]
	v_mfma_f32_16x16x32_bf16 v[174:177], v[8:11], v[174:177], v[52:55]
	v_mfma_f32_16x16x32_bf16 v[170:173], v[8:11], v[170:173], v[68:71]
	v_mfma_f32_16x16x32_bf16 v[136:139], v[158:161], v[178:181], v[136:139]
	v_mfma_f32_16x16x32_bf16 v[178:181], v[8:11], v[178:181], v[84:87]
	ds_read_b128 v[8:11], v20
	ds_read_b128 v[154:157], v21
	ds_read_b128 v[158:161], v23
	ds_read_b128 v[230:233], v22
	ds_read_b128 v[16:19], v24
	ds_read_b128 v[20:23], v25
	ds_read_b128 v[52:55], v26
	ds_read_b128 v[24:27], v27
	s_waitcnt lgkmcnt(3)
	v_mfma_f32_16x16x32_bf16 v[234:237], v[8:11], v[16:19], v[40:43]
	v_mfma_f32_16x16x32_bf16 v[238:241], v[154:157], v[16:19], v[44:47]
	v_mfma_f32_16x16x32_bf16 v[242:245], v[158:161], v[16:19], v[48:51]
	v_mfma_f32_16x16x32_bf16 v[162:165], v[230:233], v[16:19], v[162:165]
	ds_read_b128 v[16:19], v28
	s_waitcnt lgkmcnt(3)
	v_mfma_f32_16x16x32_bf16 v[108:111], v[8:11], v[20:23], v[56:59]
	v_mfma_f32_16x16x32_bf16 v[104:107], v[154:157], v[20:23], v[60:63]
	v_mfma_f32_16x16x32_bf16 v[100:103], v[158:161], v[20:23], v[64:67]
	v_mfma_f32_16x16x32_bf16 v[96:99], v[230:233], v[20:23], v[166:169]
	ds_read_b128 v[20:23], v29
	s_waitcnt lgkmcnt(3)
	v_mfma_f32_16x16x32_bf16 v[92:95], v[8:11], v[52:55], v[72:75]
	v_mfma_f32_16x16x32_bf16 v[88:91], v[154:157], v[52:55], v[76:79]
	v_mfma_f32_16x16x32_bf16 v[84:87], v[158:161], v[52:55], v[80:83]
	v_mfma_f32_16x16x32_bf16 v[80:83], v[230:233], v[52:55], v[32:35]
	ds_read_b128 v[166:169], v30
	s_waitcnt lgkmcnt(3)
	v_mfma_f32_16x16x32_bf16 v[76:79], v[8:11], v[24:27], v[214:217]
	v_mfma_f32_16x16x32_bf16 v[72:75], v[154:157], v[24:27], v[218:221]
	v_mfma_f32_16x16x32_bf16 v[68:71], v[158:161], v[24:27], v[222:225]
	v_mfma_f32_16x16x32_bf16 v[64:67], v[230:233], v[24:27], v[12:15]
	ds_read_b128 v[214:217], v31
	s_waitcnt lgkmcnt(3)
	v_mfma_f32_16x16x32_bf16 v[60:63], v[8:11], v[16:19], v[36:39]
	v_mfma_f32_16x16x32_bf16 v[56:59], v[154:157], v[16:19], v[226:229]
	v_mfma_f32_16x16x32_bf16 v[52:55], v[158:161], v[16:19], v[112:115]
	v_mfma_f32_16x16x32_bf16 v[48:51], v[230:233], v[16:19], v[174:177]
	s_waitcnt lgkmcnt(2)
	v_mfma_f32_16x16x32_bf16 v[44:47], v[8:11], v[20:23], v[116:119]
	v_mfma_f32_16x16x32_bf16 v[40:43], v[154:157], v[20:23], v[120:123]
	v_mfma_f32_16x16x32_bf16 v[36:39], v[158:161], v[20:23], v[124:127]
	v_mfma_f32_16x16x32_bf16 v[32:35], v[230:233], v[20:23], v[170:173]
	s_waitcnt lgkmcnt(1)
	v_mfma_f32_16x16x32_bf16 v[28:31], v[8:11], v[166:169], v[128:131]
	v_mfma_f32_16x16x32_bf16 v[24:27], v[154:157], v[166:169], v[132:135]
	v_mfma_f32_16x16x32_bf16 v[20:23], v[158:161], v[166:169], v[136:139]
	v_mfma_f32_16x16x32_bf16 v[16:19], v[230:233], v[166:169], v[178:181]
	s_waitcnt lgkmcnt(0)
	v_mfma_f32_16x16x32_bf16 v[12:15], v[8:11], v[214:217], v[0:3]
	v_mfma_f32_16x16x32_bf16 v[8:11], v[154:157], v[214:217], v[4:7]
	v_mfma_f32_16x16x32_bf16 v[4:7], v[158:161], v[214:217], v[140:143]
	v_mfma_f32_16x16x32_bf16 v[0:3], v[230:233], v[214:217], v[150:153]
	v_mov_b32_e32 v145, v184
	s_waitcnt vmcnt(0)
	s_barrier
	s_lshl_b32 s16, s13, 8
	s_lshl_b32 s14, s12, 8
	v_and_b32_e32 v151, 15, v145
	v_ashrrev_i32_e32 v112, 1, v145
	v_and_b32_e32 v153, 0xffffff80, v112
	v_or_b32_e32 v112, s16, v151
	v_add_u32_e32 v112, v112, v153
	v_ashrrev_i32_e32 v113, 31, v112
	v_lshlrev_b64 v[112:113], 13, v[112:113]
	v_bfe_u32 v150, v145, 6, 2
	v_lshl_add_u64 v[112:113], s[4:5], 0, v[112:113]
	s_ashr_i32 s15, s14, 31
	v_bfe_u32 v152, v145, 4, 2
	v_lshl_add_u64 v[112:113], s[14:15], 2, v[112:113]
	v_lshlrev_b32_e32 v146, 8, v150
	v_lshl_add_u64 v[112:113], v[112:113], 0, v[146:147]
	v_lshlrev_b32_e32 v146, 4, v152
	v_lshl_add_u64 v[154:155], v[112:113], 0, v[146:147]
	global_load_dwordx4 v[120:123], v[154:155], off offset:192
	global_load_dwordx4 v[128:131], v[154:155], off offset:128
	global_load_dwordx4 v[136:139], v[154:155], off offset:64
	global_load_dwordx4 v[140:143], v[154:155], off
	v_add_co_u32_e32 v112, vcc, s66, v154
	v_lshlrev_b32_e32 v158, 2, v152
	s_nop 0
	v_addc_co_u32_e32 v113, vcc, 0, v155, vcc
	global_load_dwordx4 v[132:135], v[112:113], off
	global_load_dwordx4 v[124:127], v[112:113], off offset:64
	global_load_dwordx4 v[116:119], v[112:113], off offset:128
	v_cmp_lt_i32_e32 vcc, v188, v186
	global_load_dwordx4 v[112:115], v[112:113], off offset:192
	v_cmp_eq_u32_e64 s[0:1], 0, v152
	v_cndmask_b32_e32 v146, v185, v188, vcc
	v_cmp_lt_i32_e32 vcc, v187, v186
	v_lshlrev_b32_e32 v149, 2, v146
	v_lshlrev_b32_e32 v157, 6, v150
	v_cndmask_b32_e32 v156, v185, v187, vcc
	v_lshlrev_b32_e32 v146, 2, v156
	v_or_b32_e32 v156, v153, v151
	v_add_u32_e32 v152, s16, v156
	v_ashrrev_i32_e32 v153, 31, v152
	v_lshl_or_b32 v182, v150, 10, v204
	v_or3_b32 v150, v157, s14, v158
	v_lshlrev_b64 v[158:159], 13, v[152:153]
	v_ashrrev_i32_e32 v151, 31, v150
	v_lshlrev_b64 v[160:161], 12, v[152:153]
	v_lshl_add_u64 v[158:159], s[4:5], 0, v[158:159]
	v_lshl_add_u64 v[160:161], s[6:7], 0, v[160:161]
	v_lshl_add_u64 v[166:167], v[150:151], 2, v[158:159]
	v_lshl_add_u64 v[168:169], v[150:151], 1, v[160:161]
	s_waitcnt vmcnt(7)
	v_pk_add_f32 v[158:159], v[162:163], v[120:121]
	s_waitcnt vmcnt(6)
	v_pk_add_f32 v[120:121], v[242:243], v[128:129]
	s_waitcnt vmcnt(5)
	v_pk_add_f32 v[128:129], v[238:239], v[136:137]
	s_waitcnt vmcnt(4)
	v_pk_add_f32 v[136:137], v[234:235], v[140:141]
	v_pk_add_f32 v[160:161], v[164:165], v[122:123]
	v_pk_add_f32 v[122:123], v[244:245], v[130:131]
	v_pk_add_f32 v[130:131], v[240:241], v[138:139]
	v_pk_add_f32 v[138:139], v[236:237], v[142:143]
	v_pk_mul_f32 v[172:173], v[128:129], v[128:129]
	v_pk_mul_f32 v[178:179], v[136:137], v[136:137]
	v_pk_mul_f32 v[162:163], v[120:121], v[120:121]
	v_pk_mul_f32 v[174:175], v[130:131], v[130:131]
	v_cvt_pk_bf16_f32 v176, v136, v137
	v_pk_mul_f32 v[180:181], v[138:139], v[138:139]
	global_store_dwordx4 v[166:167], v[136:139], off
	v_add_f32_e32 v153, v172, v173
	v_add_f32_e32 v157, v178, v179
	v_pk_mul_f32 v[136:137], v[158:159], v[158:159]
	v_pk_mul_f32 v[164:165], v[122:123], v[122:123]
	v_cvt_pk_bf16_f32 v177, v138, v139
	v_pk_mul_f32 v[138:139], v[160:161], v[160:161]
	v_add_f32_e32 v162, v162, v163
	v_add_f32_e32 v136, v136, v137
	v_add_f32_e32 v137, v174, v153
	v_add_f32_e32 v153, v180, v157
	v_add_f32_e32 v157, v164, v162
	v_add_f32_e32 v136, v138, v136
	v_add_f32_e32 v137, v175, v137
	v_add_f32_e32 v138, v181, v153
	v_add_f32_e32 v153, v165, v157
	v_add_f32_e32 v137, v138, v137
	v_add_f32_e32 v137, v137, v153
	v_add_f32_e32 v136, v139, v136
	v_add_f32_e32 v136, v137, v136
	ds_bpermute_b32 v137, v149, v136
	v_cvt_pk_bf16_f32 v170, v128, v129
	v_cvt_pk_bf16_f32 v171, v130, v131
	v_cvt_pk_bf16_f32 v142, v120, v121
	global_store_dwordx2 v[168:169], v[176:177], off
	global_store_dwordx4 v[166:167], v[128:131], off offset:64
	global_store_dwordx2 v[168:169], v[170:171], off offset:32
	global_store_dwordx4 v[166:167], v[120:123], off offset:128
	v_cvt_pk_bf16_f32 v140, v158, v159
	v_cvt_pk_bf16_f32 v141, v160, v161
	s_waitcnt lgkmcnt(0)
	v_add_f32_e32 v120, v136, v137
	ds_bpermute_b32 v121, v146, v120
	v_cvt_pk_bf16_f32 v143, v122, v123
	v_lshl_add_u32 v153, v156, 2, v182
	global_store_dwordx2 v[168:169], v[142:143], off offset:64
	global_store_dwordx4 v[166:167], v[158:161], off offset:192
	global_store_dwordx2 v[168:169], v[140:141], off offset:96
	s_and_saveexec_b64 s[14:15], s[0:1]
	s_cbranch_execz .LBB0_254
	s_waitcnt lgkmcnt(0)
	v_add_f32_e32 v120, v120, v121
	ds_write_b32 v153, v120

.LBB0_565:
	s_mul_i32 s20, s23, 0x300000
	s_mul_hi_i32 s21, s23, 0x300000
	s_add_u32 s20, s26, s20
	s_addc_u32 s21, s27, s21
	s_mul_hi_i32 s23, s22, 0x300000
	s_mul_i32 s22, s22, 0x300000
	s_add_u32 s22, s38, s22
	s_addc_u32 s23, s39, s23
	s_add_u32 s62, s0, 0x80
	v_and_b32_e32 v8, 48, v7
	v_lshlrev_b32_e32 v9, 6, v7
	v_lshlrev_b32_e32 v7, 2, v7
	s_addc_u32 s63, s1, 0
	v_and_b32_e32 v10, 0x3c0, v9
	v_and_b32_e32 v149, 32, v7
	s_add_u32 s64, s14, 0x80
	v_or_b32_e32 v145, v10, v8
	v_bitop3_b32 v12, v10, v149, v8 bitop3:0x36
	s_waitcnt vmcnt(0)
	s_barrier
	v_lshlrev_b32_e32 v8, 13, v6
	s_addc_u32 s65, s15, 0
	s_add_i32 s52, s42, 0x10000
	v_lshl_add_u64 v[6:7], s[62:63], 0, v[0:1]
	s_mov_b32 s53, m0
	s_mov_b32 m0, s52
	s_nop 0
	global_load_lds_dwordx4 v[6:7], off
	s_mov_b32 m0, s53
	s_add_i32 s51, s42, 0x18000
	v_lshl_add_u64 v[6:7], s[64:65], 0, v[0:1]
	s_mov_b32 s53, m0
	s_mov_b32 m0, s51
	s_nop 0
	global_load_lds_dwordx4 v[6:7], off
	s_mov_b32 m0, s53
	v_lshl_add_u64 v[6:7], s[62:63], 0, v[2:3]
	s_add_i32 s53, s42, 0x12000
	s_mov_b32 s54, m0
	s_mov_b32 m0, s53
	s_nop 0
	global_load_lds_dwordx4 v[6:7], off
	s_mov_b32 m0, s54
	v_lshl_add_u64 v[6:7], s[64:65], 0, v[2:3]
	s_add_i32 s54, s42, 0x1a000
	s_mov_b32 s55, m0
	s_mov_b32 m0, s54
	s_nop 0
	global_load_lds_dwordx4 v[6:7], off
	s_mov_b32 m0, s55
	v_lshl_add_u64 v[6:7], s[62:63], 0, v[4:5]
	s_add_i32 s55, s42, 0x14000
	s_mov_b32 s58, m0
	s_mov_b32 m0, s55
	s_nop 0
	global_load_lds_dwordx4 v[6:7], off
	s_mov_b32 m0, s58
	v_lshl_add_u64 v[6:7], s[64:65], 0, v[4:5]
	s_add_i32 s58, s42, 0x1c000
	s_mov_b32 s68, m0
	s_mov_b32 m0, s58
	s_nop 0
	global_load_lds_dwordx4 v[6:7], off
	s_mov_b32 m0, s68
	v_lshl_add_u64 v[6:7], s[62:63], 0, v[146:147]
	s_add_i32 s62, s42, 0x16000
	s_mov_b32 s63, m0
	s_mov_b32 m0, s62
	s_nop 0
	global_load_lds_dwordx4 v[6:7], off
	s_mov_b32 m0, s63
	v_lshl_add_u64 v[6:7], s[64:65], 0, v[146:147]
	s_add_i32 s63, s42, 0x1e000
	s_mov_b32 s64, m0
	s_mov_b32 m0, s63
	s_nop 0
	global_load_lds_dwordx4 v[6:7], off
	s_mov_b32 m0, s64
	v_and_b32_e32 v182, 0xffffc000, v9
	v_or_b32_e32 v183, 0x800, v182
	v_or_b32_e32 v189, 0x1000, v182
	v_or_b32_e32 v199, 0x1800, v182
	v_or_b32_e32 v200, 0x2000, v182
	v_or_b32_e32 v201, 0x2800, v182
	v_or_b32_e32 v203, 0x3000, v182
	v_or_b32_e32 v206, 0x3800, v182
	s_movk_i32 s64, 0x6000
	v_and_or_b32 v7, v8, s64, v12
	ds_read_b128 v[8:11], v7 offset:32768
	v_or_b32_e32 v6, v12, v182
	ds_read_b128 v[12:15], v7 offset:34816
	ds_read_b128 v[16:19], v7 offset:36864
	ds_read_b128 v[24:27], v7 offset:38912
	ds_read_b128 v[20:23], v6
	ds_read_b128 v[28:31], v6 offset:2048
	ds_read_b128 v[32:35], v6 offset:4096
	ds_read_b128 v[36:39], v6 offset:6144
	s_waitcnt lgkmcnt(3)
	v_mfma_f32_16x16x32_bf16 v[40:43], v[8:11], v[20:23], 0
	v_mfma_f32_16x16x32_bf16 v[44:47], v[12:15], v[20:23], 0
	v_mfma_f32_16x16x32_bf16 v[48:51], v[16:19], v[20:23], 0
	v_mfma_f32_16x16x32_bf16 v[20:23], v[24:27], v[20:23], 0
	ds_read_b128 v[52:55], v6 offset:8192
	s_waitcnt lgkmcnt(3)
	v_mfma_f32_16x16x32_bf16 v[56:59], v[8:11], v[28:31], 0
	v_mfma_f32_16x16x32_bf16 v[60:63], v[12:15], v[28:31], 0
	v_mfma_f32_16x16x32_bf16 v[64:67], v[16:19], v[28:31], 0
	v_mfma_f32_16x16x32_bf16 v[28:31], v[24:27], v[28:31], 0
	ds_read_b128 v[68:71], v6 offset:10240
	s_waitcnt lgkmcnt(3)
	v_mfma_f32_16x16x32_bf16 v[72:75], v[8:11], v[32:35], 0
	v_mfma_f32_16x16x32_bf16 v[76:79], v[12:15], v[32:35], 0
	v_mfma_f32_16x16x32_bf16 v[80:83], v[16:19], v[32:35], 0
	v_mfma_f32_16x16x32_bf16 v[32:35], v[24:27], v[32:35], 0
	ds_read_b128 v[84:87], v6 offset:12288
	s_waitcnt lgkmcnt(3)
	v_mfma_f32_16x16x32_bf16 v[88:91], v[8:11], v[36:39], 0
	v_mfma_f32_16x16x32_bf16 v[92:95], v[12:15], v[36:39], 0
	v_mfma_f32_16x16x32_bf16 v[96:99], v[16:19], v[36:39], 0
	v_mfma_f32_16x16x32_bf16 v[36:39], v[24:27], v[36:39], 0
	ds_read_b128 v[100:103], v6 offset:14336
	s_waitcnt lgkmcnt(3)
	v_mfma_f32_16x16x32_bf16 v[104:107], v[8:11], v[52:55], 0
	v_mfma_f32_16x16x32_bf16 v[108:111], v[12:15], v[52:55], 0
	v_mfma_f32_16x16x32_bf16 v[112:115], v[16:19], v[52:55], 0
	v_mfma_f32_16x16x32_bf16 v[52:55], v[24:27], v[52:55], 0
	s_waitcnt lgkmcnt(2)
	v_mfma_f32_16x16x32_bf16 v[116:119], v[8:11], v[68:71], 0
	v_mfma_f32_16x16x32_bf16 v[120:123], v[12:15], v[68:71], 0
	v_mfma_f32_16x16x32_bf16 v[124:127], v[16:19], v[68:71], 0
	v_mfma_f32_16x16x32_bf16 v[68:71], v[24:27], v[68:71], 0
	s_waitcnt lgkmcnt(1)
	v_mfma_f32_16x16x32_bf16 v[128:131], v[8:11], v[84:87], 0
	v_mfma_f32_16x16x32_bf16 v[132:135], v[12:15], v[84:87], 0
	v_mfma_f32_16x16x32_bf16 v[136:139], v[16:19], v[84:87], 0
	v_mfma_f32_16x16x32_bf16 v[84:87], v[24:27], v[84:87], 0
	s_waitcnt lgkmcnt(0)
	v_mfma_f32_16x16x32_bf16 v[8:11], v[8:11], v[100:103], 0
	v_mfma_f32_16x16x32_bf16 v[12:15], v[12:15], v[100:103], 0
	v_mfma_f32_16x16x32_bf16 v[16:19], v[16:19], v[100:103], 0
	v_mfma_f32_16x16x32_bf16 v[24:27], v[24:27], v[100:103], 0
	ds_read_b128 v[100:103], v7 offset:33792
	ds_read_b128 v[140:143], v7 offset:35840
	ds_read_b128 v[150:153], v7 offset:37888
	ds_read_b128 v[158:161], v7 offset:39936
	ds_read_b128 v[154:157], v6 offset:1024
	ds_read_b128 v[162:165], v6 offset:3072
	ds_read_b128 v[166:169], v6 offset:5120
	ds_read_b128 v[170:173], v6 offset:7168
	s_waitcnt lgkmcnt(3)
	v_mfma_f32_16x16x32_bf16 v[40:43], v[100:103], v[154:157], v[40:43]
	v_mfma_f32_16x16x32_bf16 v[44:47], v[140:143], v[154:157], v[44:47]
	v_mfma_f32_16x16x32_bf16 v[48:51], v[150:153], v[154:157], v[48:51]
	v_mfma_f32_16x16x32_bf16 v[20:23], v[158:161], v[154:157], v[20:23]
	ds_read_b128 v[154:157], v6 offset:9216
	s_waitcnt lgkmcnt(3)
	v_mfma_f32_16x16x32_bf16 v[56:59], v[100:103], v[162:165], v[56:59]
	v_mfma_f32_16x16x32_bf16 v[60:63], v[140:143], v[162:165], v[60:63]
	v_mfma_f32_16x16x32_bf16 v[64:67], v[150:153], v[162:165], v[64:67]
	v_mfma_f32_16x16x32_bf16 v[28:31], v[158:161], v[162:165], v[28:31]
	ds_read_b128 v[162:165], v6 offset:11264
	s_waitcnt lgkmcnt(3)
	v_mfma_f32_16x16x32_bf16 v[72:75], v[100:103], v[166:169], v[72:75]
	v_mfma_f32_16x16x32_bf16 v[76:79], v[140:143], v[166:169], v[76:79]
	v_mfma_f32_16x16x32_bf16 v[80:83], v[150:153], v[166:169], v[80:83]
	v_mfma_f32_16x16x32_bf16 v[32:35], v[158:161], v[166:169], v[32:35]
	ds_read_b128 v[166:169], v6 offset:13312
	s_waitcnt lgkmcnt(3)
	v_mfma_f32_16x16x32_bf16 v[88:91], v[100:103], v[170:173], v[88:91]
	v_mfma_f32_16x16x32_bf16 v[92:95], v[140:143], v[170:173], v[92:95]
	v_mfma_f32_16x16x32_bf16 v[96:99], v[150:153], v[170:173], v[96:99]
	v_mfma_f32_16x16x32_bf16 v[36:39], v[158:161], v[170:173], v[36:39]
	ds_read_b128 v[170:173], v6 offset:15360
	s_waitcnt lgkmcnt(3)
	v_mfma_f32_16x16x32_bf16 v[104:107], v[100:103], v[154:157], v[104:107]
	v_mfma_f32_16x16x32_bf16 v[108:111], v[140:143], v[154:157], v[108:111]
	v_mfma_f32_16x16x32_bf16 v[112:115], v[150:153], v[154:157], v[112:115]
	v_mfma_f32_16x16x32_bf16 v[52:55], v[158:161], v[154:157], v[52:55]
	s_waitcnt lgkmcnt(2)
	v_mfma_f32_16x16x32_bf16 v[116:119], v[100:103], v[162:165], v[116:119]
	v_mfma_f32_16x16x32_bf16 v[120:123], v[140:143], v[162:165], v[120:123]
	v_mfma_f32_16x16x32_bf16 v[124:127], v[150:153], v[162:165], v[124:127]
	v_mfma_f32_16x16x32_bf16 v[68:71], v[158:161], v[162:165], v[68:71]
	s_waitcnt lgkmcnt(1)
	v_mfma_f32_16x16x32_bf16 v[128:131], v[100:103], v[166:169], v[128:131]
	v_mfma_f32_16x16x32_bf16 v[132:135], v[140:143], v[166:169], v[132:135]
	v_mfma_f32_16x16x32_bf16 v[136:139], v[150:153], v[166:169], v[136:139]
	v_mfma_f32_16x16x32_bf16 v[84:87], v[158:161], v[166:169], v[84:87]
	s_waitcnt lgkmcnt(0)
	v_mfma_f32_16x16x32_bf16 v[100:103], v[100:103], v[170:173], v[8:11]
	v_mfma_f32_16x16x32_bf16 v[150:153], v[150:153], v[170:173], v[16:19]
	v_mfma_f32_16x16x32_bf16 v[24:27], v[158:161], v[170:173], v[24:27]
	v_mfma_f32_16x16x32_bf16 v[140:143], v[140:143], v[170:173], v[12:15]
	s_add_u32 s64, s0, 0x100
	s_addc_u32 s65, s1, 0
	s_add_u32 s68, s14, 0x100
	s_waitcnt vmcnt(0)
	s_barrier
	s_addc_u32 s69, s15, 0
	v_lshl_add_u64 v[8:9], s[64:65], 0, v[0:1]
	s_mov_b32 s70, m0
	s_mov_b32 m0, s42
	s_nop 0
	global_load_lds_dwordx4 v[8:9], off
	s_mov_b32 m0, s70
	v_lshl_add_u64 v[8:9], s[68:69], 0, v[0:1]
	s_mov_b32 s70, m0
	s_mov_b32 m0, s43
	s_nop 0
	global_load_lds_dwordx4 v[8:9], off
	s_mov_b32 m0, s70
	v_lshl_add_u64 v[8:9], s[64:65], 0, v[2:3]
	s_mov_b32 s70, m0
	s_mov_b32 m0, s44
	s_nop 0
	global_load_lds_dwordx4 v[8:9], off
	s_mov_b32 m0, s70
	v_lshl_add_u64 v[8:9], s[68:69], 0, v[2:3]
	s_mov_b32 s70, m0
	s_mov_b32 m0, s45
	s_nop 0
	global_load_lds_dwordx4 v[8:9], off
	s_mov_b32 m0, s70
	v_lshl_add_u64 v[8:9], s[64:65], 0, v[4:5]
	s_mov_b32 s70, m0
	s_mov_b32 m0, s46
	s_nop 0
	global_load_lds_dwordx4 v[8:9], off
	s_mov_b32 m0, s70
	v_lshl_add_u64 v[8:9], s[68:69], 0, v[4:5]
	s_mov_b32 s70, m0
	s_mov_b32 m0, s47
	s_nop 0
	global_load_lds_dwordx4 v[8:9], off
	s_mov_b32 m0, s70
	v_lshl_add_u64 v[8:9], s[64:65], 0, v[146:147]
	s_mov_b32 s64, m0
	s_mov_b32 m0, s49
	s_nop 0
	global_load_lds_dwordx4 v[8:9], off
	s_mov_b32 m0, s64
	v_lshl_add_u64 v[8:9], s[68:69], 0, v[146:147]
	s_mov_b32 s64, m0
	s_mov_b32 m0, s50
	s_nop 0
	global_load_lds_dwordx4 v[8:9], off
	s_mov_b32 m0, s64
	v_or_b32_e32 v8, 0x18000, v7
	v_or_b32_e32 v9, 0x18800, v7
	v_or_b32_e32 v11, 0x19000, v7
	v_or_b32_e32 v10, 0x19800, v7
	ds_read_b128 v[154:157], v8
	ds_read_b128 v[158:161], v9
	ds_read_b128 v[162:165], v11
	ds_read_b128 v[166:169], v10
	v_bitop3_b32 v207, v145, s33, v149 bitop3:0xde
	v_add_u32_e32 v12, v207, v182
	ds_read_b128 v[16:19], v12
	v_add_u32_e32 v13, v207, v183
	v_add_u32_e32 v14, v207, v189
	v_add_u32_e32 v15, v207, v199
	ds_read_b128 v[170:173], v13
	ds_read_b128 v[174:177], v14
	ds_read_b128 v[178:181], v15
	s_waitcnt lgkmcnt(3)
	v_mfma_f32_16x16x32_bf16 v[40:43], v[154:157], v[16:19], v[40:43]
	v_mfma_f32_16x16x32_bf16 v[44:47], v[158:161], v[16:19], v[44:47]
	v_mfma_f32_16x16x32_bf16 v[48:51], v[162:165], v[16:19], v[48:51]
	v_mfma_f32_16x16x32_bf16 v[214:217], v[166:169], v[16:19], v[20:23]
	v_add_u32_e32 v16, v207, v200
	v_add_u32_e32 v17, v207, v201
	v_add_u32_e32 v18, v207, v203
	v_add_u32_e32 v19, v207, v206
	ds_read_b128 v[20:23], v16
	s_waitcnt lgkmcnt(3)
	v_mfma_f32_16x16x32_bf16 v[56:59], v[154:157], v[170:173], v[56:59]
	v_mfma_f32_16x16x32_bf16 v[60:63], v[158:161], v[170:173], v[60:63]
	v_mfma_f32_16x16x32_bf16 v[64:67], v[162:165], v[170:173], v[64:67]
	v_mfma_f32_16x16x32_bf16 v[170:173], v[166:169], v[170:173], v[28:31]
	s_nop 2
	ds_read_b128 v[28:31], v17
	s_waitcnt lgkmcnt(3)
	v_mfma_f32_16x16x32_bf16 v[72:75], v[154:157], v[174:177], v[72:75]
	v_mfma_f32_16x16x32_bf16 v[76:79], v[158:161], v[174:177], v[76:79]
	v_mfma_f32_16x16x32_bf16 v[80:83], v[162:165], v[174:177], v[80:83]
	v_mfma_f32_16x16x32_bf16 v[32:35], v[166:169], v[174:177], v[32:35]
	ds_read_b128 v[174:177], v18
	s_waitcnt lgkmcnt(3)
	v_mfma_f32_16x16x32_bf16 v[88:91], v[154:157], v[178:181], v[88:91]
	v_mfma_f32_16x16x32_bf16 v[92:95], v[158:161], v[178:181], v[92:95]
	v_mfma_f32_16x16x32_bf16 v[96:99], v[162:165], v[178:181], v[96:99]
	v_mfma_f32_16x16x32_bf16 v[36:39], v[166:169], v[178:181], v[36:39]
	ds_read_b128 v[178:181], v19
	s_waitcnt lgkmcnt(3)
	v_mfma_f32_16x16x32_bf16 v[104:107], v[154:157], v[20:23], v[104:107]
	v_mfma_f32_16x16x32_bf16 v[108:111], v[158:161], v[20:23], v[108:111]
	v_mfma_f32_16x16x32_bf16 v[112:115], v[162:165], v[20:23], v[112:115]
	v_mfma_f32_16x16x32_bf16 v[52:55], v[166:169], v[20:23], v[52:55]
	s_waitcnt lgkmcnt(2)
	v_mfma_f32_16x16x32_bf16 v[116:119], v[154:157], v[28:31], v[116:119]
	v_mfma_f32_16x16x32_bf16 v[120:123], v[158:161], v[28:31], v[120:123]
	v_mfma_f32_16x16x32_bf16 v[124:127], v[162:165], v[28:31], v[124:127]
	v_mfma_f32_16x16x32_bf16 v[68:71], v[166:169], v[28:31], v[68:71]
	s_waitcnt lgkmcnt(1)
	v_mfma_f32_16x16x32_bf16 v[128:131], v[154:157], v[174:177], v[128:131]
	v_mfma_f32_16x16x32_bf16 v[132:135], v[158:161], v[174:177], v[132:135]
	v_mfma_f32_16x16x32_bf16 v[84:87], v[166:169], v[174:177], v[84:87]
	s_waitcnt lgkmcnt(0)
	v_mfma_f32_16x16x32_bf16 v[100:103], v[154:157], v[178:181], v[100:103]
	v_mfma_f32_16x16x32_bf16 v[150:153], v[162:165], v[178:181], v[150:153]
	v_mfma_f32_16x16x32_bf16 v[154:157], v[166:169], v[178:181], v[24:27]
	v_mfma_f32_16x16x32_bf16 v[136:139], v[162:165], v[174:177], v[136:139]
	v_mfma_f32_16x16x32_bf16 v[140:143], v[158:161], v[178:181], v[140:143]
	v_or_b32_e32 v20, 0x18400, v7
	v_or_b32_e32 v21, 0x18c00, v7
	v_or_b32_e32 v23, 0x19400, v7
	v_or_b32_e32 v22, 0x19c00, v7
	ds_read_b128 v[158:161], v20
	ds_read_b128 v[162:165], v21
	ds_read_b128 v[166:169], v23
	ds_read_b128 v[174:177], v22
	s_mov_b32 s64, 0x10400
	v_bitop3_b32 v145, v145, s64, v149 bitop3:0xde
	v_add_u32_e32 v24, v145, v182
	ds_read_b128 v[28:31], v24
	v_add_u32_e32 v25, v145, v183
	v_add_u32_e32 v26, v145, v189
	v_add_u32_e32 v27, v145, v199
	ds_read_b128 v[178:181], v25
	ds_read_b128 v[218:221], v26
	ds_read_b128 v[222:225], v27
	s_waitcnt lgkmcnt(3)
	v_mfma_f32_16x16x32_bf16 v[40:43], v[158:161], v[28:31], v[40:43]
	v_mfma_f32_16x16x32_bf16 v[44:47], v[162:165], v[28:31], v[44:47]
	v_mfma_f32_16x16x32_bf16 v[48:51], v[166:169], v[28:31], v[48:51]
	v_mfma_f32_16x16x32_bf16 v[214:217], v[174:177], v[28:31], v[214:217]
	v_add_u32_e32 v28, v145, v200
	v_add_u32_e32 v29, v145, v201
	v_add_u32_e32 v30, v145, v203
	v_add_u32_e32 v31, v145, v206
	ds_read_b128 v[226:229], v28
	s_waitcnt lgkmcnt(3)
	v_mfma_f32_16x16x32_bf16 v[56:59], v[158:161], v[178:181], v[56:59]
	v_mfma_f32_16x16x32_bf16 v[60:63], v[162:165], v[178:181], v[60:63]
	v_mfma_f32_16x16x32_bf16 v[64:67], v[166:169], v[178:181], v[64:67]
	v_mfma_f32_16x16x32_bf16 v[170:173], v[174:177], v[178:181], v[170:173]
	ds_read_b128 v[178:181], v29
	s_waitcnt lgkmcnt(3)
	v_mfma_f32_16x16x32_bf16 v[72:75], v[158:161], v[218:221], v[72:75]
	v_mfma_f32_16x16x32_bf16 v[76:79], v[162:165], v[218:221], v[76:79]
	v_mfma_f32_16x16x32_bf16 v[80:83], v[166:169], v[218:221], v[80:83]
	v_mfma_f32_16x16x32_bf16 v[32:35], v[174:177], v[218:221], v[32:35]
	ds_read_b128 v[218:221], v30
	s_waitcnt lgkmcnt(3)
	v_mfma_f32_16x16x32_bf16 v[88:91], v[158:161], v[222:225], v[88:91]
	v_mfma_f32_16x16x32_bf16 v[92:95], v[162:165], v[222:225], v[92:95]
	v_mfma_f32_16x16x32_bf16 v[96:99], v[166:169], v[222:225], v[96:99]
	v_mfma_f32_16x16x32_bf16 v[36:39], v[174:177], v[222:225], v[36:39]
	ds_read_b128 v[222:225], v31
	s_waitcnt lgkmcnt(3)
	v_mfma_f32_16x16x32_bf16 v[104:107], v[158:161], v[226:229], v[104:107]
	v_mfma_f32_16x16x32_bf16 v[108:111], v[162:165], v[226:229], v[108:111]
	v_mfma_f32_16x16x32_bf16 v[112:115], v[166:169], v[226:229], v[112:115]
	v_mfma_f32_16x16x32_bf16 v[52:55], v[174:177], v[226:229], v[52:55]
	s_waitcnt lgkmcnt(2)
	v_mfma_f32_16x16x32_bf16 v[116:119], v[158:161], v[178:181], v[116:119]
	v_mfma_f32_16x16x32_bf16 v[120:123], v[162:165], v[178:181], v[120:123]
	v_mfma_f32_16x16x32_bf16 v[124:127], v[166:169], v[178:181], v[124:127]
	v_mfma_f32_16x16x32_bf16 v[68:71], v[174:177], v[178:181], v[68:71]
	s_waitcnt lgkmcnt(1)
	v_mfma_f32_16x16x32_bf16 v[132:135], v[162:165], v[218:221], v[132:135]
	v_mfma_f32_16x16x32_bf16 v[84:87], v[174:177], v[218:221], v[84:87]
	s_waitcnt lgkmcnt(0)
	v_mfma_f32_16x16x32_bf16 v[100:103], v[158:161], v[222:225], v[100:103]
	v_mfma_f32_16x16x32_bf16 v[150:153], v[166:169], v[222:225], v[150:153]
	v_mfma_f32_16x16x32_bf16 v[154:157], v[174:177], v[222:225], v[154:157]
	v_mfma_f32_16x16x32_bf16 v[128:131], v[158:161], v[218:221], v[128:131]
	v_mfma_f32_16x16x32_bf16 v[136:139], v[166:169], v[218:221], v[136:139]
	v_mfma_f32_16x16x32_bf16 v[140:143], v[162:165], v[222:225], v[140:143]
	s_add_u32 s64, s0, 0x180
	s_addc_u32 s65, s1, 0
	s_add_u32 s68, s14, 0x180
	s_waitcnt vmcnt(0)
	s_barrier
	s_addc_u32 s69, s15, 0
	v_lshl_add_u64 v[158:159], s[64:65], 0, v[0:1]
	s_mov_b32 s70, m0
	s_mov_b32 m0, s52
	s_nop 0
	global_load_lds_dwordx4 v[158:159], off
	s_mov_b32 m0, s70
	v_lshl_add_u64 v[158:159], s[68:69], 0, v[0:1]
	s_mov_b32 s70, m0
	s_mov_b32 m0, s51
	s_nop 0
	global_load_lds_dwordx4 v[158:159], off
	s_mov_b32 m0, s70
	v_lshl_add_u64 v[158:159], s[64:65], 0, v[2:3]
	s_mov_b32 s70, m0
	s_mov_b32 m0, s53
	s_nop 0
	global_load_lds_dwordx4 v[158:159], off
	s_mov_b32 m0, s70
	v_lshl_add_u64 v[158:159], s[68:69], 0, v[2:3]
	s_mov_b32 s70, m0
	s_mov_b32 m0, s54
	s_nop 0
	global_load_lds_dwordx4 v[158:159], off
	s_mov_b32 m0, s70
	v_lshl_add_u64 v[158:159], s[64:65], 0, v[4:5]
	s_mov_b32 s70, m0
	s_mov_b32 m0, s55
	s_nop 0
	global_load_lds_dwordx4 v[158:159], off
	s_mov_b32 m0, s70
	v_lshl_add_u64 v[158:159], s[68:69], 0, v[4:5]
	s_mov_b32 s70, m0
	s_mov_b32 m0, s58
	s_nop 0
	global_load_lds_dwordx4 v[158:159], off
	s_mov_b32 m0, s70
	v_lshl_add_u64 v[158:159], s[64:65], 0, v[146:147]
	s_mov_b32 s64, m0
	s_mov_b32 m0, s62
	s_nop 0
	global_load_lds_dwordx4 v[158:159], off
	s_mov_b32 m0, s64
	v_lshl_add_u64 v[158:159], s[68:69], 0, v[146:147]
	s_mov_b32 s64, m0
	s_mov_b32 m0, s63
	s_nop 0
	global_load_lds_dwordx4 v[158:159], off
	s_mov_b32 m0, s64
	ds_read_b128 v[158:161], v7 offset:32768
	ds_read_b128 v[162:165], v7 offset:34816
	ds_read_b128 v[166:169], v7 offset:36864
	ds_read_b128 v[178:181], v7 offset:38912
	ds_read_b128 v[174:177], v6
	ds_read_b128 v[218:221], v6 offset:2048
	ds_read_b128 v[222:225], v6 offset:4096
	ds_read_b128 v[226:229], v6 offset:6144
	s_waitcnt lgkmcnt(3)
	v_mfma_f32_16x16x32_bf16 v[40:43], v[158:161], v[174:177], v[40:43]
	v_mfma_f32_16x16x32_bf16 v[44:47], v[162:165], v[174:177], v[44:47]
	v_mfma_f32_16x16x32_bf16 v[48:51], v[166:169], v[174:177], v[48:51]
	v_mfma_f32_16x16x32_bf16 v[174:177], v[178:181], v[174:177], v[214:217]
	s_nop 2
	ds_read_b128 v[214:217], v6 offset:8192
	s_waitcnt lgkmcnt(3)
	v_mfma_f32_16x16x32_bf16 v[56:59], v[158:161], v[218:221], v[56:59]
	v_mfma_f32_16x16x32_bf16 v[60:63], v[162:165], v[218:221], v[60:63]
	v_mfma_f32_16x16x32_bf16 v[64:67], v[166:169], v[218:221], v[64:67]
	v_mfma_f32_16x16x32_bf16 v[170:173], v[178:181], v[218:221], v[170:173]
	ds_read_b128 v[218:221], v6 offset:10240
	s_waitcnt lgkmcnt(3)
	v_mfma_f32_16x16x32_bf16 v[72:75], v[158:161], v[222:225], v[72:75]
	v_mfma_f32_16x16x32_bf16 v[76:79], v[162:165], v[222:225], v[76:79]
	v_mfma_f32_16x16x32_bf16 v[80:83], v[166:169], v[222:225], v[80:83]
	v_mfma_f32_16x16x32_bf16 v[32:35], v[178:181], v[222:225], v[32:35]
	ds_read_b128 v[222:225], v6 offset:12288
	s_waitcnt lgkmcnt(3)
	v_mfma_f32_16x16x32_bf16 v[88:91], v[158:161], v[226:229], v[88:91]
	v_mfma_f32_16x16x32_bf16 v[92:95], v[162:165], v[226:229], v[92:95]
	v_mfma_f32_16x16x32_bf16 v[96:99], v[166:169], v[226:229], v[96:99]
	v_mfma_f32_16x16x32_bf16 v[36:39], v[178:181], v[226:229], v[36:39]
	ds_read_b128 v[226:229], v6 offset:14336
	s_waitcnt lgkmcnt(3)
	v_mfma_f32_16x16x32_bf16 v[104:107], v[158:161], v[214:217], v[104:107]
	v_mfma_f32_16x16x32_bf16 v[108:111], v[162:165], v[214:217], v[108:111]
	v_mfma_f32_16x16x32_bf16 v[112:115], v[166:169], v[214:217], v[112:115]
	v_mfma_f32_16x16x32_bf16 v[52:55], v[178:181], v[214:217], v[52:55]
	s_waitcnt lgkmcnt(2)
	v_mfma_f32_16x16x32_bf16 v[116:119], v[158:161], v[218:221], v[116:119]
	v_mfma_f32_16x16x32_bf16 v[120:123], v[162:165], v[218:221], v[120:123]
	v_mfma_f32_16x16x32_bf16 v[124:127], v[166:169], v[218:221], v[124:127]
	v_mfma_f32_16x16x32_bf16 v[68:71], v[178:181], v[218:221], v[68:71]
	s_waitcnt lgkmcnt(1)
	v_mfma_f32_16x16x32_bf16 v[132:135], v[162:165], v[222:225], v[132:135]
	v_mfma_f32_16x16x32_bf16 v[84:87], v[178:181], v[222:225], v[84:87]
	s_waitcnt lgkmcnt(0)
	v_mfma_f32_16x16x32_bf16 v[100:103], v[158:161], v[226:229], v[100:103]
	v_mfma_f32_16x16x32_bf16 v[150:153], v[166:169], v[226:229], v[150:153]
	v_mfma_f32_16x16x32_bf16 v[154:157], v[178:181], v[226:229], v[154:157]
	v_mfma_f32_16x16x32_bf16 v[128:131], v[158:161], v[222:225], v[128:131]
	v_mfma_f32_16x16x32_bf16 v[136:139], v[166:169], v[222:225], v[136:139]
	v_mfma_f32_16x16x32_bf16 v[140:143], v[162:165], v[226:229], v[140:143]
	ds_read_b128 v[158:161], v7 offset:33792
	ds_read_b128 v[162:165], v7 offset:35840
	ds_read_b128 v[166:169], v7 offset:37888
	ds_read_b128 v[214:217], v7 offset:39936
	ds_read_b128 v[178:181], v6 offset:1024
	ds_read_b128 v[218:221], v6 offset:3072
	ds_read_b128 v[222:225], v6 offset:5120
	ds_read_b128 v[226:229], v6 offset:7168
	s_waitcnt lgkmcnt(3)
	v_mfma_f32_16x16x32_bf16 v[40:43], v[158:161], v[178:181], v[40:43]
	v_mfma_f32_16x16x32_bf16 v[44:47], v[162:165], v[178:181], v[44:47]
	v_mfma_f32_16x16x32_bf16 v[48:51], v[166:169], v[178:181], v[48:51]
	v_mfma_f32_16x16x32_bf16 v[174:177], v[214:217], v[178:181], v[174:177]
	ds_read_b128 v[178:181], v6 offset:9216
	s_waitcnt lgkmcnt(3)
	v_mfma_f32_16x16x32_bf16 v[56:59], v[158:161], v[218:221], v[56:59]
	v_mfma_f32_16x16x32_bf16 v[60:63], v[162:165], v[218:221], v[60:63]
	v_mfma_f32_16x16x32_bf16 v[64:67], v[166:169], v[218:221], v[64:67]
	v_mfma_f32_16x16x32_bf16 v[170:173], v[214:217], v[218:221], v[170:173]
	ds_read_b128 v[218:221], v6 offset:11264
	s_waitcnt lgkmcnt(3)
	v_mfma_f32_16x16x32_bf16 v[72:75], v[158:161], v[222:225], v[72:75]
	v_mfma_f32_16x16x32_bf16 v[76:79], v[162:165], v[222:225], v[76:79]
	v_mfma_f32_16x16x32_bf16 v[80:83], v[166:169], v[222:225], v[80:83]
	v_mfma_f32_16x16x32_bf16 v[32:35], v[214:217], v[222:225], v[32:35]
	ds_read_b128 v[222:225], v6 offset:13312
	s_waitcnt lgkmcnt(3)
	v_mfma_f32_16x16x32_bf16 v[88:91], v[158:161], v[226:229], v[88:91]
	v_mfma_f32_16x16x32_bf16 v[92:95], v[162:165], v[226:229], v[92:95]
	v_mfma_f32_16x16x32_bf16 v[96:99], v[166:169], v[226:229], v[96:99]
	v_mfma_f32_16x16x32_bf16 v[36:39], v[214:217], v[226:229], v[36:39]
	ds_read_b128 v[226:229], v6 offset:15360
	s_waitcnt lgkmcnt(3)
	v_mfma_f32_16x16x32_bf16 v[104:107], v[158:161], v[178:181], v[104:107]
	v_mfma_f32_16x16x32_bf16 v[108:111], v[162:165], v[178:181], v[108:111]
	v_mfma_f32_16x16x32_bf16 v[112:115], v[166:169], v[178:181], v[112:115]
	v_mfma_f32_16x16x32_bf16 v[52:55], v[214:217], v[178:181], v[52:55]
	s_waitcnt lgkmcnt(2)
	v_mfma_f32_16x16x32_bf16 v[116:119], v[158:161], v[218:221], v[116:119]
	v_mfma_f32_16x16x32_bf16 v[120:123], v[162:165], v[218:221], v[120:123]
	v_mfma_f32_16x16x32_bf16 v[124:127], v[166:169], v[218:221], v[124:127]
	v_mfma_f32_16x16x32_bf16 v[68:71], v[214:217], v[218:221], v[68:71]
	s_waitcnt lgkmcnt(1)
	v_mfma_f32_16x16x32_bf16 v[132:135], v[162:165], v[222:225], v[132:135]
	v_mfma_f32_16x16x32_bf16 v[84:87], v[214:217], v[222:225], v[84:87]
	s_waitcnt lgkmcnt(0)
	v_mfma_f32_16x16x32_bf16 v[100:103], v[158:161], v[226:229], v[100:103]
	v_mfma_f32_16x16x32_bf16 v[150:153], v[166:169], v[226:229], v[150:153]
	v_mfma_f32_16x16x32_bf16 v[154:157], v[214:217], v[226:229], v[154:157]
	v_mfma_f32_16x16x32_bf16 v[128:131], v[158:161], v[222:225], v[128:131]
	v_mfma_f32_16x16x32_bf16 v[136:139], v[166:169], v[222:225], v[136:139]
	v_mfma_f32_16x16x32_bf16 v[140:143], v[162:165], v[226:229], v[140:143]
	s_add_u32 s64, s0, 0x200
	s_addc_u32 s65, s1, 0
	s_add_u32 s68, s14, 0x200
	s_waitcnt vmcnt(0)
	s_barrier
	s_addc_u32 s69, s15, 0
	s_mov_b32 s70, 0x280
	ds_read_b128 v[158:161], v8
	ds_read_b128 v[162:165], v12
	ds_read_b128 v[166:169], v9
	ds_read_b128 v[178:181], v13
	ds_read_b128 v[214:217], v11
	ds_read_b128 v[218:221], v10
	ds_read_b128 v[222:225], v14
	ds_read_b128 v[226:229], v15
	s_branch .Lmy_rot_r_r6a

.Lmy_rot_r_r6a:
	s_waitcnt lgkmcnt(6)
	v_mfma_f32_16x16x32_bf16 v[40:43], v[158:161], v[162:165], v[40:43]
	s_waitcnt lgkmcnt(5)
	v_mfma_f32_16x16x32_bf16 v[44:47], v[166:169], v[162:165], v[44:47]
	s_waitcnt lgkmcnt(4)
	s_mov_b32 m0, s42
	v_mfma_f32_16x16x32_bf16 v[56:59], v[158:161], v[178:181], v[56:59]
	global_load_lds_dwordx4 v0, s[64:65]
	v_mfma_f32_16x16x32_bf16 v[60:63], v[166:169], v[178:181], v[60:63]
	s_waitcnt lgkmcnt(3)
	v_mfma_f32_16x16x32_bf16 v[48:51], v[214:217], v[162:165], v[48:51]
	v_mfma_f32_16x16x32_bf16 v[64:67], v[214:217], v[178:181], v[64:67]
	s_waitcnt lgkmcnt(2)
	s_mov_b32 m0, s43
	v_mfma_f32_16x16x32_bf16 v[174:177], v[218:221], v[162:165], v[174:177]
	global_load_lds_dwordx4 v0, s[68:69]
	ds_read_b128 v[162:165], v16
	v_mfma_f32_16x16x32_bf16 v[170:173], v[218:221], v[178:181], v[170:173]
	ds_read_b128 v[178:181], v17
	s_waitcnt lgkmcnt(3)
	v_mfma_f32_16x16x32_bf16 v[72:75], v[158:161], v[222:225], v[72:75]
	v_mfma_f32_16x16x32_bf16 v[76:79], v[166:169], v[222:225], v[76:79]
	s_mov_b32 m0, s44
	v_mfma_f32_16x16x32_bf16 v[80:83], v[214:217], v[222:225], v[80:83]
	global_load_lds_dwordx4 v2, s[64:65]
	v_mfma_f32_16x16x32_bf16 v[32:35], v[218:221], v[222:225], v[32:35]
	ds_read_b128 v[222:225], v18
	s_waitcnt lgkmcnt(3)
	v_mfma_f32_16x16x32_bf16 v[88:91], v[158:161], v[226:229], v[88:91]
	v_mfma_f32_16x16x32_bf16 v[92:95], v[166:169], v[226:229], v[92:95]
	s_mov_b32 m0, s45
	v_mfma_f32_16x16x32_bf16 v[96:99], v[214:217], v[226:229], v[96:99]
	global_load_lds_dwordx4 v2, s[68:69]
	v_mfma_f32_16x16x32_bf16 v[36:39], v[218:221], v[226:229], v[36:39]
	ds_read_b128 v[226:229], v19
	s_waitcnt lgkmcnt(3)
	v_mfma_f32_16x16x32_bf16 v[108:111], v[166:169], v[162:165], v[108:111]
	s_waitcnt lgkmcnt(2)
	v_mfma_f32_16x16x32_bf16 v[120:123], v[166:169], v[178:181], v[120:123]
	s_waitcnt lgkmcnt(1)
	s_mov_b32 m0, s46
	v_mfma_f32_16x16x32_bf16 v[132:135], v[166:169], v[222:225], v[132:135]
	global_load_lds_dwordx4 v4, s[64:65]
	s_waitcnt lgkmcnt(0)
	v_mfma_f32_16x16x32_bf16 v[140:143], v[166:169], v[226:229], v[140:143]
	ds_read_b128 v[166:169], v20
	v_mfma_f32_16x16x32_bf16 v[104:107], v[158:161], v[162:165], v[104:107]
	v_mfma_f32_16x16x32_bf16 v[116:119], v[158:161], v[178:181], v[116:119]
	s_mov_b32 m0, s47
	v_mfma_f32_16x16x32_bf16 v[128:131], v[158:161], v[222:225], v[128:131]
	global_load_lds_dwordx4 v4, s[68:69]
	v_mfma_f32_16x16x32_bf16 v[100:103], v[158:161], v[226:229], v[100:103]
	ds_read_b128 v[158:161], v24
	v_mfma_f32_16x16x32_bf16 v[124:127], v[214:217], v[178:181], v[124:127]
	v_mfma_f32_16x16x32_bf16 v[68:71], v[218:221], v[178:181], v[68:71]
	ds_read_b128 v[178:181], v21
	s_mov_b32 m0, s49
	v_mfma_f32_16x16x32_bf16 v[112:115], v[214:217], v[162:165], v[112:115]
	global_load_lds_dwordx4 v146, s[64:65]
	v_mfma_f32_16x16x32_bf16 v[52:55], v[218:221], v[162:165], v[52:55]
	ds_read_b128 v[162:165], v25
	v_mfma_f32_16x16x32_bf16 v[136:139], v[214:217], v[222:225], v[136:139]
	v_mfma_f32_16x16x32_bf16 v[84:87], v[218:221], v[222:225], v[84:87]
	ds_read_b128 v[222:225], v26
	s_mov_b32 m0, s50
	v_mfma_f32_16x16x32_bf16 v[150:153], v[214:217], v[226:229], v[150:153]
	global_load_lds_dwordx4 v146, s[68:69]
	ds_read_b128 v[214:217], v23
	v_mfma_f32_16x16x32_bf16 v[154:157], v[218:221], v[226:229], v[154:157]
	ds_read_b128 v[218:221], v22
	ds_read_b128 v[226:229], v27
	s_waitcnt lgkmcnt(6)
	v_mfma_f32_16x16x32_bf16 v[40:43], v[166:169], v[158:161], v[40:43]
	s_waitcnt lgkmcnt(5)
	v_mfma_f32_16x16x32_bf16 v[44:47], v[178:181], v[158:161], v[44:47]
	s_waitcnt lgkmcnt(4)
	v_mfma_f32_16x16x32_bf16 v[56:59], v[166:169], v[162:165], v[56:59]
	v_mfma_f32_16x16x32_bf16 v[60:63], v[178:181], v[162:165], v[60:63]
	s_waitcnt lgkmcnt(3)
	v_mfma_f32_16x16x32_bf16 v[72:75], v[166:169], v[222:225], v[72:75]
	v_mfma_f32_16x16x32_bf16 v[76:79], v[178:181], v[222:225], v[76:79]
	s_waitcnt lgkmcnt(2)
	v_mfma_f32_16x16x32_bf16 v[48:51], v[214:217], v[158:161], v[48:51]
	s_waitcnt lgkmcnt(1)
	v_mfma_f32_16x16x32_bf16 v[174:177], v[218:221], v[158:161], v[174:177]
	ds_read_b128 v[158:161], v28
	v_mfma_f32_16x16x32_bf16 v[64:67], v[214:217], v[162:165], v[64:67]
	v_mfma_f32_16x16x32_bf16 v[170:173], v[218:221], v[162:165], v[170:173]
	ds_read_b128 v[162:165], v29
	v_mfma_f32_16x16x32_bf16 v[80:83], v[214:217], v[222:225], v[80:83]
	v_mfma_f32_16x16x32_bf16 v[32:35], v[218:221], v[222:225], v[32:35]
	ds_read_b128 v[222:225], v30
	s_waitcnt lgkmcnt(3)
	v_mfma_f32_16x16x32_bf16 v[88:91], v[166:169], v[226:229], v[88:91]
	v_mfma_f32_16x16x32_bf16 v[92:95], v[178:181], v[226:229], v[92:95]
	v_mfma_f32_16x16x32_bf16 v[96:99], v[214:217], v[226:229], v[96:99]
	v_mfma_f32_16x16x32_bf16 v[36:39], v[218:221], v[226:229], v[36:39]
	ds_read_b128 v[226:229], v31
	s_waitcnt lgkmcnt(3)
	v_mfma_f32_16x16x32_bf16 v[104:107], v[166:169], v[158:161], v[104:107]
	v_mfma_f32_16x16x32_bf16 v[108:111], v[178:181], v[158:161], v[108:111]
	v_mfma_f32_16x16x32_bf16 v[112:115], v[214:217], v[158:161], v[112:115]
	v_mfma_f32_16x16x32_bf16 v[52:55], v[218:221], v[158:161], v[52:55]
	s_waitcnt lgkmcnt(2)
	v_mfma_f32_16x16x32_bf16 v[116:119], v[166:169], v[162:165], v[116:119]
	v_mfma_f32_16x16x32_bf16 v[120:123], v[178:181], v[162:165], v[120:123]
	v_mfma_f32_16x16x32_bf16 v[124:127], v[214:217], v[162:165], v[124:127]
	v_mfma_f32_16x16x32_bf16 v[68:71], v[218:221], v[162:165], v[68:71]
	s_add_u32 s64, s0, s70
	s_addc_u32 s65, s1, 0
	s_add_u32 s68, s14, s70
	s_addc_u32 s69, s15, 0
	s_add_u32 s70, s70, 0x80
	s_waitcnt vmcnt(0)
	s_waitcnt lgkmcnt(0)
	s_barrier
	ds_read_b128 v[158:161], v7 offset:32768
	ds_read_b128 v[162:165], v6
	v_mfma_f32_16x16x32_bf16 v[128:131], v[166:169], v[222:225], v[128:131]
	v_mfma_f32_16x16x32_bf16 v[100:103], v[166:169], v[226:229], v[100:103]
	ds_read_b128 v[166:169], v7 offset:34816
	v_mfma_f32_16x16x32_bf16 v[132:135], v[178:181], v[222:225], v[132:135]
	v_mfma_f32_16x16x32_bf16 v[140:143], v[178:181], v[226:229], v[140:143]
	ds_read_b128 v[178:181], v6 offset:2048
	v_mfma_f32_16x16x32_bf16 v[136:139], v[214:217], v[222:225], v[136:139]
	v_mfma_f32_16x16x32_bf16 v[150:153], v[214:217], v[226:229], v[150:153]
	ds_read_b128 v[214:217], v7 offset:36864
	v_mfma_f32_16x16x32_bf16 v[84:87], v[218:221], v[222:225], v[84:87]
	v_mfma_f32_16x16x32_bf16 v[154:157], v[218:221], v[226:229], v[154:157]
	ds_read_b128 v[218:221], v7 offset:38912
	ds_read_b128 v[222:225], v6 offset:4096
	ds_read_b128 v[226:229], v6 offset:6144
	s_waitcnt lgkmcnt(6)
	v_mfma_f32_16x16x32_bf16 v[40:43], v[158:161], v[162:165], v[40:43]
	s_waitcnt lgkmcnt(5)
	v_mfma_f32_16x16x32_bf16 v[44:47], v[166:169], v[162:165], v[44:47]
	s_waitcnt lgkmcnt(4)
	s_mov_b32 m0, s52
	v_mfma_f32_16x16x32_bf16 v[56:59], v[158:161], v[178:181], v[56:59]
	global_load_lds_dwordx4 v0, s[64:65]
	v_mfma_f32_16x16x32_bf16 v[60:63], v[166:169], v[178:181], v[60:63]
	s_waitcnt lgkmcnt(3)
	v_mfma_f32_16x16x32_bf16 v[48:51], v[214:217], v[162:165], v[48:51]
	v_mfma_f32_16x16x32_bf16 v[64:67], v[214:217], v[178:181], v[64:67]
	s_waitcnt lgkmcnt(2)
	s_mov_b32 m0, s51
	v_mfma_f32_16x16x32_bf16 v[174:177], v[218:221], v[162:165], v[174:177]
	global_load_lds_dwordx4 v0, s[68:69]
	ds_read_b128 v[162:165], v6 offset:8192
	v_mfma_f32_16x16x32_bf16 v[170:173], v[218:221], v[178:181], v[170:173]
	ds_read_b128 v[178:181], v6 offset:10240
	s_waitcnt lgkmcnt(3)
	v_mfma_f32_16x16x32_bf16 v[72:75], v[158:161], v[222:225], v[72:75]
	v_mfma_f32_16x16x32_bf16 v[76:79], v[166:169], v[222:225], v[76:79]
	s_mov_b32 m0, s53
	v_mfma_f32_16x16x32_bf16 v[80:83], v[214:217], v[222:225], v[80:83]
	global_load_lds_dwordx4 v2, s[64:65]
	v_mfma_f32_16x16x32_bf16 v[32:35], v[218:221], v[222:225], v[32:35]
	ds_read_b128 v[222:225], v6 offset:12288
	s_waitcnt lgkmcnt(3)
	v_mfma_f32_16x16x32_bf16 v[88:91], v[158:161], v[226:229], v[88:91]
	v_mfma_f32_16x16x32_bf16 v[92:95], v[166:169], v[226:229], v[92:95]
	s_mov_b32 m0, s54
	v_mfma_f32_16x16x32_bf16 v[96:99], v[214:217], v[226:229], v[96:99]
	global_load_lds_dwordx4 v2, s[68:69]
	v_mfma_f32_16x16x32_bf16 v[36:39], v[218:221], v[226:229], v[36:39]
	ds_read_b128 v[226:229], v6 offset:14336
	s_waitcnt lgkmcnt(3)
	v_mfma_f32_16x16x32_bf16 v[108:111], v[166:169], v[162:165], v[108:111]
	s_waitcnt lgkmcnt(2)
	v_mfma_f32_16x16x32_bf16 v[120:123], v[166:169], v[178:181], v[120:123]
	s_waitcnt lgkmcnt(1)
	s_mov_b32 m0, s55
	v_mfma_f32_16x16x32_bf16 v[132:135], v[166:169], v[222:225], v[132:135]
	global_load_lds_dwordx4 v4, s[64:65]
	s_waitcnt lgkmcnt(0)
	v_mfma_f32_16x16x32_bf16 v[140:143], v[166:169], v[226:229], v[140:143]
	ds_read_b128 v[166:169], v7 offset:33792
	v_mfma_f32_16x16x32_bf16 v[104:107], v[158:161], v[162:165], v[104:107]
	v_mfma_f32_16x16x32_bf16 v[116:119], v[158:161], v[178:181], v[116:119]
	s_mov_b32 m0, s58
	v_mfma_f32_16x16x32_bf16 v[128:131], v[158:161], v[222:225], v[128:131]
	global_load_lds_dwordx4 v4, s[68:69]
	v_mfma_f32_16x16x32_bf16 v[100:103], v[158:161], v[226:229], v[100:103]
	ds_read_b128 v[158:161], v6 offset:1024
	v_mfma_f32_16x16x32_bf16 v[124:127], v[214:217], v[178:181], v[124:127]
	v_mfma_f32_16x16x32_bf16 v[68:71], v[218:221], v[178:181], v[68:71]
	ds_read_b128 v[178:181], v7 offset:35840
	s_mov_b32 m0, s62
	v_mfma_f32_16x16x32_bf16 v[112:115], v[214:217], v[162:165], v[112:115]
	global_load_lds_dwordx4 v146, s[64:65]
	v_mfma_f32_16x16x32_bf16 v[52:55], v[218:221], v[162:165], v[52:55]
	ds_read_b128 v[162:165], v6 offset:3072
	v_mfma_f32_16x16x32_bf16 v[136:139], v[214:217], v[222:225], v[136:139]
	v_mfma_f32_16x16x32_bf16 v[84:87], v[218:221], v[222:225], v[84:87]
	ds_read_b128 v[222:225], v6 offset:5120
	s_mov_b32 m0, s63
	v_mfma_f32_16x16x32_bf16 v[150:153], v[214:217], v[226:229], v[150:153]
	global_load_lds_dwordx4 v146, s[68:69]
	ds_read_b128 v[214:217], v7 offset:37888
	v_mfma_f32_16x16x32_bf16 v[154:157], v[218:221], v[226:229], v[154:157]
	ds_read_b128 v[218:221], v7 offset:39936
	ds_read_b128 v[226:229], v6 offset:7168
	s_waitcnt lgkmcnt(6)
	v_mfma_f32_16x16x32_bf16 v[40:43], v[166:169], v[158:161], v[40:43]
	s_waitcnt lgkmcnt(5)
	v_mfma_f32_16x16x32_bf16 v[44:47], v[178:181], v[158:161], v[44:47]
	s_waitcnt lgkmcnt(4)
	v_mfma_f32_16x16x32_bf16 v[56:59], v[166:169], v[162:165], v[56:59]
	v_mfma_f32_16x16x32_bf16 v[60:63], v[178:181], v[162:165], v[60:63]
	s_waitcnt lgkmcnt(3)
	v_mfma_f32_16x16x32_bf16 v[72:75], v[166:169], v[222:225], v[72:75]
	v_mfma_f32_16x16x32_bf16 v[76:79], v[178:181], v[222:225], v[76:79]
	s_waitcnt lgkmcnt(2)
	v_mfma_f32_16x16x32_bf16 v[48:51], v[214:217], v[158:161], v[48:51]
	s_waitcnt lgkmcnt(1)
	v_mfma_f32_16x16x32_bf16 v[174:177], v[218:221], v[158:161], v[174:177]
	ds_read_b128 v[158:161], v6 offset:9216
	v_mfma_f32_16x16x32_bf16 v[64:67], v[214:217], v[162:165], v[64:67]
	v_mfma_f32_16x16x32_bf16 v[170:173], v[218:221], v[162:165], v[170:173]
	ds_read_b128 v[162:165], v6 offset:11264
	v_mfma_f32_16x16x32_bf16 v[80:83], v[214:217], v[222:225], v[80:83]
	v_mfma_f32_16x16x32_bf16 v[32:35], v[218:221], v[222:225], v[32:35]
	ds_read_b128 v[222:225], v6 offset:13312
	s_waitcnt lgkmcnt(3)
	v_mfma_f32_16x16x32_bf16 v[88:91], v[166:169], v[226:229], v[88:91]
	v_mfma_f32_16x16x32_bf16 v[92:95], v[178:181], v[226:229], v[92:95]
	v_mfma_f32_16x16x32_bf16 v[96:99], v[214:217], v[226:229], v[96:99]
	v_mfma_f32_16x16x32_bf16 v[36:39], v[218:221], v[226:229], v[36:39]
	ds_read_b128 v[226:229], v6 offset:15360
	s_waitcnt lgkmcnt(3)
	v_mfma_f32_16x16x32_bf16 v[104:107], v[166:169], v[158:161], v[104:107]
	v_mfma_f32_16x16x32_bf16 v[108:111], v[178:181], v[158:161], v[108:111]
	v_mfma_f32_16x16x32_bf16 v[112:115], v[214:217], v[158:161], v[112:115]
	v_mfma_f32_16x16x32_bf16 v[52:55], v[218:221], v[158:161], v[52:55]
	s_waitcnt lgkmcnt(2)
	v_mfma_f32_16x16x32_bf16 v[116:119], v[166:169], v[162:165], v[116:119]
	v_mfma_f32_16x16x32_bf16 v[120:123], v[178:181], v[162:165], v[120:123]
	v_mfma_f32_16x16x32_bf16 v[124:127], v[214:217], v[162:165], v[124:127]
	v_mfma_f32_16x16x32_bf16 v[68:71], v[218:221], v[162:165], v[68:71]
	s_add_u32 s64, s0, s70
	s_addc_u32 s65, s1, 0
	s_add_u32 s68, s14, s70
	s_addc_u32 s69, s15, 0
	s_add_u32 s70, s70, 0x80
	s_cmp_lg_u32 s70, 0x2f80
	s_waitcnt vmcnt(0)
	s_waitcnt lgkmcnt(0)
	s_barrier
	s_cbranch_scc1 .Lmy_rr_r6a
	v_mfma_f32_16x16x32_bf16 v[128:131], v[166:169], v[222:225], v[128:131]
	v_mfma_f32_16x16x32_bf16 v[100:103], v[166:169], v[226:229], v[100:103]
	v_mfma_f32_16x16x32_bf16 v[132:135], v[178:181], v[222:225], v[132:135]
	v_mfma_f32_16x16x32_bf16 v[140:143], v[178:181], v[226:229], v[140:143]
	v_mfma_f32_16x16x32_bf16 v[136:139], v[214:217], v[222:225], v[136:139]
	v_mfma_f32_16x16x32_bf16 v[150:153], v[214:217], v[226:229], v[150:153]
	v_mfma_f32_16x16x32_bf16 v[84:87], v[218:221], v[222:225], v[84:87]
	v_mfma_f32_16x16x32_bf16 v[154:157], v[218:221], v[226:229], v[154:157]
	s_nop 15
	s_nop 15
	v_lshl_add_u64 v[158:159], s[64:65], 0, v[0:1]
	s_mov_b32 s70, m0
	s_mov_b32 m0, s42
	s_nop 0
	global_load_lds_dwordx4 v[158:159], off
	s_mov_b32 m0, s70
	v_lshl_add_u64 v[158:159], s[68:69], 0, v[0:1]
	s_mov_b32 s70, m0
	s_mov_b32 m0, s43
	s_nop 0
	global_load_lds_dwordx4 v[158:159], off
	s_mov_b32 m0, s70
	v_lshl_add_u64 v[158:159], s[64:65], 0, v[2:3]
	s_mov_b32 s70, m0
	s_mov_b32 m0, s44
	s_nop 0
	global_load_lds_dwordx4 v[158:159], off
	s_mov_b32 m0, s70
	v_lshl_add_u64 v[158:159], s[68:69], 0, v[2:3]
	s_mov_b32 s70, m0
	s_mov_b32 m0, s45
	s_nop 0
	global_load_lds_dwordx4 v[158:159], off
	s_mov_b32 m0, s70
	v_lshl_add_u64 v[158:159], s[64:65], 0, v[4:5]
	s_mov_b32 s70, m0
	s_mov_b32 m0, s46
	s_nop 0
	global_load_lds_dwordx4 v[158:159], off
	s_mov_b32 m0, s70
	v_lshl_add_u64 v[158:159], s[68:69], 0, v[4:5]
	s_mov_b32 s70, m0
	s_mov_b32 m0, s47
	s_nop 0
	global_load_lds_dwordx4 v[158:159], off
	s_mov_b32 m0, s70
	v_lshl_add_u64 v[158:159], s[64:65], 0, v[146:147]
	s_mov_b32 s64, m0
	s_mov_b32 m0, s49
	s_nop 0
	global_load_lds_dwordx4 v[158:159], off
	s_mov_b32 m0, s64
	v_lshl_add_u64 v[158:159], s[68:69], 0, v[146:147]
	s_mov_b32 s64, m0
	s_mov_b32 m0, s50
	s_nop 0
	global_load_lds_dwordx4 v[158:159], off
	s_mov_b32 m0, s64
	ds_read_b128 v[158:161], v8
	ds_read_b128 v[162:165], v9
	ds_read_b128 v[166:169], v11
	ds_read_b128 v[214:217], v10
	ds_read_b128 v[178:181], v12
	ds_read_b128 v[218:221], v13
	ds_read_b128 v[222:225], v14
	ds_read_b128 v[226:229], v15
	s_waitcnt lgkmcnt(3)
	v_mfma_f32_16x16x32_bf16 v[40:43], v[158:161], v[178:181], v[40:43]
	v_mfma_f32_16x16x32_bf16 v[44:47], v[162:165], v[178:181], v[44:47]
	v_mfma_f32_16x16x32_bf16 v[48:51], v[166:169], v[178:181], v[48:51]
	v_mfma_f32_16x16x32_bf16 v[174:177], v[214:217], v[178:181], v[174:177]
	ds_read_b128 v[178:181], v16
	s_waitcnt lgkmcnt(3)
	v_mfma_f32_16x16x32_bf16 v[56:59], v[158:161], v[218:221], v[56:59]
	v_mfma_f32_16x16x32_bf16 v[60:63], v[162:165], v[218:221], v[60:63]
	v_mfma_f32_16x16x32_bf16 v[64:67], v[166:169], v[218:221], v[64:67]
	v_mfma_f32_16x16x32_bf16 v[170:173], v[214:217], v[218:221], v[170:173]
	ds_read_b128 v[218:221], v17
	s_waitcnt lgkmcnt(3)
	v_mfma_f32_16x16x32_bf16 v[72:75], v[158:161], v[222:225], v[72:75]
	v_mfma_f32_16x16x32_bf16 v[76:79], v[162:165], v[222:225], v[76:79]
	v_mfma_f32_16x16x32_bf16 v[80:83], v[166:169], v[222:225], v[80:83]
	v_mfma_f32_16x16x32_bf16 v[32:35], v[214:217], v[222:225], v[32:35]
	ds_read_b128 v[222:225], v18
	s_waitcnt lgkmcnt(3)
	v_mfma_f32_16x16x32_bf16 v[88:91], v[158:161], v[226:229], v[88:91]
	v_mfma_f32_16x16x32_bf16 v[92:95], v[162:165], v[226:229], v[92:95]
	v_mfma_f32_16x16x32_bf16 v[96:99], v[166:169], v[226:229], v[96:99]
	v_mfma_f32_16x16x32_bf16 v[36:39], v[214:217], v[226:229], v[36:39]
	ds_read_b128 v[226:229], v19
	s_waitcnt lgkmcnt(3)
	v_mfma_f32_16x16x32_bf16 v[104:107], v[158:161], v[178:181], v[104:107]
	v_mfma_f32_16x16x32_bf16 v[108:111], v[162:165], v[178:181], v[108:111]
	v_mfma_f32_16x16x32_bf16 v[112:115], v[166:169], v[178:181], v[112:115]
	v_mfma_f32_16x16x32_bf16 v[52:55], v[214:217], v[178:181], v[52:55]
	s_waitcnt lgkmcnt(2)
	v_mfma_f32_16x16x32_bf16 v[116:119], v[158:161], v[218:221], v[116:119]
	v_mfma_f32_16x16x32_bf16 v[120:123], v[162:165], v[218:221], v[120:123]
	v_mfma_f32_16x16x32_bf16 v[124:127], v[166:169], v[218:221], v[124:127]
	v_mfma_f32_16x16x32_bf16 v[68:71], v[214:217], v[218:221], v[68:71]
	s_waitcnt lgkmcnt(1)
	v_mfma_f32_16x16x32_bf16 v[132:135], v[162:165], v[222:225], v[132:135]
	v_mfma_f32_16x16x32_bf16 v[84:87], v[214:217], v[222:225], v[84:87]
	s_waitcnt lgkmcnt(0)
	v_mfma_f32_16x16x32_bf16 v[100:103], v[158:161], v[226:229], v[100:103]
	v_mfma_f32_16x16x32_bf16 v[150:153], v[166:169], v[226:229], v[150:153]
	v_mfma_f32_16x16x32_bf16 v[154:157], v[214:217], v[226:229], v[154:157]
	v_mfma_f32_16x16x32_bf16 v[128:131], v[158:161], v[222:225], v[128:131]
	v_mfma_f32_16x16x32_bf16 v[136:139], v[166:169], v[222:225], v[136:139]
	v_mfma_f32_16x16x32_bf16 v[140:143], v[162:165], v[226:229], v[140:143]
	ds_read_b128 v[158:161], v20
	ds_read_b128 v[162:165], v21
	ds_read_b128 v[166:169], v23
	ds_read_b128 v[214:217], v22
	ds_read_b128 v[178:181], v24
	ds_read_b128 v[218:221], v25
	ds_read_b128 v[222:225], v26
	ds_read_b128 v[226:229], v27
	s_waitcnt lgkmcnt(3)
	v_mfma_f32_16x16x32_bf16 v[40:43], v[158:161], v[178:181], v[40:43]
	v_mfma_f32_16x16x32_bf16 v[44:47], v[162:165], v[178:181], v[44:47]
	v_mfma_f32_16x16x32_bf16 v[48:51], v[166:169], v[178:181], v[48:51]
	v_mfma_f32_16x16x32_bf16 v[174:177], v[214:217], v[178:181], v[174:177]
	ds_read_b128 v[178:181], v28
	s_waitcnt lgkmcnt(3)
	v_mfma_f32_16x16x32_bf16 v[56:59], v[158:161], v[218:221], v[56:59]
	v_mfma_f32_16x16x32_bf16 v[60:63], v[162:165], v[218:221], v[60:63]
	v_mfma_f32_16x16x32_bf16 v[64:67], v[166:169], v[218:221], v[64:67]
	v_mfma_f32_16x16x32_bf16 v[170:173], v[214:217], v[218:221], v[170:173]
	ds_read_b128 v[218:221], v29
	s_waitcnt lgkmcnt(3)
	v_mfma_f32_16x16x32_bf16 v[72:75], v[158:161], v[222:225], v[72:75]
	v_mfma_f32_16x16x32_bf16 v[76:79], v[162:165], v[222:225], v[76:79]
	v_mfma_f32_16x16x32_bf16 v[80:83], v[166:169], v[222:225], v[80:83]
	v_mfma_f32_16x16x32_bf16 v[32:35], v[214:217], v[222:225], v[32:35]
	ds_read_b128 v[222:225], v30
	s_waitcnt lgkmcnt(3)
	v_mfma_f32_16x16x32_bf16 v[88:91], v[158:161], v[226:229], v[88:91]
	v_mfma_f32_16x16x32_bf16 v[92:95], v[162:165], v[226:229], v[92:95]
	v_mfma_f32_16x16x32_bf16 v[96:99], v[166:169], v[226:229], v[96:99]
	v_mfma_f32_16x16x32_bf16 v[36:39], v[214:217], v[226:229], v[36:39]
	ds_read_b128 v[226:229], v31
	s_waitcnt lgkmcnt(3)
	v_mfma_f32_16x16x32_bf16 v[104:107], v[158:161], v[178:181], v[104:107]
	v_mfma_f32_16x16x32_bf16 v[108:111], v[162:165], v[178:181], v[108:111]
	v_mfma_f32_16x16x32_bf16 v[112:115], v[166:169], v[178:181], v[112:115]
	v_mfma_f32_16x16x32_bf16 v[52:55], v[214:217], v[178:181], v[52:55]
	s_waitcnt lgkmcnt(2)
	v_mfma_f32_16x16x32_bf16 v[116:119], v[158:161], v[218:221], v[116:119]
	v_mfma_f32_16x16x32_bf16 v[120:123], v[162:165], v[218:221], v[120:123]
	v_mfma_f32_16x16x32_bf16 v[124:127], v[166:169], v[218:221], v[124:127]
	v_mfma_f32_16x16x32_bf16 v[68:71], v[214:217], v[218:221], v[68:71]
	s_waitcnt lgkmcnt(1)
	v_mfma_f32_16x16x32_bf16 v[132:135], v[162:165], v[222:225], v[132:135]
	v_mfma_f32_16x16x32_bf16 v[84:87], v[214:217], v[222:225], v[84:87]
	s_waitcnt lgkmcnt(0)
	v_mfma_f32_16x16x32_bf16 v[100:103], v[158:161], v[226:229], v[100:103]
	v_mfma_f32_16x16x32_bf16 v[150:153], v[166:169], v[226:229], v[150:153]
	v_mfma_f32_16x16x32_bf16 v[154:157], v[214:217], v[226:229], v[154:157]
	v_mfma_f32_16x16x32_bf16 v[128:131], v[158:161], v[222:225], v[128:131]
	v_mfma_f32_16x16x32_bf16 v[136:139], v[166:169], v[222:225], v[136:139]
	v_mfma_f32_16x16x32_bf16 v[140:143], v[162:165], v[226:229], v[140:143]
	s_add_u32 s0, s0, 0x2f80
	s_addc_u32 s1, s1, 0
	s_add_u32 s14, s14, 0x2f80
	s_waitcnt vmcnt(0)
	s_barrier
	s_addc_u32 s15, s15, 0
	v_lshl_add_u64 v[158:159], s[0:1], 0, v[0:1]
	s_mov_b32 s64, m0
	s_mov_b32 m0, s52
	s_nop 0
	global_load_lds_dwordx4 v[158:159], off
	s_mov_b32 m0, s64
	v_lshl_add_u64 v[158:159], s[14:15], 0, v[0:1]
	s_mov_b32 s52, m0
	s_mov_b32 m0, s51
	s_nop 0
	global_load_lds_dwordx4 v[158:159], off
	s_mov_b32 m0, s52
	v_lshl_add_u64 v[158:159], s[0:1], 0, v[2:3]
	s_mov_b32 s51, m0
	s_mov_b32 m0, s53
	s_nop 0
	global_load_lds_dwordx4 v[158:159], off
	s_mov_b32 m0, s51
	v_lshl_add_u64 v[158:159], s[14:15], 0, v[2:3]
	s_mov_b32 s51, m0
	s_mov_b32 m0, s54
	s_nop 0
	global_load_lds_dwordx4 v[158:159], off
	s_mov_b32 m0, s51
	v_lshl_add_u64 v[158:159], s[0:1], 0, v[4:5]
	s_mov_b32 s51, m0
	s_mov_b32 m0, s55
	s_nop 0
	global_load_lds_dwordx4 v[158:159], off
	s_mov_b32 m0, s51
	v_lshl_add_u64 v[158:159], s[14:15], 0, v[4:5]
	s_mov_b32 s51, m0
	s_mov_b32 m0, s58
	s_nop 0
	global_load_lds_dwordx4 v[158:159], off
	s_mov_b32 m0, s51
	v_lshl_add_u64 v[158:159], s[0:1], 0, v[146:147]
	s_mov_b32 s0, m0
	s_mov_b32 m0, s62
	s_nop 0
	global_load_lds_dwordx4 v[158:159], off
	s_mov_b32 m0, s0
	v_lshl_add_u64 v[158:159], s[14:15], 0, v[146:147]
	s_mov_b32 s0, m0
	s_mov_b32 m0, s63
	s_nop 0
	global_load_lds_dwordx4 v[158:159], off
	s_mov_b32 m0, s0
	ds_read_b128 v[158:161], v7 offset:32768
	ds_read_b128 v[162:165], v7 offset:34816
	ds_read_b128 v[166:169], v7 offset:36864
	ds_read_b128 v[214:217], v7 offset:38912
	ds_read_b128 v[178:181], v6
	ds_read_b128 v[218:221], v6 offset:2048
	ds_read_b128 v[222:225], v6 offset:4096
	ds_read_b128 v[226:229], v6 offset:6144
	s_waitcnt lgkmcnt(3)
	v_mfma_f32_16x16x32_bf16 v[40:43], v[158:161], v[178:181], v[40:43]
	v_mfma_f32_16x16x32_bf16 v[44:47], v[162:165], v[178:181], v[44:47]
	v_mfma_f32_16x16x32_bf16 v[48:51], v[166:169], v[178:181], v[48:51]
	v_mfma_f32_16x16x32_bf16 v[174:177], v[214:217], v[178:181], v[174:177]
	ds_read_b128 v[178:181], v6 offset:8192
	s_waitcnt lgkmcnt(3)
	v_mfma_f32_16x16x32_bf16 v[56:59], v[158:161], v[218:221], v[56:59]
	v_mfma_f32_16x16x32_bf16 v[60:63], v[162:165], v[218:221], v[60:63]
	v_mfma_f32_16x16x32_bf16 v[64:67], v[166:169], v[218:221], v[64:67]
	v_mfma_f32_16x16x32_bf16 v[170:173], v[214:217], v[218:221], v[170:173]
	ds_read_b128 v[218:221], v6 offset:10240
	s_waitcnt lgkmcnt(3)
	v_mfma_f32_16x16x32_bf16 v[72:75], v[158:161], v[222:225], v[72:75]
	v_mfma_f32_16x16x32_bf16 v[76:79], v[162:165], v[222:225], v[76:79]
	v_mfma_f32_16x16x32_bf16 v[80:83], v[166:169], v[222:225], v[80:83]
	v_mfma_f32_16x16x32_bf16 v[32:35], v[214:217], v[222:225], v[32:35]
	ds_read_b128 v[222:225], v6 offset:12288
	s_waitcnt lgkmcnt(3)
	v_mfma_f32_16x16x32_bf16 v[88:91], v[158:161], v[226:229], v[88:91]
	v_mfma_f32_16x16x32_bf16 v[92:95], v[162:165], v[226:229], v[92:95]
	v_mfma_f32_16x16x32_bf16 v[96:99], v[166:169], v[226:229], v[96:99]
	v_mfma_f32_16x16x32_bf16 v[36:39], v[214:217], v[226:229], v[36:39]
	ds_read_b128 v[226:229], v6 offset:14336
	s_waitcnt lgkmcnt(3)
	v_mfma_f32_16x16x32_bf16 v[104:107], v[158:161], v[178:181], v[104:107]
	v_mfma_f32_16x16x32_bf16 v[108:111], v[162:165], v[178:181], v[108:111]
	v_mfma_f32_16x16x32_bf16 v[112:115], v[166:169], v[178:181], v[112:115]
	v_mfma_f32_16x16x32_bf16 v[52:55], v[214:217], v[178:181], v[52:55]
	s_waitcnt lgkmcnt(2)
	v_mfma_f32_16x16x32_bf16 v[116:119], v[158:161], v[218:221], v[116:119]
	v_mfma_f32_16x16x32_bf16 v[120:123], v[162:165], v[218:221], v[120:123]
	v_mfma_f32_16x16x32_bf16 v[124:127], v[166:169], v[218:221], v[124:127]
	v_mfma_f32_16x16x32_bf16 v[68:71], v[214:217], v[218:221], v[68:71]
	s_waitcnt lgkmcnt(1)
	v_mfma_f32_16x16x32_bf16 v[132:135], v[162:165], v[222:225], v[132:135]
	v_mfma_f32_16x16x32_bf16 v[84:87], v[214:217], v[222:225], v[84:87]
	s_waitcnt lgkmcnt(0)
	v_mfma_f32_16x16x32_bf16 v[100:103], v[158:161], v[226:229], v[100:103]
	v_mfma_f32_16x16x32_bf16 v[150:153], v[166:169], v[226:229], v[150:153]
	v_mfma_f32_16x16x32_bf16 v[154:157], v[214:217], v[226:229], v[154:157]
	v_mfma_f32_16x16x32_bf16 v[128:131], v[158:161], v[222:225], v[128:131]
	v_mfma_f32_16x16x32_bf16 v[136:139], v[166:169], v[222:225], v[136:139]
	v_mfma_f32_16x16x32_bf16 v[140:143], v[162:165], v[226:229], v[140:143]
	ds_read_b128 v[158:161], v7 offset:33792
	ds_read_b128 v[162:165], v7 offset:35840
	ds_read_b128 v[166:169], v7 offset:37888
	ds_read_b128 v[214:217], v7 offset:39936
	ds_read_b128 v[178:181], v6 offset:1024
	ds_read_b128 v[218:221], v6 offset:3072
	ds_read_b128 v[222:225], v6 offset:5120
	ds_read_b128 v[226:229], v6 offset:7168
	s_waitcnt lgkmcnt(3)
	v_mfma_f32_16x16x32_bf16 v[40:43], v[158:161], v[178:181], v[40:43]
	v_mfma_f32_16x16x32_bf16 v[44:47], v[162:165], v[178:181], v[44:47]
	v_mfma_f32_16x16x32_bf16 v[48:51], v[166:169], v[178:181], v[48:51]
	v_mfma_f32_16x16x32_bf16 v[174:177], v[214:217], v[178:181], v[174:177]
	ds_read_b128 v[178:181], v6 offset:9216
	s_waitcnt lgkmcnt(3)
	v_mfma_f32_16x16x32_bf16 v[56:59], v[158:161], v[218:221], v[56:59]
	v_mfma_f32_16x16x32_bf16 v[60:63], v[162:165], v[218:221], v[60:63]
	v_mfma_f32_16x16x32_bf16 v[64:67], v[166:169], v[218:221], v[64:67]
	v_mfma_f32_16x16x32_bf16 v[170:173], v[214:217], v[218:221], v[170:173]
	ds_read_b128 v[218:221], v6 offset:11264
	s_waitcnt lgkmcnt(3)
	v_mfma_f32_16x16x32_bf16 v[72:75], v[158:161], v[222:225], v[72:75]
	v_mfma_f32_16x16x32_bf16 v[76:79], v[162:165], v[222:225], v[76:79]
	v_mfma_f32_16x16x32_bf16 v[80:83], v[166:169], v[222:225], v[80:83]
	v_mfma_f32_16x16x32_bf16 v[32:35], v[214:217], v[222:225], v[32:35]
	ds_read_b128 v[222:225], v6 offset:13312
	s_waitcnt lgkmcnt(3)
	v_mfma_f32_16x16x32_bf16 v[88:91], v[158:161], v[226:229], v[88:91]
	v_mfma_f32_16x16x32_bf16 v[92:95], v[162:165], v[226:229], v[92:95]
	v_mfma_f32_16x16x32_bf16 v[96:99], v[166:169], v[226:229], v[96:99]
	v_mfma_f32_16x16x32_bf16 v[36:39], v[214:217], v[226:229], v[36:39]
	ds_read_b128 v[226:229], v6 offset:15360
	s_waitcnt lgkmcnt(3)
	v_mfma_f32_16x16x32_bf16 v[104:107], v[158:161], v[178:181], v[104:107]
	v_mfma_f32_16x16x32_bf16 v[108:111], v[162:165], v[178:181], v[108:111]
	v_mfma_f32_16x16x32_bf16 v[112:115], v[166:169], v[178:181], v[112:115]
	v_mfma_f32_16x16x32_bf16 v[52:55], v[214:217], v[178:181], v[52:55]
	s_waitcnt lgkmcnt(2)
	v_mfma_f32_16x16x32_bf16 v[116:119], v[158:161], v[218:221], v[116:119]
	v_mfma_f32_16x16x32_bf16 v[120:123], v[162:165], v[218:221], v[120:123]
	v_mfma_f32_16x16x32_bf16 v[124:127], v[166:169], v[218:221], v[124:127]
	v_mfma_f32_16x16x32_bf16 v[68:71], v[214:217], v[218:221], v[68:71]
	s_waitcnt lgkmcnt(1)
	v_mfma_f32_16x16x32_bf16 v[132:135], v[162:165], v[222:225], v[132:135]
	v_mfma_f32_16x16x32_bf16 v[84:87], v[214:217], v[222:225], v[84:87]
	s_waitcnt lgkmcnt(0)
	v_mfma_f32_16x16x32_bf16 v[100:103], v[158:161], v[226:229], v[100:103]
	v_mfma_f32_16x16x32_bf16 v[150:153], v[166:169], v[226:229], v[150:153]
	v_mfma_f32_16x16x32_bf16 v[154:157], v[214:217], v[226:229], v[154:157]
	v_mfma_f32_16x16x32_bf16 v[128:131], v[158:161], v[222:225], v[128:131]
	v_mfma_f32_16x16x32_bf16 v[136:139], v[166:169], v[222:225], v[136:139]
	v_mfma_f32_16x16x32_bf16 v[140:143], v[162:165], v[226:229], v[140:143]
	s_waitcnt vmcnt(0)
	s_barrier
	v_lshl_add_u64 v[6:7], s[20:21], 0, v[0:1]
	s_mov_b32 s0, m0
	s_mov_b32 m0, s42
	s_nop 0
	global_load_lds_dwordx4 v[6:7], off
	s_mov_b32 m0, s0
	v_lshl_add_u64 v[0:1], s[22:23], 0, v[0:1]
	s_mov_b32 s0, m0
	s_mov_b32 m0, s43
	s_nop 0
	global_load_lds_dwordx4 v[0:1], off
	s_mov_b32 m0, s0
	v_lshl_add_u64 v[0:1], s[20:21], 0, v[2:3]
	s_mov_b32 s0, m0
	s_mov_b32 m0, s44
	s_nop 0
	global_load_lds_dwordx4 v[0:1], off
	s_mov_b32 m0, s0
	v_lshl_add_u64 v[0:1], s[22:23], 0, v[2:3]
	s_mov_b32 s0, m0
	s_mov_b32 m0, s45
	s_nop 0
	global_load_lds_dwordx4 v[0:1], off
	s_mov_b32 m0, s0
	v_lshl_add_u64 v[0:1], s[20:21], 0, v[4:5]
	s_mov_b32 s0, m0
	s_mov_b32 m0, s46
	s_nop 0
	global_load_lds_dwordx4 v[0:1], off
	s_mov_b32 m0, s0
	v_lshl_add_u64 v[0:1], s[22:23], 0, v[4:5]
	s_mov_b32 s0, m0
	s_mov_b32 m0, s47
	s_nop 0
	global_load_lds_dwordx4 v[0:1], off
	s_mov_b32 m0, s0
	v_lshl_add_u64 v[0:1], s[20:21], 0, v[146:147]
	s_mov_b32 s0, m0
	s_mov_b32 m0, s49
	s_nop 0
	global_load_lds_dwordx4 v[0:1], off
	s_mov_b32 m0, s0
	v_lshl_add_u64 v[0:1], s[22:23], 0, v[146:147]
	s_mov_b32 s0, m0
	s_mov_b32 m0, s50
	s_nop 0
	global_load_lds_dwordx4 v[0:1], off
	s_mov_b32 m0, s0
	ds_read_b128 v[0:3], v8
	ds_read_b128 v[4:7], v9
	ds_read_b128 v[158:161], v11
	ds_read_b128 v[8:11], v10
	ds_read_b128 v[162:165], v12
	ds_read_b128 v[166:169], v13
	ds_read_b128 v[178:181], v14
	ds_read_b128 v[12:15], v15
	s_waitcnt lgkmcnt(3)
	v_mfma_f32_16x16x32_bf16 v[40:43], v[0:3], v[162:165], v[40:43]
	v_mfma_f32_16x16x32_bf16 v[44:47], v[4:7], v[162:165], v[44:47]
	v_mfma_f32_16x16x32_bf16 v[48:51], v[158:161], v[162:165], v[48:51]
	v_mfma_f32_16x16x32_bf16 v[162:165], v[8:11], v[162:165], v[174:177]
	s_nop 2
	ds_read_b128 v[174:177], v16
	s_waitcnt lgkmcnt(3)
	v_mfma_f32_16x16x32_bf16 v[56:59], v[0:3], v[166:169], v[56:59]
	v_mfma_f32_16x16x32_bf16 v[60:63], v[4:7], v[166:169], v[60:63]
	v_mfma_f32_16x16x32_bf16 v[64:67], v[158:161], v[166:169], v[64:67]
	v_mfma_f32_16x16x32_bf16 v[166:169], v[8:11], v[166:169], v[170:173]
	s_nop 2
	ds_read_b128 v[170:173], v17
	s_waitcnt lgkmcnt(3)
	v_mfma_f32_16x16x32_bf16 v[72:75], v[0:3], v[178:181], v[72:75]
	v_mfma_f32_16x16x32_bf16 v[76:79], v[4:7], v[178:181], v[76:79]
	v_mfma_f32_16x16x32_bf16 v[80:83], v[158:161], v[178:181], v[80:83]
	v_mfma_f32_16x16x32_bf16 v[32:35], v[8:11], v[178:181], v[32:35]
	ds_read_b128 v[178:181], v18
	s_waitcnt lgkmcnt(3)
	v_mfma_f32_16x16x32_bf16 v[214:217], v[0:3], v[12:15], v[88:91]
	v_mfma_f32_16x16x32_bf16 v[218:221], v[4:7], v[12:15], v[92:95]
	v_mfma_f32_16x16x32_bf16 v[222:225], v[158:161], v[12:15], v[96:99]
	v_mfma_f32_16x16x32_bf16 v[12:15], v[8:11], v[12:15], v[36:39]
	ds_read_b128 v[16:19], v19
	s_waitcnt lgkmcnt(3)
	v_mfma_f32_16x16x32_bf16 v[36:39], v[0:3], v[174:177], v[104:107]
	v_mfma_f32_16x16x32_bf16 v[226:229], v[4:7], v[174:177], v[108:111]
	v_mfma_f32_16x16x32_bf16 v[112:115], v[158:161], v[174:177], v[112:115]
	s_waitcnt lgkmcnt(2)
	v_mfma_f32_16x16x32_bf16 v[116:119], v[0:3], v[170:173], v[116:119]
	v_mfma_f32_16x16x32_bf16 v[120:123], v[4:7], v[170:173], v[120:123]
	v_mfma_f32_16x16x32_bf16 v[124:127], v[158:161], v[170:173], v[124:127]
	s_waitcnt lgkmcnt(1)
	v_mfma_f32_16x16x32_bf16 v[128:131], v[0:3], v[178:181], v[128:131]
	v_mfma_f32_16x16x32_bf16 v[132:135], v[4:7], v[178:181], v[132:135]
	s_waitcnt lgkmcnt(0)
	v_mfma_f32_16x16x32_bf16 v[0:3], v[0:3], v[16:19], v[100:103]
	v_mfma_f32_16x16x32_bf16 v[4:7], v[4:7], v[16:19], v[140:143]
	v_mfma_f32_16x16x32_bf16 v[140:143], v[158:161], v[16:19], v[150:153]
	v_mfma_f32_16x16x32_bf16 v[150:153], v[8:11], v[16:19], v[154:157]
	v_mfma_f32_16x16x32_bf16 v[174:177], v[8:11], v[174:177], v[52:55]
	v_mfma_f32_16x16x32_bf16 v[170:173], v[8:11], v[170:173], v[68:71]
	v_mfma_f32_16x16x32_bf16 v[136:139], v[158:161], v[178:181], v[136:139]
	v_mfma_f32_16x16x32_bf16 v[178:181], v[8:11], v[178:181], v[84:87]
	ds_read_b128 v[8:11], v20
	ds_read_b128 v[154:157], v21
	ds_read_b128 v[158:161], v23
	ds_read_b128 v[230:233], v22
	ds_read_b128 v[16:19], v24
	ds_read_b128 v[20:23], v25
	ds_read_b128 v[52:55], v26
	ds_read_b128 v[24:27], v27
	s_waitcnt lgkmcnt(3)
	v_mfma_f32_16x16x32_bf16 v[234:237], v[8:11], v[16:19], v[40:43]
	v_mfma_f32_16x16x32_bf16 v[238:241], v[154:157], v[16:19], v[44:47]
	v_mfma_f32_16x16x32_bf16 v[242:245], v[158:161], v[16:19], v[48:51]
	v_mfma_f32_16x16x32_bf16 v[162:165], v[230:233], v[16:19], v[162:165]
	ds_read_b128 v[16:19], v28
	s_waitcnt lgkmcnt(3)
	v_mfma_f32_16x16x32_bf16 v[108:111], v[8:11], v[20:23], v[56:59]
	v_mfma_f32_16x16x32_bf16 v[104:107], v[154:157], v[20:23], v[60:63]
	v_mfma_f32_16x16x32_bf16 v[100:103], v[158:161], v[20:23], v[64:67]
	v_mfma_f32_16x16x32_bf16 v[96:99], v[230:233], v[20:23], v[166:169]
	ds_read_b128 v[20:23], v29
	s_waitcnt lgkmcnt(3)
	v_mfma_f32_16x16x32_bf16 v[92:95], v[8:11], v[52:55], v[72:75]
	v_mfma_f32_16x16x32_bf16 v[88:91], v[154:157], v[52:55], v[76:79]
	v_mfma_f32_16x16x32_bf16 v[84:87], v[158:161], v[52:55], v[80:83]
	v_mfma_f32_16x16x32_bf16 v[80:83], v[230:233], v[52:55], v[32:35]
	ds_read_b128 v[166:169], v30
	s_waitcnt lgkmcnt(3)
	v_mfma_f32_16x16x32_bf16 v[76:79], v[8:11], v[24:27], v[214:217]
	v_mfma_f32_16x16x32_bf16 v[72:75], v[154:157], v[24:27], v[218:221]
	v_mfma_f32_16x16x32_bf16 v[68:71], v[158:161], v[24:27], v[222:225]
	v_mfma_f32_16x16x32_bf16 v[64:67], v[230:233], v[24:27], v[12:15]
	ds_read_b128 v[214:217], v31
	s_waitcnt lgkmcnt(3)
	v_mfma_f32_16x16x32_bf16 v[60:63], v[8:11], v[16:19], v[36:39]
	v_mfma_f32_16x16x32_bf16 v[56:59], v[154:157], v[16:19], v[226:229]
	v_mfma_f32_16x16x32_bf16 v[52:55], v[158:161], v[16:19], v[112:115]
	v_mfma_f32_16x16x32_bf16 v[48:51], v[230:233], v[16:19], v[174:177]
	s_waitcnt lgkmcnt(2)
	v_mfma_f32_16x16x32_bf16 v[44:47], v[8:11], v[20:23], v[116:119]
	v_mfma_f32_16x16x32_bf16 v[40:43], v[154:157], v[20:23], v[120:123]
	v_mfma_f32_16x16x32_bf16 v[36:39], v[158:161], v[20:23], v[124:127]
	v_mfma_f32_16x16x32_bf16 v[32:35], v[230:233], v[20:23], v[170:173]
	s_waitcnt lgkmcnt(1)
	v_mfma_f32_16x16x32_bf16 v[28:31], v[8:11], v[166:169], v[128:131]
	v_mfma_f32_16x16x32_bf16 v[24:27], v[154:157], v[166:169], v[132:135]
	v_mfma_f32_16x16x32_bf16 v[20:23], v[158:161], v[166:169], v[136:139]
	v_mfma_f32_16x16x32_bf16 v[16:19], v[230:233], v[166:169], v[178:181]
	s_waitcnt lgkmcnt(0)
	v_mfma_f32_16x16x32_bf16 v[12:15], v[8:11], v[214:217], v[0:3]
	v_mfma_f32_16x16x32_bf16 v[8:11], v[154:157], v[214:217], v[4:7]
	v_mfma_f32_16x16x32_bf16 v[4:7], v[158:161], v[214:217], v[140:143]
	v_mfma_f32_16x16x32_bf16 v[0:3], v[230:233], v[214:217], v[150:153]
	v_mov_b32_e32 v145, v184
	s_waitcnt vmcnt(0)
	s_barrier
	s_lshl_b32 s20, s13, 8
	s_lshl_b32 s14, s12, 8
	v_and_b32_e32 v151, 15, v145
	v_ashrrev_i32_e32 v112, 1, v145
	v_and_b32_e32 v153, 0xffffff80, v112
	v_or_b32_e32 v112, s20, v151
	v_add_u32_e32 v112, v112, v153
	v_ashrrev_i32_e32 v113, 31, v112
	v_lshlrev_b64 v[112:113], 13, v[112:113]
	v_bfe_u32 v150, v145, 6, 2
	v_lshl_add_u64 v[112:113], s[4:5], 0, v[112:113]
	s_ashr_i32 s15, s14, 31
	v_bfe_u32 v152, v145, 4, 2
	v_lshl_add_u64 v[112:113], s[14:15], 2, v[112:113]
	v_lshlrev_b32_e32 v146, 8, v150
	v_lshl_add_u64 v[112:113], v[112:113], 0, v[146:147]
	v_lshlrev_b32_e32 v146, 4, v152
	v_lshl_add_u64 v[154:155], v[112:113], 0, v[146:147]
	global_load_dwordx4 v[120:123], v[154:155], off offset:192
	global_load_dwordx4 v[128:131], v[154:155], off offset:128
	global_load_dwordx4 v[136:139], v[154:155], off offset:64
	global_load_dwordx4 v[140:143], v[154:155], off
	v_add_co_u32_e32 v112, vcc, s66, v154
	v_lshlrev_b32_e32 v158, 2, v152
	s_nop 0
	v_addc_co_u32_e32 v113, vcc, 0, v155, vcc
	global_load_dwordx4 v[132:135], v[112:113], off
	global_load_dwordx4 v[124:127], v[112:113], off offset:64
	global_load_dwordx4 v[116:119], v[112:113], off offset:128
	v_cmp_lt_i32_e32 vcc, v188, v186
	global_load_dwordx4 v[112:115], v[112:113], off offset:192
	v_cmp_eq_u32_e64 s[0:1], 0, v152
	v_cndmask_b32_e32 v146, v185, v188, vcc
	v_cmp_lt_i32_e32 vcc, v187, v186
	v_lshlrev_b32_e32 v149, 2, v146
	v_lshlrev_b32_e32 v157, 6, v150
	v_cndmask_b32_e32 v156, v185, v187, vcc
	v_lshlrev_b32_e32 v146, 2, v156
	v_or_b32_e32 v156, v153, v151
	v_add_u32_e32 v152, s20, v156
	v_ashrrev_i32_e32 v153, 31, v152
	v_lshl_or_b32 v182, v150, 10, v204
	v_or3_b32 v150, v157, s14, v158
	v_lshlrev_b64 v[158:159], 13, v[152:153]
	v_ashrrev_i32_e32 v151, 31, v150
	v_lshlrev_b64 v[160:161], 12, v[152:153]
	v_lshl_add_u64 v[158:159], s[4:5], 0, v[158:159]
	v_lshl_add_u64 v[160:161], s[6:7], 0, v[160:161]
	v_lshl_add_u64 v[166:167], v[150:151], 2, v[158:159]
	v_lshl_add_u64 v[168:169], v[150:151], 1, v[160:161]
	s_waitcnt vmcnt(7)
	v_pk_add_f32 v[158:159], v[162:163], v[120:121]
	s_waitcnt vmcnt(6)
	v_pk_add_f32 v[120:121], v[242:243], v[128:129]
	s_waitcnt vmcnt(5)
	v_pk_add_f32 v[128:129], v[238:239], v[136:137]
	s_waitcnt vmcnt(4)
	v_pk_add_f32 v[136:137], v[234:235], v[140:141]
	v_pk_add_f32 v[160:161], v[164:165], v[122:123]
	v_pk_add_f32 v[122:123], v[244:245], v[130:131]
	v_pk_add_f32 v[130:131], v[240:241], v[138:139]
	v_pk_add_f32 v[138:139], v[236:237], v[142:143]
	v_pk_mul_f32 v[172:173], v[128:129], v[128:129]
	v_pk_mul_f32 v[178:179], v[136:137], v[136:137]
	v_pk_mul_f32 v[162:163], v[120:121], v[120:121]
	v_pk_mul_f32 v[174:175], v[130:131], v[130:131]
	v_cvt_pk_bf16_f32 v176, v136, v137
	v_pk_mul_f32 v[180:181], v[138:139], v[138:139]
	global_store_dwordx4 v[166:167], v[136:139], off
	v_add_f32_e32 v153, v172, v173
	v_add_f32_e32 v157, v178, v179
	v_pk_mul_f32 v[136:137], v[158:159], v[158:159]
	v_pk_mul_f32 v[164:165], v[122:123], v[122:123]
	v_cvt_pk_bf16_f32 v177, v138, v139
	v_pk_mul_f32 v[138:139], v[160:161], v[160:161]
	v_add_f32_e32 v162, v162, v163
	v_add_f32_e32 v136, v136, v137
	v_add_f32_e32 v137, v174, v153
	v_add_f32_e32 v153, v180, v157
	v_add_f32_e32 v157, v164, v162
	v_add_f32_e32 v136, v138, v136
	v_add_f32_e32 v137, v175, v137
	v_add_f32_e32 v138, v181, v153
	v_add_f32_e32 v153, v165, v157
	v_add_f32_e32 v137, v138, v137
	v_add_f32_e32 v137, v137, v153
	v_add_f32_e32 v136, v139, v136
	v_add_f32_e32 v136, v137, v136
	ds_bpermute_b32 v137, v149, v136
	v_cvt_pk_bf16_f32 v170, v128, v129
	v_cvt_pk_bf16_f32 v171, v130, v131
	v_cvt_pk_bf16_f32 v142, v120, v121
	global_store_dwordx2 v[168:169], v[176:177], off
	global_store_dwordx4 v[166:167], v[128:131], off offset:64
	global_store_dwordx2 v[168:169], v[170:171], off offset:32
	global_store_dwordx4 v[166:167], v[120:123], off offset:128
	v_cvt_pk_bf16_f32 v140, v158, v159
	v_cvt_pk_bf16_f32 v141, v160, v161
	s_waitcnt lgkmcnt(0)
	v_add_f32_e32 v120, v136, v137
	ds_bpermute_b32 v121, v146, v120
	v_cvt_pk_bf16_f32 v143, v122, v123
	v_lshl_add_u32 v153, v156, 2, v182
	global_store_dwordx2 v[168:169], v[142:143], off offset:64
	global_store_dwordx4 v[166:167], v[158:161], off offset:192
	global_store_dwordx2 v[168:169], v[140:141], off offset:96
	s_and_saveexec_b64 s[14:15], s[0:1]
	s_cbranch_execz .LBB0_567
	s_waitcnt lgkmcnt(0)
	v_add_f32_e32 v120, v120, v121
	ds_write_b32 v153, v120

.LBB0_696:
	s_ashr_i32 s23, s22, 31
	s_lshl_b64 s[22:23], s[22:23], 20
	s_add_u32 s22, s28, s22
	s_addc_u32 s23, s29, s23
	s_ashr_i32 s25, s24, 31
	s_lshl_b64 s[24:25], s[24:25], 20
	s_add_u32 s24, s6, s24
	s_addc_u32 s25, s7, s25
	s_add_u32 s46, s14, 0x80
	v_and_b32_e32 v8, 48, v7
	v_lshlrev_b32_e32 v9, 6, v7
	v_lshlrev_b32_e32 v7, 2, v7
	s_addc_u32 s47, s15, 0
	v_and_b32_e32 v10, 0x3c0, v9
	v_and_b32_e32 v149, 32, v7
	s_add_u32 s50, s20, 0x80
	v_or_b32_e32 v145, v10, v8
	v_bitop3_b32 v12, v10, v149, v8 bitop3:0x36
	s_waitcnt vmcnt(0)
	s_barrier
	v_lshlrev_b32_e32 v8, 13, v6
	s_addc_u32 s51, s21, 0
	s_add_i32 s27, s1, 0x10000
	v_lshl_add_u64 v[6:7], s[46:47], 0, v[0:1]
	s_mov_b32 s41, m0
	s_mov_b32 m0, s27
	s_nop 0
	global_load_lds_dwordx4 v[6:7], off
	s_mov_b32 m0, s41
	s_add_i32 s26, s1, 0x18000
	v_lshl_add_u64 v[6:7], s[50:51], 0, v[0:1]
	s_mov_b32 s41, m0
	s_mov_b32 m0, s26
	s_nop 0
	global_load_lds_dwordx4 v[6:7], off
	s_mov_b32 m0, s41
	v_lshl_add_u64 v[6:7], s[46:47], 0, v[2:3]
	s_add_i32 s41, s1, 0x12000
	s_mov_b32 s42, m0
	s_mov_b32 m0, s41
	s_nop 0
	global_load_lds_dwordx4 v[6:7], off
	s_mov_b32 m0, s42
	v_lshl_add_u64 v[6:7], s[50:51], 0, v[2:3]
	s_add_i32 s42, s1, 0x1a000
	s_mov_b32 s43, m0
	s_mov_b32 m0, s42
	s_nop 0
	global_load_lds_dwordx4 v[6:7], off
	s_mov_b32 m0, s43
	v_lshl_add_u64 v[6:7], s[46:47], 0, v[4:5]
	s_add_i32 s43, s1, 0x14000
	s_mov_b32 s44, m0
	s_mov_b32 m0, s43
	s_nop 0
	global_load_lds_dwordx4 v[6:7], off
	s_mov_b32 m0, s44
	v_lshl_add_u64 v[6:7], s[50:51], 0, v[4:5]
	s_add_i32 s44, s1, 0x1c000
	s_mov_b32 s45, m0
	s_mov_b32 m0, s44
	s_nop 0
	global_load_lds_dwordx4 v[6:7], off
	s_mov_b32 m0, s45
	v_lshl_add_u64 v[6:7], s[46:47], 0, v[146:147]
	s_add_i32 s45, s1, 0x16000
	s_mov_b32 s46, m0
	s_mov_b32 m0, s45
	s_nop 0
	global_load_lds_dwordx4 v[6:7], off
	s_mov_b32 m0, s46
	v_lshl_add_u64 v[6:7], s[50:51], 0, v[146:147]
	s_add_i32 s46, s1, 0x1e000
	s_mov_b32 s47, m0
	s_mov_b32 m0, s46
	s_nop 0
	global_load_lds_dwordx4 v[6:7], off
	s_mov_b32 m0, s47
	v_and_b32_e32 v182, 0xffffc000, v9
	v_or_b32_e32 v183, 0x800, v182
	v_or_b32_e32 v189, 0x1000, v182
	v_or_b32_e32 v199, 0x1800, v182
	v_or_b32_e32 v200, 0x2000, v182
	v_or_b32_e32 v201, 0x2800, v182
	v_or_b32_e32 v203, 0x3000, v182
	v_or_b32_e32 v206, 0x3800, v182
	s_movk_i32 s47, 0x6000
	v_and_or_b32 v7, v8, s47, v12
	ds_read_b128 v[8:11], v7 offset:32768
	v_or_b32_e32 v6, v12, v182
	ds_read_b128 v[12:15], v7 offset:34816
	ds_read_b128 v[16:19], v7 offset:36864
	ds_read_b128 v[24:27], v7 offset:38912
	ds_read_b128 v[20:23], v6
	ds_read_b128 v[28:31], v6 offset:2048
	ds_read_b128 v[32:35], v6 offset:4096
	ds_read_b128 v[36:39], v6 offset:6144
	s_waitcnt lgkmcnt(3)
	v_mfma_f32_16x16x32_bf16 v[40:43], v[8:11], v[20:23], 0
	v_mfma_f32_16x16x32_bf16 v[44:47], v[12:15], v[20:23], 0
	v_mfma_f32_16x16x32_bf16 v[48:51], v[16:19], v[20:23], 0
	v_mfma_f32_16x16x32_bf16 v[20:23], v[24:27], v[20:23], 0
	ds_read_b128 v[52:55], v6 offset:8192
	s_waitcnt lgkmcnt(3)
	v_mfma_f32_16x16x32_bf16 v[56:59], v[8:11], v[28:31], 0
	v_mfma_f32_16x16x32_bf16 v[60:63], v[12:15], v[28:31], 0
	v_mfma_f32_16x16x32_bf16 v[64:67], v[16:19], v[28:31], 0
	v_mfma_f32_16x16x32_bf16 v[28:31], v[24:27], v[28:31], 0
	ds_read_b128 v[68:71], v6 offset:10240
	s_waitcnt lgkmcnt(3)
	v_mfma_f32_16x16x32_bf16 v[72:75], v[8:11], v[32:35], 0
	v_mfma_f32_16x16x32_bf16 v[76:79], v[12:15], v[32:35], 0
	v_mfma_f32_16x16x32_bf16 v[80:83], v[16:19], v[32:35], 0
	v_mfma_f32_16x16x32_bf16 v[32:35], v[24:27], v[32:35], 0
	ds_read_b128 v[84:87], v6 offset:12288
	s_waitcnt lgkmcnt(3)
	v_mfma_f32_16x16x32_bf16 v[88:91], v[8:11], v[36:39], 0
	v_mfma_f32_16x16x32_bf16 v[92:95], v[12:15], v[36:39], 0
	v_mfma_f32_16x16x32_bf16 v[96:99], v[16:19], v[36:39], 0
	v_mfma_f32_16x16x32_bf16 v[36:39], v[24:27], v[36:39], 0
	ds_read_b128 v[100:103], v6 offset:14336
	s_waitcnt lgkmcnt(3)
	v_mfma_f32_16x16x32_bf16 v[104:107], v[8:11], v[52:55], 0
	v_mfma_f32_16x16x32_bf16 v[108:111], v[12:15], v[52:55], 0
	v_mfma_f32_16x16x32_bf16 v[112:115], v[16:19], v[52:55], 0
	v_mfma_f32_16x16x32_bf16 v[52:55], v[24:27], v[52:55], 0
	s_waitcnt lgkmcnt(2)
	v_mfma_f32_16x16x32_bf16 v[116:119], v[8:11], v[68:71], 0
	v_mfma_f32_16x16x32_bf16 v[120:123], v[12:15], v[68:71], 0
	v_mfma_f32_16x16x32_bf16 v[124:127], v[16:19], v[68:71], 0
	v_mfma_f32_16x16x32_bf16 v[68:71], v[24:27], v[68:71], 0
	s_waitcnt lgkmcnt(1)
	v_mfma_f32_16x16x32_bf16 v[128:131], v[8:11], v[84:87], 0
	v_mfma_f32_16x16x32_bf16 v[132:135], v[12:15], v[84:87], 0
	v_mfma_f32_16x16x32_bf16 v[136:139], v[16:19], v[84:87], 0
	v_mfma_f32_16x16x32_bf16 v[84:87], v[24:27], v[84:87], 0
	s_waitcnt lgkmcnt(0)
	v_mfma_f32_16x16x32_bf16 v[8:11], v[8:11], v[100:103], 0
	v_mfma_f32_16x16x32_bf16 v[12:15], v[12:15], v[100:103], 0
	v_mfma_f32_16x16x32_bf16 v[16:19], v[16:19], v[100:103], 0
	v_mfma_f32_16x16x32_bf16 v[24:27], v[24:27], v[100:103], 0
	ds_read_b128 v[100:103], v7 offset:33792
	ds_read_b128 v[140:143], v7 offset:35840
	ds_read_b128 v[150:153], v7 offset:37888
	ds_read_b128 v[158:161], v7 offset:39936
	ds_read_b128 v[154:157], v6 offset:1024
	ds_read_b128 v[162:165], v6 offset:3072
	ds_read_b128 v[166:169], v6 offset:5120
	ds_read_b128 v[170:173], v6 offset:7168
	s_waitcnt lgkmcnt(3)
	v_mfma_f32_16x16x32_bf16 v[40:43], v[100:103], v[154:157], v[40:43]
	v_mfma_f32_16x16x32_bf16 v[44:47], v[140:143], v[154:157], v[44:47]
	v_mfma_f32_16x16x32_bf16 v[48:51], v[150:153], v[154:157], v[48:51]
	v_mfma_f32_16x16x32_bf16 v[20:23], v[158:161], v[154:157], v[20:23]
	ds_read_b128 v[154:157], v6 offset:9216
	s_waitcnt lgkmcnt(3)
	v_mfma_f32_16x16x32_bf16 v[56:59], v[100:103], v[162:165], v[56:59]
	v_mfma_f32_16x16x32_bf16 v[60:63], v[140:143], v[162:165], v[60:63]
	v_mfma_f32_16x16x32_bf16 v[64:67], v[150:153], v[162:165], v[64:67]
	v_mfma_f32_16x16x32_bf16 v[28:31], v[158:161], v[162:165], v[28:31]
	ds_read_b128 v[162:165], v6 offset:11264
	s_waitcnt lgkmcnt(3)
	v_mfma_f32_16x16x32_bf16 v[72:75], v[100:103], v[166:169], v[72:75]
	v_mfma_f32_16x16x32_bf16 v[76:79], v[140:143], v[166:169], v[76:79]
	v_mfma_f32_16x16x32_bf16 v[80:83], v[150:153], v[166:169], v[80:83]
	v_mfma_f32_16x16x32_bf16 v[32:35], v[158:161], v[166:169], v[32:35]
	ds_read_b128 v[166:169], v6 offset:13312
	s_waitcnt lgkmcnt(3)
	v_mfma_f32_16x16x32_bf16 v[88:91], v[100:103], v[170:173], v[88:91]
	v_mfma_f32_16x16x32_bf16 v[92:95], v[140:143], v[170:173], v[92:95]
	v_mfma_f32_16x16x32_bf16 v[96:99], v[150:153], v[170:173], v[96:99]
	v_mfma_f32_16x16x32_bf16 v[36:39], v[158:161], v[170:173], v[36:39]
	ds_read_b128 v[170:173], v6 offset:15360
	s_waitcnt lgkmcnt(3)
	v_mfma_f32_16x16x32_bf16 v[104:107], v[100:103], v[154:157], v[104:107]
	v_mfma_f32_16x16x32_bf16 v[108:111], v[140:143], v[154:157], v[108:111]
	v_mfma_f32_16x16x32_bf16 v[112:115], v[150:153], v[154:157], v[112:115]
	v_mfma_f32_16x16x32_bf16 v[52:55], v[158:161], v[154:157], v[52:55]
	s_waitcnt lgkmcnt(2)
	v_mfma_f32_16x16x32_bf16 v[116:119], v[100:103], v[162:165], v[116:119]
	v_mfma_f32_16x16x32_bf16 v[120:123], v[140:143], v[162:165], v[120:123]
	v_mfma_f32_16x16x32_bf16 v[124:127], v[150:153], v[162:165], v[124:127]
	v_mfma_f32_16x16x32_bf16 v[68:71], v[158:161], v[162:165], v[68:71]
	s_waitcnt lgkmcnt(1)
	v_mfma_f32_16x16x32_bf16 v[128:131], v[100:103], v[166:169], v[128:131]
	v_mfma_f32_16x16x32_bf16 v[132:135], v[140:143], v[166:169], v[132:135]
	v_mfma_f32_16x16x32_bf16 v[136:139], v[150:153], v[166:169], v[136:139]
	v_mfma_f32_16x16x32_bf16 v[84:87], v[158:161], v[166:169], v[84:87]
	s_waitcnt lgkmcnt(0)
	v_mfma_f32_16x16x32_bf16 v[100:103], v[100:103], v[170:173], v[8:11]
	v_mfma_f32_16x16x32_bf16 v[150:153], v[150:153], v[170:173], v[16:19]
	v_mfma_f32_16x16x32_bf16 v[24:27], v[158:161], v[170:173], v[24:27]
	v_mfma_f32_16x16x32_bf16 v[140:143], v[140:143], v[170:173], v[12:15]
	s_add_u32 s50, s14, 0x100
	s_addc_u32 s51, s15, 0
	s_add_u32 s52, s20, 0x100
	s_waitcnt vmcnt(0)
	s_barrier
	s_addc_u32 s53, s21, 0
	v_lshl_add_u64 v[8:9], s[50:51], 0, v[0:1]
	s_mov_b32 s47, m0
	s_mov_b32 m0, s1
	s_nop 0
	global_load_lds_dwordx4 v[8:9], off
	s_mov_b32 m0, s47
	v_lshl_add_u64 v[8:9], s[52:53], 0, v[0:1]
	s_mov_b32 s47, m0
	s_mov_b32 m0, s34
	s_nop 0
	global_load_lds_dwordx4 v[8:9], off
	s_mov_b32 m0, s47
	v_lshl_add_u64 v[8:9], s[50:51], 0, v[2:3]
	s_mov_b32 s47, m0
	s_mov_b32 m0, s35
	s_nop 0
	global_load_lds_dwordx4 v[8:9], off
	s_mov_b32 m0, s47
	v_lshl_add_u64 v[8:9], s[52:53], 0, v[2:3]
	s_mov_b32 s47, m0
	s_mov_b32 m0, s36
	s_nop 0
	global_load_lds_dwordx4 v[8:9], off
	s_mov_b32 m0, s47
	v_lshl_add_u64 v[8:9], s[50:51], 0, v[4:5]
	s_mov_b32 s47, m0
	s_mov_b32 m0, s37
	s_nop 0
	global_load_lds_dwordx4 v[8:9], off
	s_mov_b32 m0, s47
	v_lshl_add_u64 v[8:9], s[52:53], 0, v[4:5]
	s_mov_b32 s47, m0
	s_mov_b32 m0, s38
	s_nop 0
	global_load_lds_dwordx4 v[8:9], off
	s_mov_b32 m0, s47
	v_lshl_add_u64 v[8:9], s[50:51], 0, v[146:147]
	s_mov_b32 s47, m0
	s_mov_b32 m0, s39
	s_nop 0
	global_load_lds_dwordx4 v[8:9], off
	s_mov_b32 m0, s47
	v_lshl_add_u64 v[8:9], s[52:53], 0, v[146:147]
	s_mov_b32 s47, m0
	s_mov_b32 m0, s40
	s_nop 0
	global_load_lds_dwordx4 v[8:9], off
	s_mov_b32 m0, s47
	v_or_b32_e32 v8, 0x18000, v7
	v_or_b32_e32 v9, 0x18800, v7
	v_or_b32_e32 v11, 0x19000, v7
	v_or_b32_e32 v10, 0x19800, v7
	ds_read_b128 v[154:157], v8
	ds_read_b128 v[158:161], v9
	ds_read_b128 v[162:165], v11
	ds_read_b128 v[166:169], v10
	v_bitop3_b32 v207, v145, s33, v149 bitop3:0xde
	v_add_u32_e32 v12, v207, v182
	ds_read_b128 v[16:19], v12
	v_add_u32_e32 v13, v207, v183
	v_add_u32_e32 v14, v207, v189
	v_add_u32_e32 v15, v207, v199
	ds_read_b128 v[170:173], v13
	ds_read_b128 v[174:177], v14
	ds_read_b128 v[178:181], v15
	s_waitcnt lgkmcnt(3)
	v_mfma_f32_16x16x32_bf16 v[40:43], v[154:157], v[16:19], v[40:43]
	v_mfma_f32_16x16x32_bf16 v[44:47], v[158:161], v[16:19], v[44:47]
	v_mfma_f32_16x16x32_bf16 v[48:51], v[162:165], v[16:19], v[48:51]
	v_mfma_f32_16x16x32_bf16 v[214:217], v[166:169], v[16:19], v[20:23]
	v_add_u32_e32 v16, v207, v200
	v_add_u32_e32 v17, v207, v201
	v_add_u32_e32 v18, v207, v203
	v_add_u32_e32 v19, v207, v206
	ds_read_b128 v[20:23], v16
	s_waitcnt lgkmcnt(3)
	v_mfma_f32_16x16x32_bf16 v[56:59], v[154:157], v[170:173], v[56:59]
	v_mfma_f32_16x16x32_bf16 v[60:63], v[158:161], v[170:173], v[60:63]
	v_mfma_f32_16x16x32_bf16 v[64:67], v[162:165], v[170:173], v[64:67]
	v_mfma_f32_16x16x32_bf16 v[170:173], v[166:169], v[170:173], v[28:31]
	s_nop 2
	ds_read_b128 v[28:31], v17
	s_waitcnt lgkmcnt(3)
	v_mfma_f32_16x16x32_bf16 v[72:75], v[154:157], v[174:177], v[72:75]
	v_mfma_f32_16x16x32_bf16 v[76:79], v[158:161], v[174:177], v[76:79]
	v_mfma_f32_16x16x32_bf16 v[80:83], v[162:165], v[174:177], v[80:83]
	v_mfma_f32_16x16x32_bf16 v[32:35], v[166:169], v[174:177], v[32:35]
	ds_read_b128 v[174:177], v18
	s_waitcnt lgkmcnt(3)
	v_mfma_f32_16x16x32_bf16 v[88:91], v[154:157], v[178:181], v[88:91]
	v_mfma_f32_16x16x32_bf16 v[92:95], v[158:161], v[178:181], v[92:95]
	v_mfma_f32_16x16x32_bf16 v[96:99], v[162:165], v[178:181], v[96:99]
	v_mfma_f32_16x16x32_bf16 v[36:39], v[166:169], v[178:181], v[36:39]
	ds_read_b128 v[178:181], v19
	s_waitcnt lgkmcnt(3)
	v_mfma_f32_16x16x32_bf16 v[104:107], v[154:157], v[20:23], v[104:107]
	v_mfma_f32_16x16x32_bf16 v[108:111], v[158:161], v[20:23], v[108:111]
	v_mfma_f32_16x16x32_bf16 v[112:115], v[162:165], v[20:23], v[112:115]
	v_mfma_f32_16x16x32_bf16 v[52:55], v[166:169], v[20:23], v[52:55]
	s_waitcnt lgkmcnt(2)
	v_mfma_f32_16x16x32_bf16 v[116:119], v[154:157], v[28:31], v[116:119]
	v_mfma_f32_16x16x32_bf16 v[120:123], v[158:161], v[28:31], v[120:123]
	v_mfma_f32_16x16x32_bf16 v[124:127], v[162:165], v[28:31], v[124:127]
	v_mfma_f32_16x16x32_bf16 v[68:71], v[166:169], v[28:31], v[68:71]
	s_waitcnt lgkmcnt(1)
	v_mfma_f32_16x16x32_bf16 v[128:131], v[154:157], v[174:177], v[128:131]
	v_mfma_f32_16x16x32_bf16 v[132:135], v[158:161], v[174:177], v[132:135]
	v_mfma_f32_16x16x32_bf16 v[84:87], v[166:169], v[174:177], v[84:87]
	s_waitcnt lgkmcnt(0)
	v_mfma_f32_16x16x32_bf16 v[100:103], v[154:157], v[178:181], v[100:103]
	v_mfma_f32_16x16x32_bf16 v[150:153], v[162:165], v[178:181], v[150:153]
	v_mfma_f32_16x16x32_bf16 v[154:157], v[166:169], v[178:181], v[24:27]
	v_mfma_f32_16x16x32_bf16 v[136:139], v[162:165], v[174:177], v[136:139]
	v_mfma_f32_16x16x32_bf16 v[140:143], v[158:161], v[178:181], v[140:143]
	v_or_b32_e32 v20, 0x18400, v7
	v_or_b32_e32 v21, 0x18c00, v7
	v_or_b32_e32 v23, 0x19400, v7
	v_or_b32_e32 v22, 0x19c00, v7
	ds_read_b128 v[158:161], v20
	ds_read_b128 v[162:165], v21
	ds_read_b128 v[166:169], v23
	ds_read_b128 v[174:177], v22
	s_mov_b32 s47, 0x10400
	v_bitop3_b32 v145, v145, s47, v149 bitop3:0xde
	v_add_u32_e32 v24, v145, v182
	ds_read_b128 v[28:31], v24
	v_add_u32_e32 v25, v145, v183
	v_add_u32_e32 v26, v145, v189
	v_add_u32_e32 v27, v145, v199
	ds_read_b128 v[178:181], v25
	ds_read_b128 v[218:221], v26
	ds_read_b128 v[222:225], v27
	s_waitcnt lgkmcnt(3)
	v_mfma_f32_16x16x32_bf16 v[40:43], v[158:161], v[28:31], v[40:43]
	v_mfma_f32_16x16x32_bf16 v[44:47], v[162:165], v[28:31], v[44:47]
	v_mfma_f32_16x16x32_bf16 v[48:51], v[166:169], v[28:31], v[48:51]
	v_mfma_f32_16x16x32_bf16 v[214:217], v[174:177], v[28:31], v[214:217]
	v_add_u32_e32 v28, v145, v200
	v_add_u32_e32 v29, v145, v201
	v_add_u32_e32 v30, v145, v203
	v_add_u32_e32 v31, v145, v206
	ds_read_b128 v[226:229], v28
	s_waitcnt lgkmcnt(3)
	v_mfma_f32_16x16x32_bf16 v[56:59], v[158:161], v[178:181], v[56:59]
	v_mfma_f32_16x16x32_bf16 v[60:63], v[162:165], v[178:181], v[60:63]
	v_mfma_f32_16x16x32_bf16 v[64:67], v[166:169], v[178:181], v[64:67]
	v_mfma_f32_16x16x32_bf16 v[170:173], v[174:177], v[178:181], v[170:173]
	ds_read_b128 v[178:181], v29
	s_waitcnt lgkmcnt(3)
	v_mfma_f32_16x16x32_bf16 v[72:75], v[158:161], v[218:221], v[72:75]
	v_mfma_f32_16x16x32_bf16 v[76:79], v[162:165], v[218:221], v[76:79]
	v_mfma_f32_16x16x32_bf16 v[80:83], v[166:169], v[218:221], v[80:83]
	v_mfma_f32_16x16x32_bf16 v[32:35], v[174:177], v[218:221], v[32:35]
	ds_read_b128 v[218:221], v30
	s_waitcnt lgkmcnt(3)
	v_mfma_f32_16x16x32_bf16 v[88:91], v[158:161], v[222:225], v[88:91]
	v_mfma_f32_16x16x32_bf16 v[92:95], v[162:165], v[222:225], v[92:95]
	v_mfma_f32_16x16x32_bf16 v[96:99], v[166:169], v[222:225], v[96:99]
	v_mfma_f32_16x16x32_bf16 v[36:39], v[174:177], v[222:225], v[36:39]
	ds_read_b128 v[222:225], v31
	s_waitcnt lgkmcnt(3)
	v_mfma_f32_16x16x32_bf16 v[104:107], v[158:161], v[226:229], v[104:107]
	v_mfma_f32_16x16x32_bf16 v[108:111], v[162:165], v[226:229], v[108:111]
	v_mfma_f32_16x16x32_bf16 v[112:115], v[166:169], v[226:229], v[112:115]
	v_mfma_f32_16x16x32_bf16 v[52:55], v[174:177], v[226:229], v[52:55]
	s_waitcnt lgkmcnt(2)
	v_mfma_f32_16x16x32_bf16 v[116:119], v[158:161], v[178:181], v[116:119]
	v_mfma_f32_16x16x32_bf16 v[120:123], v[162:165], v[178:181], v[120:123]
	v_mfma_f32_16x16x32_bf16 v[124:127], v[166:169], v[178:181], v[124:127]
	v_mfma_f32_16x16x32_bf16 v[68:71], v[174:177], v[178:181], v[68:71]
	s_waitcnt lgkmcnt(1)
	v_mfma_f32_16x16x32_bf16 v[132:135], v[162:165], v[218:221], v[132:135]
	v_mfma_f32_16x16x32_bf16 v[84:87], v[174:177], v[218:221], v[84:87]
	s_waitcnt lgkmcnt(0)
	v_mfma_f32_16x16x32_bf16 v[100:103], v[158:161], v[222:225], v[100:103]
	v_mfma_f32_16x16x32_bf16 v[150:153], v[166:169], v[222:225], v[150:153]
	v_mfma_f32_16x16x32_bf16 v[154:157], v[174:177], v[222:225], v[154:157]
	v_mfma_f32_16x16x32_bf16 v[128:131], v[158:161], v[218:221], v[128:131]
	v_mfma_f32_16x16x32_bf16 v[136:139], v[166:169], v[218:221], v[136:139]
	v_mfma_f32_16x16x32_bf16 v[140:143], v[162:165], v[222:225], v[140:143]
	s_add_u32 s50, s14, 0x180
	s_addc_u32 s51, s15, 0
	s_add_u32 s52, s20, 0x180
	s_waitcnt vmcnt(0)
	s_barrier
	s_addc_u32 s53, s21, 0
	v_lshl_add_u64 v[158:159], s[50:51], 0, v[0:1]
	s_mov_b32 s47, m0
	s_mov_b32 m0, s27
	s_nop 0
	global_load_lds_dwordx4 v[158:159], off
	s_mov_b32 m0, s47
	v_lshl_add_u64 v[158:159], s[52:53], 0, v[0:1]
	s_mov_b32 s47, m0
	s_mov_b32 m0, s26
	s_nop 0
	global_load_lds_dwordx4 v[158:159], off
	s_mov_b32 m0, s47
	v_lshl_add_u64 v[158:159], s[50:51], 0, v[2:3]
	s_mov_b32 s47, m0
	s_mov_b32 m0, s41
	s_nop 0
	global_load_lds_dwordx4 v[158:159], off
	s_mov_b32 m0, s47
	v_lshl_add_u64 v[158:159], s[52:53], 0, v[2:3]
	s_mov_b32 s47, m0
	s_mov_b32 m0, s42
	s_nop 0
	global_load_lds_dwordx4 v[158:159], off
	s_mov_b32 m0, s47
	v_lshl_add_u64 v[158:159], s[50:51], 0, v[4:5]
	s_mov_b32 s47, m0
	s_mov_b32 m0, s43
	s_nop 0
	global_load_lds_dwordx4 v[158:159], off
	s_mov_b32 m0, s47
	v_lshl_add_u64 v[158:159], s[52:53], 0, v[4:5]
	s_mov_b32 s47, m0
	s_mov_b32 m0, s44
	s_nop 0
	global_load_lds_dwordx4 v[158:159], off
	s_mov_b32 m0, s47
	v_lshl_add_u64 v[158:159], s[50:51], 0, v[146:147]
	s_mov_b32 s47, m0
	s_mov_b32 m0, s45
	s_nop 0
	global_load_lds_dwordx4 v[158:159], off
	s_mov_b32 m0, s47
	v_lshl_add_u64 v[158:159], s[52:53], 0, v[146:147]
	s_mov_b32 s47, m0
	s_mov_b32 m0, s46
	s_nop 0
	global_load_lds_dwordx4 v[158:159], off
	s_mov_b32 m0, s47
	ds_read_b128 v[158:161], v7 offset:32768
	ds_read_b128 v[162:165], v7 offset:34816
	ds_read_b128 v[166:169], v7 offset:36864
	ds_read_b128 v[178:181], v7 offset:38912
	ds_read_b128 v[174:177], v6
	ds_read_b128 v[218:221], v6 offset:2048
	ds_read_b128 v[222:225], v6 offset:4096
	ds_read_b128 v[226:229], v6 offset:6144
	s_waitcnt lgkmcnt(3)
	v_mfma_f32_16x16x32_bf16 v[40:43], v[158:161], v[174:177], v[40:43]
	v_mfma_f32_16x16x32_bf16 v[44:47], v[162:165], v[174:177], v[44:47]
	v_mfma_f32_16x16x32_bf16 v[48:51], v[166:169], v[174:177], v[48:51]
	v_mfma_f32_16x16x32_bf16 v[174:177], v[178:181], v[174:177], v[214:217]
	s_nop 2
	ds_read_b128 v[214:217], v6 offset:8192
	s_waitcnt lgkmcnt(3)
	v_mfma_f32_16x16x32_bf16 v[56:59], v[158:161], v[218:221], v[56:59]
	v_mfma_f32_16x16x32_bf16 v[60:63], v[162:165], v[218:221], v[60:63]
	v_mfma_f32_16x16x32_bf16 v[64:67], v[166:169], v[218:221], v[64:67]
	v_mfma_f32_16x16x32_bf16 v[170:173], v[178:181], v[218:221], v[170:173]
	ds_read_b128 v[218:221], v6 offset:10240
	s_waitcnt lgkmcnt(3)
	v_mfma_f32_16x16x32_bf16 v[72:75], v[158:161], v[222:225], v[72:75]
	v_mfma_f32_16x16x32_bf16 v[76:79], v[162:165], v[222:225], v[76:79]
	v_mfma_f32_16x16x32_bf16 v[80:83], v[166:169], v[222:225], v[80:83]
	v_mfma_f32_16x16x32_bf16 v[32:35], v[178:181], v[222:225], v[32:35]
	ds_read_b128 v[222:225], v6 offset:12288
	s_waitcnt lgkmcnt(3)
	v_mfma_f32_16x16x32_bf16 v[88:91], v[158:161], v[226:229], v[88:91]
	v_mfma_f32_16x16x32_bf16 v[92:95], v[162:165], v[226:229], v[92:95]
	v_mfma_f32_16x16x32_bf16 v[96:99], v[166:169], v[226:229], v[96:99]
	v_mfma_f32_16x16x32_bf16 v[36:39], v[178:181], v[226:229], v[36:39]
	ds_read_b128 v[226:229], v6 offset:14336
	s_waitcnt lgkmcnt(3)
	v_mfma_f32_16x16x32_bf16 v[104:107], v[158:161], v[214:217], v[104:107]
	v_mfma_f32_16x16x32_bf16 v[108:111], v[162:165], v[214:217], v[108:111]
	v_mfma_f32_16x16x32_bf16 v[112:115], v[166:169], v[214:217], v[112:115]
	v_mfma_f32_16x16x32_bf16 v[52:55], v[178:181], v[214:217], v[52:55]
	s_waitcnt lgkmcnt(2)
	v_mfma_f32_16x16x32_bf16 v[116:119], v[158:161], v[218:221], v[116:119]
	v_mfma_f32_16x16x32_bf16 v[120:123], v[162:165], v[218:221], v[120:123]
	v_mfma_f32_16x16x32_bf16 v[124:127], v[166:169], v[218:221], v[124:127]
	v_mfma_f32_16x16x32_bf16 v[68:71], v[178:181], v[218:221], v[68:71]
	s_waitcnt lgkmcnt(1)
	v_mfma_f32_16x16x32_bf16 v[132:135], v[162:165], v[222:225], v[132:135]
	v_mfma_f32_16x16x32_bf16 v[84:87], v[178:181], v[222:225], v[84:87]
	s_waitcnt lgkmcnt(0)
	v_mfma_f32_16x16x32_bf16 v[100:103], v[158:161], v[226:229], v[100:103]
	v_mfma_f32_16x16x32_bf16 v[150:153], v[166:169], v[226:229], v[150:153]
	v_mfma_f32_16x16x32_bf16 v[154:157], v[178:181], v[226:229], v[154:157]
	v_mfma_f32_16x16x32_bf16 v[128:131], v[158:161], v[222:225], v[128:131]
	v_mfma_f32_16x16x32_bf16 v[136:139], v[166:169], v[222:225], v[136:139]
	v_mfma_f32_16x16x32_bf16 v[140:143], v[162:165], v[226:229], v[140:143]
	ds_read_b128 v[158:161], v7 offset:33792
	ds_read_b128 v[162:165], v7 offset:35840
	ds_read_b128 v[166:169], v7 offset:37888
	ds_read_b128 v[214:217], v7 offset:39936
	ds_read_b128 v[178:181], v6 offset:1024
	ds_read_b128 v[218:221], v6 offset:3072
	ds_read_b128 v[222:225], v6 offset:5120
	ds_read_b128 v[226:229], v6 offset:7168
	s_waitcnt lgkmcnt(3)
	v_mfma_f32_16x16x32_bf16 v[40:43], v[158:161], v[178:181], v[40:43]
	v_mfma_f32_16x16x32_bf16 v[44:47], v[162:165], v[178:181], v[44:47]
	v_mfma_f32_16x16x32_bf16 v[48:51], v[166:169], v[178:181], v[48:51]
	v_mfma_f32_16x16x32_bf16 v[174:177], v[214:217], v[178:181], v[174:177]
	ds_read_b128 v[178:181], v6 offset:9216
	s_waitcnt lgkmcnt(3)
	v_mfma_f32_16x16x32_bf16 v[56:59], v[158:161], v[218:221], v[56:59]
	v_mfma_f32_16x16x32_bf16 v[60:63], v[162:165], v[218:221], v[60:63]
	v_mfma_f32_16x16x32_bf16 v[64:67], v[166:169], v[218:221], v[64:67]
	v_mfma_f32_16x16x32_bf16 v[170:173], v[214:217], v[218:221], v[170:173]
	ds_read_b128 v[218:221], v6 offset:11264
	s_waitcnt lgkmcnt(3)
	v_mfma_f32_16x16x32_bf16 v[72:75], v[158:161], v[222:225], v[72:75]
	v_mfma_f32_16x16x32_bf16 v[76:79], v[162:165], v[222:225], v[76:79]
	v_mfma_f32_16x16x32_bf16 v[80:83], v[166:169], v[222:225], v[80:83]
	v_mfma_f32_16x16x32_bf16 v[32:35], v[214:217], v[222:225], v[32:35]
	ds_read_b128 v[222:225], v6 offset:13312
	s_waitcnt lgkmcnt(3)
	v_mfma_f32_16x16x32_bf16 v[88:91], v[158:161], v[226:229], v[88:91]
	v_mfma_f32_16x16x32_bf16 v[92:95], v[162:165], v[226:229], v[92:95]
	v_mfma_f32_16x16x32_bf16 v[96:99], v[166:169], v[226:229], v[96:99]
	v_mfma_f32_16x16x32_bf16 v[36:39], v[214:217], v[226:229], v[36:39]
	ds_read_b128 v[226:229], v6 offset:15360
	s_waitcnt lgkmcnt(3)
	v_mfma_f32_16x16x32_bf16 v[104:107], v[158:161], v[178:181], v[104:107]
	v_mfma_f32_16x16x32_bf16 v[108:111], v[162:165], v[178:181], v[108:111]
	v_mfma_f32_16x16x32_bf16 v[112:115], v[166:169], v[178:181], v[112:115]
	v_mfma_f32_16x16x32_bf16 v[52:55], v[214:217], v[178:181], v[52:55]
	s_waitcnt lgkmcnt(2)
	v_mfma_f32_16x16x32_bf16 v[116:119], v[158:161], v[218:221], v[116:119]
	v_mfma_f32_16x16x32_bf16 v[120:123], v[162:165], v[218:221], v[120:123]
	v_mfma_f32_16x16x32_bf16 v[124:127], v[166:169], v[218:221], v[124:127]
	v_mfma_f32_16x16x32_bf16 v[68:71], v[214:217], v[218:221], v[68:71]
	s_waitcnt lgkmcnt(1)
	v_mfma_f32_16x16x32_bf16 v[132:135], v[162:165], v[222:225], v[132:135]
	v_mfma_f32_16x16x32_bf16 v[84:87], v[214:217], v[222:225], v[84:87]
	s_waitcnt lgkmcnt(0)
	v_mfma_f32_16x16x32_bf16 v[100:103], v[158:161], v[226:229], v[100:103]
	v_mfma_f32_16x16x32_bf16 v[150:153], v[166:169], v[226:229], v[150:153]
	v_mfma_f32_16x16x32_bf16 v[154:157], v[214:217], v[226:229], v[154:157]
	v_mfma_f32_16x16x32_bf16 v[128:131], v[158:161], v[222:225], v[128:131]
	v_mfma_f32_16x16x32_bf16 v[136:139], v[166:169], v[222:225], v[136:139]
	v_mfma_f32_16x16x32_bf16 v[140:143], v[162:165], v[226:229], v[140:143]
	s_add_u32 s50, s14, 0x200
	s_addc_u32 s51, s15, 0
	s_add_u32 s52, s20, 0x200
	s_waitcnt vmcnt(0)
	s_barrier
	s_addc_u32 s53, s21, 0
	s_mov_b32 s47, 0x280
	ds_read_b128 v[158:161], v8
	ds_read_b128 v[162:165], v12
	ds_read_b128 v[166:169], v9
	ds_read_b128 v[178:181], v13
	ds_read_b128 v[214:217], v11
	ds_read_b128 v[218:221], v10
	ds_read_b128 v[222:225], v14
	ds_read_b128 v[226:229], v15
	s_branch .Lmy_rot_r_r2a

.Lmy_rot_r_r2a:
	s_waitcnt lgkmcnt(6)
	v_mfma_f32_16x16x32_bf16 v[40:43], v[158:161], v[162:165], v[40:43]
	s_waitcnt lgkmcnt(5)
	v_mfma_f32_16x16x32_bf16 v[44:47], v[166:169], v[162:165], v[44:47]
	s_waitcnt lgkmcnt(4)
	s_mov_b32 m0, s1
	v_mfma_f32_16x16x32_bf16 v[56:59], v[158:161], v[178:181], v[56:59]
	global_load_lds_dwordx4 v0, s[50:51]
	v_mfma_f32_16x16x32_bf16 v[60:63], v[166:169], v[178:181], v[60:63]
	s_waitcnt lgkmcnt(3)
	v_mfma_f32_16x16x32_bf16 v[48:51], v[214:217], v[162:165], v[48:51]
	v_mfma_f32_16x16x32_bf16 v[64:67], v[214:217], v[178:181], v[64:67]
	s_waitcnt lgkmcnt(2)
	s_mov_b32 m0, s34
	v_mfma_f32_16x16x32_bf16 v[174:177], v[218:221], v[162:165], v[174:177]
	global_load_lds_dwordx4 v0, s[52:53]
	ds_read_b128 v[162:165], v16
	v_mfma_f32_16x16x32_bf16 v[170:173], v[218:221], v[178:181], v[170:173]
	ds_read_b128 v[178:181], v17
	s_waitcnt lgkmcnt(3)
	v_mfma_f32_16x16x32_bf16 v[72:75], v[158:161], v[222:225], v[72:75]
	v_mfma_f32_16x16x32_bf16 v[76:79], v[166:169], v[222:225], v[76:79]
	s_mov_b32 m0, s35
	v_mfma_f32_16x16x32_bf16 v[80:83], v[214:217], v[222:225], v[80:83]
	global_load_lds_dwordx4 v2, s[50:51]
	v_mfma_f32_16x16x32_bf16 v[32:35], v[218:221], v[222:225], v[32:35]
	ds_read_b128 v[222:225], v18
	s_waitcnt lgkmcnt(3)
	v_mfma_f32_16x16x32_bf16 v[88:91], v[158:161], v[226:229], v[88:91]
	v_mfma_f32_16x16x32_bf16 v[92:95], v[166:169], v[226:229], v[92:95]
	s_mov_b32 m0, s36
	v_mfma_f32_16x16x32_bf16 v[96:99], v[214:217], v[226:229], v[96:99]
	global_load_lds_dwordx4 v2, s[52:53]
	v_mfma_f32_16x16x32_bf16 v[36:39], v[218:221], v[226:229], v[36:39]
	ds_read_b128 v[226:229], v19
	s_waitcnt lgkmcnt(3)
	v_mfma_f32_16x16x32_bf16 v[108:111], v[166:169], v[162:165], v[108:111]
	s_waitcnt lgkmcnt(2)
	v_mfma_f32_16x16x32_bf16 v[120:123], v[166:169], v[178:181], v[120:123]
	s_waitcnt lgkmcnt(1)
	s_mov_b32 m0, s37
	v_mfma_f32_16x16x32_bf16 v[132:135], v[166:169], v[222:225], v[132:135]
	global_load_lds_dwordx4 v4, s[50:51]
	s_waitcnt lgkmcnt(0)
	v_mfma_f32_16x16x32_bf16 v[140:143], v[166:169], v[226:229], v[140:143]
	ds_read_b128 v[166:169], v20
	v_mfma_f32_16x16x32_bf16 v[104:107], v[158:161], v[162:165], v[104:107]
	v_mfma_f32_16x16x32_bf16 v[116:119], v[158:161], v[178:181], v[116:119]
	s_mov_b32 m0, s38
	v_mfma_f32_16x16x32_bf16 v[128:131], v[158:161], v[222:225], v[128:131]
	global_load_lds_dwordx4 v4, s[52:53]
	v_mfma_f32_16x16x32_bf16 v[100:103], v[158:161], v[226:229], v[100:103]
	ds_read_b128 v[158:161], v24
	v_mfma_f32_16x16x32_bf16 v[124:127], v[214:217], v[178:181], v[124:127]
	v_mfma_f32_16x16x32_bf16 v[68:71], v[218:221], v[178:181], v[68:71]
	ds_read_b128 v[178:181], v21
	s_mov_b32 m0, s39
	v_mfma_f32_16x16x32_bf16 v[112:115], v[214:217], v[162:165], v[112:115]
	global_load_lds_dwordx4 v146, s[50:51]
	v_mfma_f32_16x16x32_bf16 v[52:55], v[218:221], v[162:165], v[52:55]
	ds_read_b128 v[162:165], v25
	v_mfma_f32_16x16x32_bf16 v[136:139], v[214:217], v[222:225], v[136:139]
	v_mfma_f32_16x16x32_bf16 v[84:87], v[218:221], v[222:225], v[84:87]
	ds_read_b128 v[222:225], v26
	s_mov_b32 m0, s40
	v_mfma_f32_16x16x32_bf16 v[150:153], v[214:217], v[226:229], v[150:153]
	global_load_lds_dwordx4 v146, s[52:53]
	ds_read_b128 v[214:217], v23
	v_mfma_f32_16x16x32_bf16 v[154:157], v[218:221], v[226:229], v[154:157]
	ds_read_b128 v[218:221], v22
	ds_read_b128 v[226:229], v27
	s_waitcnt lgkmcnt(6)
	v_mfma_f32_16x16x32_bf16 v[40:43], v[166:169], v[158:161], v[40:43]
	s_waitcnt lgkmcnt(5)
	v_mfma_f32_16x16x32_bf16 v[44:47], v[178:181], v[158:161], v[44:47]
	s_waitcnt lgkmcnt(4)
	v_mfma_f32_16x16x32_bf16 v[56:59], v[166:169], v[162:165], v[56:59]
	v_mfma_f32_16x16x32_bf16 v[60:63], v[178:181], v[162:165], v[60:63]
	s_waitcnt lgkmcnt(3)
	v_mfma_f32_16x16x32_bf16 v[72:75], v[166:169], v[222:225], v[72:75]
	v_mfma_f32_16x16x32_bf16 v[76:79], v[178:181], v[222:225], v[76:79]
	s_waitcnt lgkmcnt(2)
	v_mfma_f32_16x16x32_bf16 v[48:51], v[214:217], v[158:161], v[48:51]
	s_waitcnt lgkmcnt(1)
	v_mfma_f32_16x16x32_bf16 v[174:177], v[218:221], v[158:161], v[174:177]
	ds_read_b128 v[158:161], v28
	v_mfma_f32_16x16x32_bf16 v[64:67], v[214:217], v[162:165], v[64:67]
	v_mfma_f32_16x16x32_bf16 v[170:173], v[218:221], v[162:165], v[170:173]
	ds_read_b128 v[162:165], v29
	v_mfma_f32_16x16x32_bf16 v[80:83], v[214:217], v[222:225], v[80:83]
	v_mfma_f32_16x16x32_bf16 v[32:35], v[218:221], v[222:225], v[32:35]
	ds_read_b128 v[222:225], v30
	s_waitcnt lgkmcnt(3)
	v_mfma_f32_16x16x32_bf16 v[88:91], v[166:169], v[226:229], v[88:91]
	v_mfma_f32_16x16x32_bf16 v[92:95], v[178:181], v[226:229], v[92:95]
	v_mfma_f32_16x16x32_bf16 v[96:99], v[214:217], v[226:229], v[96:99]
	v_mfma_f32_16x16x32_bf16 v[36:39], v[218:221], v[226:229], v[36:39]
	ds_read_b128 v[226:229], v31
	s_waitcnt lgkmcnt(3)
	v_mfma_f32_16x16x32_bf16 v[104:107], v[166:169], v[158:161], v[104:107]
	v_mfma_f32_16x16x32_bf16 v[108:111], v[178:181], v[158:161], v[108:111]
	v_mfma_f32_16x16x32_bf16 v[112:115], v[214:217], v[158:161], v[112:115]
	v_mfma_f32_16x16x32_bf16 v[52:55], v[218:221], v[158:161], v[52:55]
	s_waitcnt lgkmcnt(2)
	v_mfma_f32_16x16x32_bf16 v[116:119], v[166:169], v[162:165], v[116:119]
	v_mfma_f32_16x16x32_bf16 v[120:123], v[178:181], v[162:165], v[120:123]
	v_mfma_f32_16x16x32_bf16 v[124:127], v[214:217], v[162:165], v[124:127]
	v_mfma_f32_16x16x32_bf16 v[68:71], v[218:221], v[162:165], v[68:71]
	s_add_u32 s50, s14, s47
	s_addc_u32 s51, s15, 0
	s_add_u32 s52, s20, s47
	s_addc_u32 s53, s21, 0
	s_add_u32 s47, s47, 0x80
	s_waitcnt vmcnt(0)
	s_waitcnt lgkmcnt(0)
	s_barrier
	ds_read_b128 v[158:161], v7 offset:32768
	ds_read_b128 v[162:165], v6
	v_mfma_f32_16x16x32_bf16 v[128:131], v[166:169], v[222:225], v[128:131]
	v_mfma_f32_16x16x32_bf16 v[100:103], v[166:169], v[226:229], v[100:103]
	ds_read_b128 v[166:169], v7 offset:34816
	v_mfma_f32_16x16x32_bf16 v[132:135], v[178:181], v[222:225], v[132:135]
	v_mfma_f32_16x16x32_bf16 v[140:143], v[178:181], v[226:229], v[140:143]
	ds_read_b128 v[178:181], v6 offset:2048
	v_mfma_f32_16x16x32_bf16 v[136:139], v[214:217], v[222:225], v[136:139]
	v_mfma_f32_16x16x32_bf16 v[150:153], v[214:217], v[226:229], v[150:153]
	ds_read_b128 v[214:217], v7 offset:36864
	v_mfma_f32_16x16x32_bf16 v[84:87], v[218:221], v[222:225], v[84:87]
	v_mfma_f32_16x16x32_bf16 v[154:157], v[218:221], v[226:229], v[154:157]
	ds_read_b128 v[218:221], v7 offset:38912
	ds_read_b128 v[222:225], v6 offset:4096
	ds_read_b128 v[226:229], v6 offset:6144
	s_waitcnt lgkmcnt(6)
	v_mfma_f32_16x16x32_bf16 v[40:43], v[158:161], v[162:165], v[40:43]
	s_waitcnt lgkmcnt(5)
	v_mfma_f32_16x16x32_bf16 v[44:47], v[166:169], v[162:165], v[44:47]
	s_waitcnt lgkmcnt(4)
	s_mov_b32 m0, s27
	v_mfma_f32_16x16x32_bf16 v[56:59], v[158:161], v[178:181], v[56:59]
	global_load_lds_dwordx4 v0, s[50:51]
	v_mfma_f32_16x16x32_bf16 v[60:63], v[166:169], v[178:181], v[60:63]
	s_waitcnt lgkmcnt(3)
	v_mfma_f32_16x16x32_bf16 v[48:51], v[214:217], v[162:165], v[48:51]
	v_mfma_f32_16x16x32_bf16 v[64:67], v[214:217], v[178:181], v[64:67]
	s_waitcnt lgkmcnt(2)
	s_mov_b32 m0, s26
	v_mfma_f32_16x16x32_bf16 v[174:177], v[218:221], v[162:165], v[174:177]
	global_load_lds_dwordx4 v0, s[52:53]
	ds_read_b128 v[162:165], v6 offset:8192
	v_mfma_f32_16x16x32_bf16 v[170:173], v[218:221], v[178:181], v[170:173]
	ds_read_b128 v[178:181], v6 offset:10240
	s_waitcnt lgkmcnt(3)
	v_mfma_f32_16x16x32_bf16 v[72:75], v[158:161], v[222:225], v[72:75]
	v_mfma_f32_16x16x32_bf16 v[76:79], v[166:169], v[222:225], v[76:79]
	s_mov_b32 m0, s41
	v_mfma_f32_16x16x32_bf16 v[80:83], v[214:217], v[222:225], v[80:83]
	global_load_lds_dwordx4 v2, s[50:51]
	v_mfma_f32_16x16x32_bf16 v[32:35], v[218:221], v[222:225], v[32:35]
	ds_read_b128 v[222:225], v6 offset:12288
	s_waitcnt lgkmcnt(3)
	v_mfma_f32_16x16x32_bf16 v[88:91], v[158:161], v[226:229], v[88:91]
	v_mfma_f32_16x16x32_bf16 v[92:95], v[166:169], v[226:229], v[92:95]
	s_mov_b32 m0, s42
	v_mfma_f32_16x16x32_bf16 v[96:99], v[214:217], v[226:229], v[96:99]
	global_load_lds_dwordx4 v2, s[52:53]
	v_mfma_f32_16x16x32_bf16 v[36:39], v[218:221], v[226:229], v[36:39]
	ds_read_b128 v[226:229], v6 offset:14336
	s_waitcnt lgkmcnt(3)
	v_mfma_f32_16x16x32_bf16 v[108:111], v[166:169], v[162:165], v[108:111]
	s_waitcnt lgkmcnt(2)
	v_mfma_f32_16x16x32_bf16 v[120:123], v[166:169], v[178:181], v[120:123]
	s_waitcnt lgkmcnt(1)
	s_mov_b32 m0, s43
	v_mfma_f32_16x16x32_bf16 v[132:135], v[166:169], v[222:225], v[132:135]
	global_load_lds_dwordx4 v4, s[50:51]
	s_waitcnt lgkmcnt(0)
	v_mfma_f32_16x16x32_bf16 v[140:143], v[166:169], v[226:229], v[140:143]
	ds_read_b128 v[166:169], v7 offset:33792
	v_mfma_f32_16x16x32_bf16 v[104:107], v[158:161], v[162:165], v[104:107]
	v_mfma_f32_16x16x32_bf16 v[116:119], v[158:161], v[178:181], v[116:119]
	s_mov_b32 m0, s44
	v_mfma_f32_16x16x32_bf16 v[128:131], v[158:161], v[222:225], v[128:131]
	global_load_lds_dwordx4 v4, s[52:53]
	v_mfma_f32_16x16x32_bf16 v[100:103], v[158:161], v[226:229], v[100:103]
	ds_read_b128 v[158:161], v6 offset:1024
	v_mfma_f32_16x16x32_bf16 v[124:127], v[214:217], v[178:181], v[124:127]
	v_mfma_f32_16x16x32_bf16 v[68:71], v[218:221], v[178:181], v[68:71]
	ds_read_b128 v[178:181], v7 offset:35840
	s_mov_b32 m0, s45
	v_mfma_f32_16x16x32_bf16 v[112:115], v[214:217], v[162:165], v[112:115]
	global_load_lds_dwordx4 v146, s[50:51]
	v_mfma_f32_16x16x32_bf16 v[52:55], v[218:221], v[162:165], v[52:55]
	ds_read_b128 v[162:165], v6 offset:3072
	v_mfma_f32_16x16x32_bf16 v[136:139], v[214:217], v[222:225], v[136:139]
	v_mfma_f32_16x16x32_bf16 v[84:87], v[218:221], v[222:225], v[84:87]
	ds_read_b128 v[222:225], v6 offset:5120
	s_mov_b32 m0, s46
	v_mfma_f32_16x16x32_bf16 v[150:153], v[214:217], v[226:229], v[150:153]
	global_load_lds_dwordx4 v146, s[52:53]
	ds_read_b128 v[214:217], v7 offset:37888
	v_mfma_f32_16x16x32_bf16 v[154:157], v[218:221], v[226:229], v[154:157]
	ds_read_b128 v[218:221], v7 offset:39936
	ds_read_b128 v[226:229], v6 offset:7168
	s_waitcnt lgkmcnt(6)
	v_mfma_f32_16x16x32_bf16 v[40:43], v[166:169], v[158:161], v[40:43]
	s_waitcnt lgkmcnt(5)
	v_mfma_f32_16x16x32_bf16 v[44:47], v[178:181], v[158:161], v[44:47]
	s_waitcnt lgkmcnt(4)
	v_mfma_f32_16x16x32_bf16 v[56:59], v[166:169], v[162:165], v[56:59]
	v_mfma_f32_16x16x32_bf16 v[60:63], v[178:181], v[162:165], v[60:63]
	s_waitcnt lgkmcnt(3)
	v_mfma_f32_16x16x32_bf16 v[72:75], v[166:169], v[222:225], v[72:75]
	v_mfma_f32_16x16x32_bf16 v[76:79], v[178:181], v[222:225], v[76:79]
	s_waitcnt lgkmcnt(2)
	v_mfma_f32_16x16x32_bf16 v[48:51], v[214:217], v[158:161], v[48:51]
	s_waitcnt lgkmcnt(1)
	v_mfma_f32_16x16x32_bf16 v[174:177], v[218:221], v[158:161], v[174:177]
	ds_read_b128 v[158:161], v6 offset:9216
	v_mfma_f32_16x16x32_bf16 v[64:67], v[214:217], v[162:165], v[64:67]
	v_mfma_f32_16x16x32_bf16 v[170:173], v[218:221], v[162:165], v[170:173]
	ds_read_b128 v[162:165], v6 offset:11264
	v_mfma_f32_16x16x32_bf16 v[80:83], v[214:217], v[222:225], v[80:83]
	v_mfma_f32_16x16x32_bf16 v[32:35], v[218:221], v[222:225], v[32:35]
	ds_read_b128 v[222:225], v6 offset:13312
	s_waitcnt lgkmcnt(3)
	v_mfma_f32_16x16x32_bf16 v[88:91], v[166:169], v[226:229], v[88:91]
	v_mfma_f32_16x16x32_bf16 v[92:95], v[178:181], v[226:229], v[92:95]
	v_mfma_f32_16x16x32_bf16 v[96:99], v[214:217], v[226:229], v[96:99]
	v_mfma_f32_16x16x32_bf16 v[36:39], v[218:221], v[226:229], v[36:39]
	ds_read_b128 v[226:229], v6 offset:15360
	s_waitcnt lgkmcnt(3)
	v_mfma_f32_16x16x32_bf16 v[104:107], v[166:169], v[158:161], v[104:107]
	v_mfma_f32_16x16x32_bf16 v[108:111], v[178:181], v[158:161], v[108:111]
	v_mfma_f32_16x16x32_bf16 v[112:115], v[214:217], v[158:161], v[112:115]
	v_mfma_f32_16x16x32_bf16 v[52:55], v[218:221], v[158:161], v[52:55]
	s_waitcnt lgkmcnt(2)
	v_mfma_f32_16x16x32_bf16 v[116:119], v[166:169], v[162:165], v[116:119]
	v_mfma_f32_16x16x32_bf16 v[120:123], v[178:181], v[162:165], v[120:123]
	v_mfma_f32_16x16x32_bf16 v[124:127], v[214:217], v[162:165], v[124:127]
	v_mfma_f32_16x16x32_bf16 v[68:71], v[218:221], v[162:165], v[68:71]
	s_add_u32 s50, s14, s47
	s_addc_u32 s51, s15, 0
	s_add_u32 s52, s20, s47
	s_addc_u32 s53, s21, 0
	s_add_u32 s47, s47, 0x80
	s_cmp_lg_u32 s47, 0xf80
	s_waitcnt vmcnt(0)
	s_waitcnt lgkmcnt(0)
	s_barrier
	s_cbranch_scc1 .Lmy_rr_r2a
	v_mfma_f32_16x16x32_bf16 v[128:131], v[166:169], v[222:225], v[128:131]
	v_mfma_f32_16x16x32_bf16 v[100:103], v[166:169], v[226:229], v[100:103]
	v_mfma_f32_16x16x32_bf16 v[132:135], v[178:181], v[222:225], v[132:135]
	v_mfma_f32_16x16x32_bf16 v[140:143], v[178:181], v[226:229], v[140:143]
	v_mfma_f32_16x16x32_bf16 v[136:139], v[214:217], v[222:225], v[136:139]
	v_mfma_f32_16x16x32_bf16 v[150:153], v[214:217], v[226:229], v[150:153]
	v_mfma_f32_16x16x32_bf16 v[84:87], v[218:221], v[222:225], v[84:87]
	v_mfma_f32_16x16x32_bf16 v[154:157], v[218:221], v[226:229], v[154:157]
	s_nop 15
	s_nop 15
	v_lshl_add_u64 v[158:159], s[50:51], 0, v[0:1]
	s_mov_b32 s47, m0
	s_mov_b32 m0, s1
	s_nop 0
	global_load_lds_dwordx4 v[158:159], off
	s_mov_b32 m0, s47
	v_lshl_add_u64 v[158:159], s[52:53], 0, v[0:1]
	s_mov_b32 s47, m0
	s_mov_b32 m0, s34
	s_nop 0
	global_load_lds_dwordx4 v[158:159], off
	s_mov_b32 m0, s47
	v_lshl_add_u64 v[158:159], s[50:51], 0, v[2:3]
	s_mov_b32 s47, m0
	s_mov_b32 m0, s35
	s_nop 0
	global_load_lds_dwordx4 v[158:159], off
	s_mov_b32 m0, s47
	v_lshl_add_u64 v[158:159], s[52:53], 0, v[2:3]
	s_mov_b32 s47, m0
	s_mov_b32 m0, s36
	s_nop 0
	global_load_lds_dwordx4 v[158:159], off
	s_mov_b32 m0, s47
	v_lshl_add_u64 v[158:159], s[50:51], 0, v[4:5]
	s_mov_b32 s47, m0
	s_mov_b32 m0, s37
	s_nop 0
	global_load_lds_dwordx4 v[158:159], off
	s_mov_b32 m0, s47
	v_lshl_add_u64 v[158:159], s[52:53], 0, v[4:5]
	s_mov_b32 s47, m0
	s_mov_b32 m0, s38
	s_nop 0
	global_load_lds_dwordx4 v[158:159], off
	s_mov_b32 m0, s47
	v_lshl_add_u64 v[158:159], s[50:51], 0, v[146:147]
	s_mov_b32 s47, m0
	s_mov_b32 m0, s39
	s_nop 0
	global_load_lds_dwordx4 v[158:159], off
	s_mov_b32 m0, s47
	v_lshl_add_u64 v[158:159], s[52:53], 0, v[146:147]
	s_mov_b32 s47, m0
	s_mov_b32 m0, s40
	s_nop 0
	global_load_lds_dwordx4 v[158:159], off
	s_mov_b32 m0, s47
	ds_read_b128 v[158:161], v8
	ds_read_b128 v[162:165], v9
	ds_read_b128 v[166:169], v11
	ds_read_b128 v[214:217], v10
	ds_read_b128 v[178:181], v12
	ds_read_b128 v[218:221], v13
	ds_read_b128 v[222:225], v14
	ds_read_b128 v[226:229], v15
	s_waitcnt lgkmcnt(3)
	v_mfma_f32_16x16x32_bf16 v[40:43], v[158:161], v[178:181], v[40:43]
	v_mfma_f32_16x16x32_bf16 v[44:47], v[162:165], v[178:181], v[44:47]
	v_mfma_f32_16x16x32_bf16 v[48:51], v[166:169], v[178:181], v[48:51]
	v_mfma_f32_16x16x32_bf16 v[174:177], v[214:217], v[178:181], v[174:177]
	ds_read_b128 v[178:181], v16
	s_waitcnt lgkmcnt(3)
	v_mfma_f32_16x16x32_bf16 v[56:59], v[158:161], v[218:221], v[56:59]
	v_mfma_f32_16x16x32_bf16 v[60:63], v[162:165], v[218:221], v[60:63]
	v_mfma_f32_16x16x32_bf16 v[64:67], v[166:169], v[218:221], v[64:67]
	v_mfma_f32_16x16x32_bf16 v[170:173], v[214:217], v[218:221], v[170:173]
	ds_read_b128 v[218:221], v17
	s_waitcnt lgkmcnt(3)
	v_mfma_f32_16x16x32_bf16 v[72:75], v[158:161], v[222:225], v[72:75]
	v_mfma_f32_16x16x32_bf16 v[76:79], v[162:165], v[222:225], v[76:79]
	v_mfma_f32_16x16x32_bf16 v[80:83], v[166:169], v[222:225], v[80:83]
	v_mfma_f32_16x16x32_bf16 v[32:35], v[214:217], v[222:225], v[32:35]
	ds_read_b128 v[222:225], v18
	s_waitcnt lgkmcnt(3)
	v_mfma_f32_16x16x32_bf16 v[88:91], v[158:161], v[226:229], v[88:91]
	v_mfma_f32_16x16x32_bf16 v[92:95], v[162:165], v[226:229], v[92:95]
	v_mfma_f32_16x16x32_bf16 v[96:99], v[166:169], v[226:229], v[96:99]
	v_mfma_f32_16x16x32_bf16 v[36:39], v[214:217], v[226:229], v[36:39]
	ds_read_b128 v[226:229], v19
	s_waitcnt lgkmcnt(3)
	v_mfma_f32_16x16x32_bf16 v[104:107], v[158:161], v[178:181], v[104:107]
	v_mfma_f32_16x16x32_bf16 v[108:111], v[162:165], v[178:181], v[108:111]
	v_mfma_f32_16x16x32_bf16 v[112:115], v[166:169], v[178:181], v[112:115]
	v_mfma_f32_16x16x32_bf16 v[52:55], v[214:217], v[178:181], v[52:55]
	s_waitcnt lgkmcnt(2)
	v_mfma_f32_16x16x32_bf16 v[116:119], v[158:161], v[218:221], v[116:119]
	v_mfma_f32_16x16x32_bf16 v[120:123], v[162:165], v[218:221], v[120:123]
	v_mfma_f32_16x16x32_bf16 v[124:127], v[166:169], v[218:221], v[124:127]
	v_mfma_f32_16x16x32_bf16 v[68:71], v[214:217], v[218:221], v[68:71]
	s_waitcnt lgkmcnt(1)
	v_mfma_f32_16x16x32_bf16 v[132:135], v[162:165], v[222:225], v[132:135]
	v_mfma_f32_16x16x32_bf16 v[84:87], v[214:217], v[222:225], v[84:87]
	s_waitcnt lgkmcnt(0)
	v_mfma_f32_16x16x32_bf16 v[100:103], v[158:161], v[226:229], v[100:103]
	v_mfma_f32_16x16x32_bf16 v[150:153], v[166:169], v[226:229], v[150:153]
	v_mfma_f32_16x16x32_bf16 v[154:157], v[214:217], v[226:229], v[154:157]
	v_mfma_f32_16x16x32_bf16 v[128:131], v[158:161], v[222:225], v[128:131]
	v_mfma_f32_16x16x32_bf16 v[136:139], v[166:169], v[222:225], v[136:139]
	v_mfma_f32_16x16x32_bf16 v[140:143], v[162:165], v[226:229], v[140:143]
	ds_read_b128 v[158:161], v20
	ds_read_b128 v[162:165], v21
	ds_read_b128 v[166:169], v23
	ds_read_b128 v[214:217], v22
	ds_read_b128 v[178:181], v24
	ds_read_b128 v[218:221], v25
	ds_read_b128 v[222:225], v26
	ds_read_b128 v[226:229], v27
	s_waitcnt lgkmcnt(3)
	v_mfma_f32_16x16x32_bf16 v[40:43], v[158:161], v[178:181], v[40:43]
	v_mfma_f32_16x16x32_bf16 v[44:47], v[162:165], v[178:181], v[44:47]
	v_mfma_f32_16x16x32_bf16 v[48:51], v[166:169], v[178:181], v[48:51]
	v_mfma_f32_16x16x32_bf16 v[174:177], v[214:217], v[178:181], v[174:177]
	ds_read_b128 v[178:181], v28
	s_waitcnt lgkmcnt(3)
	v_mfma_f32_16x16x32_bf16 v[56:59], v[158:161], v[218:221], v[56:59]
	v_mfma_f32_16x16x32_bf16 v[60:63], v[162:165], v[218:221], v[60:63]
	v_mfma_f32_16x16x32_bf16 v[64:67], v[166:169], v[218:221], v[64:67]
	v_mfma_f32_16x16x32_bf16 v[170:173], v[214:217], v[218:221], v[170:173]
	ds_read_b128 v[218:221], v29
	s_waitcnt lgkmcnt(3)
	v_mfma_f32_16x16x32_bf16 v[72:75], v[158:161], v[222:225], v[72:75]
	v_mfma_f32_16x16x32_bf16 v[76:79], v[162:165], v[222:225], v[76:79]
	v_mfma_f32_16x16x32_bf16 v[80:83], v[166:169], v[222:225], v[80:83]
	v_mfma_f32_16x16x32_bf16 v[32:35], v[214:217], v[222:225], v[32:35]
	ds_read_b128 v[222:225], v30
	s_waitcnt lgkmcnt(3)
	v_mfma_f32_16x16x32_bf16 v[88:91], v[158:161], v[226:229], v[88:91]
	v_mfma_f32_16x16x32_bf16 v[92:95], v[162:165], v[226:229], v[92:95]
	v_mfma_f32_16x16x32_bf16 v[96:99], v[166:169], v[226:229], v[96:99]
	v_mfma_f32_16x16x32_bf16 v[36:39], v[214:217], v[226:229], v[36:39]
	ds_read_b128 v[226:229], v31
	s_waitcnt lgkmcnt(3)
	v_mfma_f32_16x16x32_bf16 v[104:107], v[158:161], v[178:181], v[104:107]
	v_mfma_f32_16x16x32_bf16 v[108:111], v[162:165], v[178:181], v[108:111]
	v_mfma_f32_16x16x32_bf16 v[112:115], v[166:169], v[178:181], v[112:115]
	v_mfma_f32_16x16x32_bf16 v[52:55], v[214:217], v[178:181], v[52:55]
	s_waitcnt lgkmcnt(2)
	v_mfma_f32_16x16x32_bf16 v[116:119], v[158:161], v[218:221], v[116:119]
	v_mfma_f32_16x16x32_bf16 v[120:123], v[162:165], v[218:221], v[120:123]
	v_mfma_f32_16x16x32_bf16 v[124:127], v[166:169], v[218:221], v[124:127]
	v_mfma_f32_16x16x32_bf16 v[68:71], v[214:217], v[218:221], v[68:71]
	s_waitcnt lgkmcnt(1)
	v_mfma_f32_16x16x32_bf16 v[132:135], v[162:165], v[222:225], v[132:135]
	v_mfma_f32_16x16x32_bf16 v[84:87], v[214:217], v[222:225], v[84:87]
	s_waitcnt lgkmcnt(0)
	v_mfma_f32_16x16x32_bf16 v[100:103], v[158:161], v[226:229], v[100:103]
	v_mfma_f32_16x16x32_bf16 v[150:153], v[166:169], v[226:229], v[150:153]
	v_mfma_f32_16x16x32_bf16 v[154:157], v[214:217], v[226:229], v[154:157]
	v_mfma_f32_16x16x32_bf16 v[128:131], v[158:161], v[222:225], v[128:131]
	v_mfma_f32_16x16x32_bf16 v[136:139], v[166:169], v[222:225], v[136:139]
	v_mfma_f32_16x16x32_bf16 v[140:143], v[162:165], v[226:229], v[140:143]
	s_add_u32 s14, s14, 0xf80
	s_addc_u32 s15, s15, 0
	s_add_u32 s20, s20, 0xf80
	s_waitcnt vmcnt(0)
	s_barrier
	s_addc_u32 s21, s21, 0
	v_lshl_add_u64 v[158:159], s[14:15], 0, v[0:1]
	s_mov_b32 s47, m0
	s_mov_b32 m0, s27
	s_nop 0
	global_load_lds_dwordx4 v[158:159], off
	s_mov_b32 m0, s47
	v_lshl_add_u64 v[158:159], s[20:21], 0, v[0:1]
	s_mov_b32 s27, m0
	s_mov_b32 m0, s26
	s_nop 0
	global_load_lds_dwordx4 v[158:159], off
	s_mov_b32 m0, s27
	v_lshl_add_u64 v[158:159], s[14:15], 0, v[2:3]
	s_mov_b32 s26, m0
	s_mov_b32 m0, s41
	s_nop 0
	global_load_lds_dwordx4 v[158:159], off
	s_mov_b32 m0, s26
	v_lshl_add_u64 v[158:159], s[20:21], 0, v[2:3]
	s_mov_b32 s26, m0
	s_mov_b32 m0, s42
	s_nop 0
	global_load_lds_dwordx4 v[158:159], off
	s_mov_b32 m0, s26
	v_lshl_add_u64 v[158:159], s[14:15], 0, v[4:5]
	s_mov_b32 s26, m0
	s_mov_b32 m0, s43
	s_nop 0
	global_load_lds_dwordx4 v[158:159], off
	s_mov_b32 m0, s26
	v_lshl_add_u64 v[158:159], s[20:21], 0, v[4:5]
	s_mov_b32 s26, m0
	s_mov_b32 m0, s44
	s_nop 0
	global_load_lds_dwordx4 v[158:159], off
	s_mov_b32 m0, s26
	v_lshl_add_u64 v[158:159], s[14:15], 0, v[146:147]
	s_mov_b32 s14, m0
	s_mov_b32 m0, s45
	s_nop 0
	global_load_lds_dwordx4 v[158:159], off
	s_mov_b32 m0, s14
	v_lshl_add_u64 v[158:159], s[20:21], 0, v[146:147]
	s_mov_b32 s14, m0
	s_mov_b32 m0, s46
	s_nop 0
	global_load_lds_dwordx4 v[158:159], off
	s_mov_b32 m0, s14
	ds_read_b128 v[158:161], v7 offset:32768
	ds_read_b128 v[162:165], v7 offset:34816
	ds_read_b128 v[166:169], v7 offset:36864
	ds_read_b128 v[214:217], v7 offset:38912
	ds_read_b128 v[178:181], v6
	ds_read_b128 v[218:221], v6 offset:2048
	ds_read_b128 v[222:225], v6 offset:4096
	ds_read_b128 v[226:229], v6 offset:6144
	s_waitcnt lgkmcnt(3)
	v_mfma_f32_16x16x32_bf16 v[40:43], v[158:161], v[178:181], v[40:43]
	v_mfma_f32_16x16x32_bf16 v[44:47], v[162:165], v[178:181], v[44:47]
	v_mfma_f32_16x16x32_bf16 v[48:51], v[166:169], v[178:181], v[48:51]
	v_mfma_f32_16x16x32_bf16 v[174:177], v[214:217], v[178:181], v[174:177]
	ds_read_b128 v[178:181], v6 offset:8192
	s_waitcnt lgkmcnt(3)
	v_mfma_f32_16x16x32_bf16 v[56:59], v[158:161], v[218:221], v[56:59]
	v_mfma_f32_16x16x32_bf16 v[60:63], v[162:165], v[218:221], v[60:63]
	v_mfma_f32_16x16x32_bf16 v[64:67], v[166:169], v[218:221], v[64:67]
	v_mfma_f32_16x16x32_bf16 v[170:173], v[214:217], v[218:221], v[170:173]
	ds_read_b128 v[218:221], v6 offset:10240
	s_waitcnt lgkmcnt(3)
	v_mfma_f32_16x16x32_bf16 v[72:75], v[158:161], v[222:225], v[72:75]
	v_mfma_f32_16x16x32_bf16 v[76:79], v[162:165], v[222:225], v[76:79]
	v_mfma_f32_16x16x32_bf16 v[80:83], v[166:169], v[222:225], v[80:83]
	v_mfma_f32_16x16x32_bf16 v[32:35], v[214:217], v[222:225], v[32:35]
	ds_read_b128 v[222:225], v6 offset:12288
	s_waitcnt lgkmcnt(3)
	v_mfma_f32_16x16x32_bf16 v[88:91], v[158:161], v[226:229], v[88:91]
	v_mfma_f32_16x16x32_bf16 v[92:95], v[162:165], v[226:229], v[92:95]
	v_mfma_f32_16x16x32_bf16 v[96:99], v[166:169], v[226:229], v[96:99]
	v_mfma_f32_16x16x32_bf16 v[36:39], v[214:217], v[226:229], v[36:39]
	ds_read_b128 v[226:229], v6 offset:14336
	s_waitcnt lgkmcnt(3)
	v_mfma_f32_16x16x32_bf16 v[104:107], v[158:161], v[178:181], v[104:107]
	v_mfma_f32_16x16x32_bf16 v[108:111], v[162:165], v[178:181], v[108:111]
	v_mfma_f32_16x16x32_bf16 v[112:115], v[166:169], v[178:181], v[112:115]
	v_mfma_f32_16x16x32_bf16 v[52:55], v[214:217], v[178:181], v[52:55]
	s_waitcnt lgkmcnt(2)
	v_mfma_f32_16x16x32_bf16 v[116:119], v[158:161], v[218:221], v[116:119]
	v_mfma_f32_16x16x32_bf16 v[120:123], v[162:165], v[218:221], v[120:123]
	v_mfma_f32_16x16x32_bf16 v[124:127], v[166:169], v[218:221], v[124:127]
	v_mfma_f32_16x16x32_bf16 v[68:71], v[214:217], v[218:221], v[68:71]
	s_waitcnt lgkmcnt(1)
	v_mfma_f32_16x16x32_bf16 v[132:135], v[162:165], v[222:225], v[132:135]
	v_mfma_f32_16x16x32_bf16 v[84:87], v[214:217], v[222:225], v[84:87]
	s_waitcnt lgkmcnt(0)
	v_mfma_f32_16x16x32_bf16 v[100:103], v[158:161], v[226:229], v[100:103]
	v_mfma_f32_16x16x32_bf16 v[150:153], v[166:169], v[226:229], v[150:153]
	v_mfma_f32_16x16x32_bf16 v[154:157], v[214:217], v[226:229], v[154:157]
	v_mfma_f32_16x16x32_bf16 v[128:131], v[158:161], v[222:225], v[128:131]
	v_mfma_f32_16x16x32_bf16 v[136:139], v[166:169], v[222:225], v[136:139]
	v_mfma_f32_16x16x32_bf16 v[140:143], v[162:165], v[226:229], v[140:143]
	ds_read_b128 v[158:161], v7 offset:33792
	ds_read_b128 v[162:165], v7 offset:35840
	ds_read_b128 v[166:169], v7 offset:37888
	ds_read_b128 v[214:217], v7 offset:39936
	ds_read_b128 v[178:181], v6 offset:1024
	ds_read_b128 v[218:221], v6 offset:3072
	ds_read_b128 v[222:225], v6 offset:5120
	ds_read_b128 v[226:229], v6 offset:7168
	s_waitcnt lgkmcnt(3)
	v_mfma_f32_16x16x32_bf16 v[40:43], v[158:161], v[178:181], v[40:43]
	v_mfma_f32_16x16x32_bf16 v[44:47], v[162:165], v[178:181], v[44:47]
	v_mfma_f32_16x16x32_bf16 v[48:51], v[166:169], v[178:181], v[48:51]
	v_mfma_f32_16x16x32_bf16 v[174:177], v[214:217], v[178:181], v[174:177]
	ds_read_b128 v[178:181], v6 offset:9216
	s_waitcnt lgkmcnt(3)
	v_mfma_f32_16x16x32_bf16 v[56:59], v[158:161], v[218:221], v[56:59]
	v_mfma_f32_16x16x32_bf16 v[60:63], v[162:165], v[218:221], v[60:63]
	v_mfma_f32_16x16x32_bf16 v[64:67], v[166:169], v[218:221], v[64:67]
	v_mfma_f32_16x16x32_bf16 v[170:173], v[214:217], v[218:221], v[170:173]
	ds_read_b128 v[218:221], v6 offset:11264
	s_waitcnt lgkmcnt(3)
	v_mfma_f32_16x16x32_bf16 v[72:75], v[158:161], v[222:225], v[72:75]
	v_mfma_f32_16x16x32_bf16 v[76:79], v[162:165], v[222:225], v[76:79]
	v_mfma_f32_16x16x32_bf16 v[80:83], v[166:169], v[222:225], v[80:83]
	v_mfma_f32_16x16x32_bf16 v[32:35], v[214:217], v[222:225], v[32:35]
	ds_read_b128 v[222:225], v6 offset:13312
	s_waitcnt lgkmcnt(3)
	v_mfma_f32_16x16x32_bf16 v[88:91], v[158:161], v[226:229], v[88:91]
	v_mfma_f32_16x16x32_bf16 v[92:95], v[162:165], v[226:229], v[92:95]
	v_mfma_f32_16x16x32_bf16 v[96:99], v[166:169], v[226:229], v[96:99]
	v_mfma_f32_16x16x32_bf16 v[36:39], v[214:217], v[226:229], v[36:39]
	ds_read_b128 v[226:229], v6 offset:15360
	s_waitcnt lgkmcnt(3)
	v_mfma_f32_16x16x32_bf16 v[104:107], v[158:161], v[178:181], v[104:107]
	v_mfma_f32_16x16x32_bf16 v[108:111], v[162:165], v[178:181], v[108:111]
	v_mfma_f32_16x16x32_bf16 v[112:115], v[166:169], v[178:181], v[112:115]
	v_mfma_f32_16x16x32_bf16 v[52:55], v[214:217], v[178:181], v[52:55]
	s_waitcnt lgkmcnt(2)
	v_mfma_f32_16x16x32_bf16 v[116:119], v[158:161], v[218:221], v[116:119]
	v_mfma_f32_16x16x32_bf16 v[120:123], v[162:165], v[218:221], v[120:123]
	v_mfma_f32_16x16x32_bf16 v[124:127], v[166:169], v[218:221], v[124:127]
	v_mfma_f32_16x16x32_bf16 v[68:71], v[214:217], v[218:221], v[68:71]
	s_waitcnt lgkmcnt(1)
	v_mfma_f32_16x16x32_bf16 v[132:135], v[162:165], v[222:225], v[132:135]
	v_mfma_f32_16x16x32_bf16 v[84:87], v[214:217], v[222:225], v[84:87]
	s_waitcnt lgkmcnt(0)
	v_mfma_f32_16x16x32_bf16 v[100:103], v[158:161], v[226:229], v[100:103]
	v_mfma_f32_16x16x32_bf16 v[150:153], v[166:169], v[226:229], v[150:153]
	v_mfma_f32_16x16x32_bf16 v[154:157], v[214:217], v[226:229], v[154:157]
	v_mfma_f32_16x16x32_bf16 v[128:131], v[158:161], v[222:225], v[128:131]
	v_mfma_f32_16x16x32_bf16 v[136:139], v[166:169], v[222:225], v[136:139]
	v_mfma_f32_16x16x32_bf16 v[140:143], v[162:165], v[226:229], v[140:143]
	s_waitcnt vmcnt(0)
	s_barrier
	v_lshl_add_u64 v[6:7], s[22:23], 0, v[0:1]
	s_mov_b32 s14, m0
	s_mov_b32 m0, s1
	s_nop 0
	global_load_lds_dwordx4 v[6:7], off
	s_mov_b32 m0, s14
	v_lshl_add_u64 v[0:1], s[24:25], 0, v[0:1]
	s_mov_b32 s1, m0
	s_mov_b32 m0, s34
	s_nop 0
	global_load_lds_dwordx4 v[0:1], off
	s_mov_b32 m0, s1
	v_lshl_add_u64 v[0:1], s[22:23], 0, v[2:3]
	s_mov_b32 s1, m0
	s_mov_b32 m0, s35
	s_nop 0
	global_load_lds_dwordx4 v[0:1], off
	s_mov_b32 m0, s1
	v_lshl_add_u64 v[0:1], s[24:25], 0, v[2:3]
	s_mov_b32 s1, m0
	s_mov_b32 m0, s36
	s_nop 0
	global_load_lds_dwordx4 v[0:1], off
	s_mov_b32 m0, s1
	v_lshl_add_u64 v[0:1], s[22:23], 0, v[4:5]
	s_mov_b32 s1, m0
	s_mov_b32 m0, s37
	s_nop 0
	global_load_lds_dwordx4 v[0:1], off
	s_mov_b32 m0, s1
	v_lshl_add_u64 v[0:1], s[24:25], 0, v[4:5]
	s_mov_b32 s1, m0
	s_mov_b32 m0, s38
	s_nop 0
	global_load_lds_dwordx4 v[0:1], off
	s_mov_b32 m0, s1
	v_lshl_add_u64 v[0:1], s[22:23], 0, v[146:147]
	s_mov_b32 s1, m0
	s_mov_b32 m0, s39
	s_nop 0
	global_load_lds_dwordx4 v[0:1], off
	s_mov_b32 m0, s1
	v_lshl_add_u64 v[0:1], s[24:25], 0, v[146:147]
	s_mov_b32 s1, m0
	s_mov_b32 m0, s40
	s_nop 0
	global_load_lds_dwordx4 v[0:1], off
	s_mov_b32 m0, s1
	ds_read_b128 v[0:3], v8
	ds_read_b128 v[4:7], v9
	ds_read_b128 v[158:161], v11
	ds_read_b128 v[8:11], v10
	ds_read_b128 v[162:165], v12
	ds_read_b128 v[166:169], v13
	ds_read_b128 v[178:181], v14
	ds_read_b128 v[12:15], v15
	s_waitcnt lgkmcnt(3)
	v_mfma_f32_16x16x32_bf16 v[40:43], v[0:3], v[162:165], v[40:43]
	v_mfma_f32_16x16x32_bf16 v[44:47], v[4:7], v[162:165], v[44:47]
	v_mfma_f32_16x16x32_bf16 v[48:51], v[158:161], v[162:165], v[48:51]
	v_mfma_f32_16x16x32_bf16 v[162:165], v[8:11], v[162:165], v[174:177]
	s_nop 2
	ds_read_b128 v[174:177], v16
	s_waitcnt lgkmcnt(3)
	v_mfma_f32_16x16x32_bf16 v[56:59], v[0:3], v[166:169], v[56:59]
	v_mfma_f32_16x16x32_bf16 v[60:63], v[4:7], v[166:169], v[60:63]
	v_mfma_f32_16x16x32_bf16 v[64:67], v[158:161], v[166:169], v[64:67]
	v_mfma_f32_16x16x32_bf16 v[166:169], v[8:11], v[166:169], v[170:173]
	s_nop 2
	ds_read_b128 v[170:173], v17
	s_waitcnt lgkmcnt(3)
	v_mfma_f32_16x16x32_bf16 v[72:75], v[0:3], v[178:181], v[72:75]
	v_mfma_f32_16x16x32_bf16 v[76:79], v[4:7], v[178:181], v[76:79]
	v_mfma_f32_16x16x32_bf16 v[80:83], v[158:161], v[178:181], v[80:83]
	v_mfma_f32_16x16x32_bf16 v[32:35], v[8:11], v[178:181], v[32:35]
	ds_read_b128 v[178:181], v18
	s_waitcnt lgkmcnt(3)
	v_mfma_f32_16x16x32_bf16 v[214:217], v[0:3], v[12:15], v[88:91]
	v_mfma_f32_16x16x32_bf16 v[218:221], v[4:7], v[12:15], v[92:95]
	v_mfma_f32_16x16x32_bf16 v[222:225], v[158:161], v[12:15], v[96:99]
	v_mfma_f32_16x16x32_bf16 v[12:15], v[8:11], v[12:15], v[36:39]
	ds_read_b128 v[16:19], v19
	s_waitcnt lgkmcnt(3)
	v_mfma_f32_16x16x32_bf16 v[36:39], v[0:3], v[174:177], v[104:107]
	v_mfma_f32_16x16x32_bf16 v[226:229], v[4:7], v[174:177], v[108:111]
	v_mfma_f32_16x16x32_bf16 v[112:115], v[158:161], v[174:177], v[112:115]
	s_waitcnt lgkmcnt(2)
	v_mfma_f32_16x16x32_bf16 v[116:119], v[0:3], v[170:173], v[116:119]
	v_mfma_f32_16x16x32_bf16 v[120:123], v[4:7], v[170:173], v[120:123]
	v_mfma_f32_16x16x32_bf16 v[124:127], v[158:161], v[170:173], v[124:127]
	s_waitcnt lgkmcnt(1)
	v_mfma_f32_16x16x32_bf16 v[128:131], v[0:3], v[178:181], v[128:131]
	v_mfma_f32_16x16x32_bf16 v[132:135], v[4:7], v[178:181], v[132:135]
	s_waitcnt lgkmcnt(0)
	v_mfma_f32_16x16x32_bf16 v[0:3], v[0:3], v[16:19], v[100:103]
	v_mfma_f32_16x16x32_bf16 v[4:7], v[4:7], v[16:19], v[140:143]
	v_mfma_f32_16x16x32_bf16 v[140:143], v[158:161], v[16:19], v[150:153]
	v_mfma_f32_16x16x32_bf16 v[150:153], v[8:11], v[16:19], v[154:157]
	v_mfma_f32_16x16x32_bf16 v[174:177], v[8:11], v[174:177], v[52:55]
	v_mfma_f32_16x16x32_bf16 v[170:173], v[8:11], v[170:173], v[68:71]
	v_mfma_f32_16x16x32_bf16 v[136:139], v[158:161], v[178:181], v[136:139]
	v_mfma_f32_16x16x32_bf16 v[178:181], v[8:11], v[178:181], v[84:87]
	ds_read_b128 v[8:11], v20
	ds_read_b128 v[154:157], v21
	ds_read_b128 v[158:161], v23
	ds_read_b128 v[230:233], v22
	ds_read_b128 v[16:19], v24
	ds_read_b128 v[20:23], v25
	ds_read_b128 v[52:55], v26
	ds_read_b128 v[24:27], v27
	s_waitcnt lgkmcnt(3)
	v_mfma_f32_16x16x32_bf16 v[234:237], v[8:11], v[16:19], v[40:43]
	v_mfma_f32_16x16x32_bf16 v[238:241], v[154:157], v[16:19], v[44:47]
	v_mfma_f32_16x16x32_bf16 v[242:245], v[158:161], v[16:19], v[48:51]
	v_mfma_f32_16x16x32_bf16 v[162:165], v[230:233], v[16:19], v[162:165]
	ds_read_b128 v[16:19], v28
	s_waitcnt lgkmcnt(3)
	v_mfma_f32_16x16x32_bf16 v[108:111], v[8:11], v[20:23], v[56:59]
	v_mfma_f32_16x16x32_bf16 v[104:107], v[154:157], v[20:23], v[60:63]
	v_mfma_f32_16x16x32_bf16 v[100:103], v[158:161], v[20:23], v[64:67]
	v_mfma_f32_16x16x32_bf16 v[96:99], v[230:233], v[20:23], v[166:169]
	ds_read_b128 v[20:23], v29
	s_waitcnt lgkmcnt(3)
	v_mfma_f32_16x16x32_bf16 v[92:95], v[8:11], v[52:55], v[72:75]
	v_mfma_f32_16x16x32_bf16 v[88:91], v[154:157], v[52:55], v[76:79]
	v_mfma_f32_16x16x32_bf16 v[84:87], v[158:161], v[52:55], v[80:83]
	v_mfma_f32_16x16x32_bf16 v[80:83], v[230:233], v[52:55], v[32:35]
	ds_read_b128 v[166:169], v30
	s_waitcnt lgkmcnt(3)
	v_mfma_f32_16x16x32_bf16 v[76:79], v[8:11], v[24:27], v[214:217]
	v_mfma_f32_16x16x32_bf16 v[72:75], v[154:157], v[24:27], v[218:221]
	v_mfma_f32_16x16x32_bf16 v[68:71], v[158:161], v[24:27], v[222:225]
	v_mfma_f32_16x16x32_bf16 v[64:67], v[230:233], v[24:27], v[12:15]
	ds_read_b128 v[214:217], v31
	s_waitcnt lgkmcnt(3)
	v_mfma_f32_16x16x32_bf16 v[60:63], v[8:11], v[16:19], v[36:39]
	v_mfma_f32_16x16x32_bf16 v[56:59], v[154:157], v[16:19], v[226:229]
	v_mfma_f32_16x16x32_bf16 v[52:55], v[158:161], v[16:19], v[112:115]
	v_mfma_f32_16x16x32_bf16 v[48:51], v[230:233], v[16:19], v[174:177]
	s_waitcnt lgkmcnt(2)
	v_mfma_f32_16x16x32_bf16 v[44:47], v[8:11], v[20:23], v[116:119]
	v_mfma_f32_16x16x32_bf16 v[40:43], v[154:157], v[20:23], v[120:123]
	v_mfma_f32_16x16x32_bf16 v[36:39], v[158:161], v[20:23], v[124:127]
	v_mfma_f32_16x16x32_bf16 v[32:35], v[230:233], v[20:23], v[170:173]
	s_waitcnt lgkmcnt(1)
	v_mfma_f32_16x16x32_bf16 v[28:31], v[8:11], v[166:169], v[128:131]
	v_mfma_f32_16x16x32_bf16 v[24:27], v[154:157], v[166:169], v[132:135]
	v_mfma_f32_16x16x32_bf16 v[20:23], v[158:161], v[166:169], v[136:139]
	v_mfma_f32_16x16x32_bf16 v[16:19], v[230:233], v[166:169], v[178:181]
	s_waitcnt lgkmcnt(0)
	v_mfma_f32_16x16x32_bf16 v[12:15], v[8:11], v[214:217], v[0:3]
	v_mfma_f32_16x16x32_bf16 v[8:11], v[154:157], v[214:217], v[4:7]
	v_mfma_f32_16x16x32_bf16 v[4:7], v[158:161], v[214:217], v[140:143]
	v_mfma_f32_16x16x32_bf16 v[0:3], v[230:233], v[214:217], v[150:153]
	v_mov_b32_e32 v145, v184
	s_waitcnt vmcnt(0)
	s_barrier
	s_lshl_b32 s20, s0, 8
	s_lshl_b32 s14, s12, 8
	v_and_b32_e32 v151, 15, v145
	v_ashrrev_i32_e32 v112, 1, v145
	v_and_b32_e32 v153, 0xffffff80, v112
	v_or_b32_e32 v112, s20, v151
	v_add_u32_e32 v112, v112, v153
	v_ashrrev_i32_e32 v113, 31, v112
	v_lshlrev_b64 v[112:113], 13, v[112:113]
	v_bfe_u32 v150, v145, 6, 2
	v_lshl_add_u64 v[112:113], s[2:3], 0, v[112:113]
	s_ashr_i32 s15, s14, 31
	v_bfe_u32 v152, v145, 4, 2
	v_lshl_add_u64 v[112:113], s[14:15], 2, v[112:113]
	v_lshlrev_b32_e32 v146, 8, v150
	v_lshl_add_u64 v[112:113], v[112:113], 0, v[146:147]
	v_lshlrev_b32_e32 v146, 4, v152
	v_lshl_add_u64 v[154:155], v[112:113], 0, v[146:147]
	global_load_dwordx4 v[120:123], v[154:155], off offset:192
	global_load_dwordx4 v[128:131], v[154:155], off offset:128
	global_load_dwordx4 v[136:139], v[154:155], off offset:64
	global_load_dwordx4 v[140:143], v[154:155], off
	v_add_co_u32_e32 v112, vcc, s66, v154
	v_lshlrev_b32_e32 v158, 2, v152
	s_nop 0
	v_addc_co_u32_e32 v113, vcc, 0, v155, vcc
	global_load_dwordx4 v[132:135], v[112:113], off
	global_load_dwordx4 v[124:127], v[112:113], off offset:64
	global_load_dwordx4 v[116:119], v[112:113], off offset:128
	v_cmp_lt_i32_e32 vcc, v188, v186
	global_load_dwordx4 v[112:115], v[112:113], off offset:192
	v_cmp_eq_u32_e64 s[0:1], 0, v152
	v_cndmask_b32_e32 v146, v185, v188, vcc
	v_cmp_lt_i32_e32 vcc, v187, v186
	v_lshlrev_b32_e32 v149, 2, v146
	v_lshlrev_b32_e32 v157, 6, v150
	v_cndmask_b32_e32 v156, v185, v187, vcc
	v_lshlrev_b32_e32 v146, 2, v156
	v_or_b32_e32 v156, v153, v151
	v_add_u32_e32 v152, s20, v156
	v_ashrrev_i32_e32 v153, 31, v152
	v_lshl_or_b32 v182, v150, 10, v204
	v_or3_b32 v150, v157, s14, v158
	v_lshlrev_b64 v[158:159], 13, v[152:153]
	v_ashrrev_i32_e32 v151, 31, v150
	v_lshlrev_b64 v[160:161], 12, v[152:153]
	v_lshl_add_u64 v[158:159], s[2:3], 0, v[158:159]
	v_lshl_add_u64 v[160:161], s[4:5], 0, v[160:161]
	v_lshl_add_u64 v[166:167], v[150:151], 2, v[158:159]
	v_lshl_add_u64 v[168:169], v[150:151], 1, v[160:161]
	s_waitcnt vmcnt(7)
	v_pk_add_f32 v[158:159], v[162:163], v[120:121]
	s_waitcnt vmcnt(6)
	v_pk_add_f32 v[120:121], v[242:243], v[128:129]
	s_waitcnt vmcnt(5)
	v_pk_add_f32 v[128:129], v[238:239], v[136:137]
	s_waitcnt vmcnt(4)
	v_pk_add_f32 v[136:137], v[234:235], v[140:141]
	v_pk_add_f32 v[160:161], v[164:165], v[122:123]
	v_pk_add_f32 v[122:123], v[244:245], v[130:131]
	v_pk_add_f32 v[130:131], v[240:241], v[138:139]
	v_pk_add_f32 v[138:139], v[236:237], v[142:143]
	v_pk_mul_f32 v[172:173], v[128:129], v[128:129]
	v_pk_mul_f32 v[178:179], v[136:137], v[136:137]
	v_pk_mul_f32 v[162:163], v[120:121], v[120:121]
	v_pk_mul_f32 v[174:175], v[130:131], v[130:131]
	v_cvt_pk_bf16_f32 v176, v136, v137
	v_pk_mul_f32 v[180:181], v[138:139], v[138:139]
	global_store_dwordx4 v[166:167], v[136:139], off
	v_add_f32_e32 v153, v172, v173
	v_add_f32_e32 v157, v178, v179
	v_pk_mul_f32 v[136:137], v[158:159], v[158:159]
	v_pk_mul_f32 v[164:165], v[122:123], v[122:123]
	v_cvt_pk_bf16_f32 v177, v138, v139
	v_pk_mul_f32 v[138:139], v[160:161], v[160:161]
	v_add_f32_e32 v162, v162, v163
	v_add_f32_e32 v136, v136, v137
	v_add_f32_e32 v137, v174, v153
	v_add_f32_e32 v153, v180, v157
	v_add_f32_e32 v157, v164, v162
	v_add_f32_e32 v136, v138, v136
	v_add_f32_e32 v137, v175, v137
	v_add_f32_e32 v138, v181, v153
	v_add_f32_e32 v153, v165, v157
	v_add_f32_e32 v137, v138, v137
	v_add_f32_e32 v137, v137, v153
	v_add_f32_e32 v136, v139, v136
	v_add_f32_e32 v136, v137, v136
	ds_bpermute_b32 v137, v149, v136
	v_cvt_pk_bf16_f32 v170, v128, v129
	v_cvt_pk_bf16_f32 v171, v130, v131
	v_cvt_pk_bf16_f32 v142, v120, v121
	global_store_dwordx2 v[168:169], v[176:177], off
	global_store_dwordx4 v[166:167], v[128:131], off offset:64
	global_store_dwordx2 v[168:169], v[170:171], off offset:32
	global_store_dwordx4 v[166:167], v[120:123], off offset:128
	v_cvt_pk_bf16_f32 v140, v158, v159
	v_cvt_pk_bf16_f32 v141, v160, v161
	s_waitcnt lgkmcnt(0)
	v_add_f32_e32 v120, v136, v137
	ds_bpermute_b32 v121, v146, v120
	v_cvt_pk_bf16_f32 v143, v122, v123
	v_lshl_add_u32 v153, v156, 2, v182
	global_store_dwordx2 v[168:169], v[142:143], off offset:64
	global_store_dwordx4 v[166:167], v[158:161], off offset:192
	global_store_dwordx2 v[168:169], v[140:141], off offset:96
	s_and_saveexec_b64 s[14:15], s[0:1]
	s_cbranch_execz .LBB0_698
	s_waitcnt lgkmcnt(0)
	v_add_f32_e32 v120, v120, v121
	ds_write_b32 v153, v120
